# DPP moves replace ds_bpermute for fixed in-row shuffles (chunk-prep sum16, FoX epilogue lane^1, out-norm sum16, in_proj epilogue lane^8); on k-inner MFMA order
# speedup vs baseline: 1.0008x; 1.0008x over previous
; #define PG8_LAS __attribute__((address_space(3)))
; __device__ __forceinline__ unsigned cvt_pk_bf16(float lo, float hi) { unsigned r; asm volatile("v_cvt_pk_bf16_f32 %0, %1, %2" : "=v"(r) : "v"(lo), "v"(hi)); return r; }
;     __device__ __forceinline__ void operator()(const f32x4 (&acc)[2][2][4][2], const Unit& u, int wr, int wc, int fr, int fq) const {
;     ...
;                 float rstd = 1.f;
;                 if (normed) { const PG8_LAS float* p = part + (ai * HALF + wr * 64 + m * 16 + fr) * 4 + (wc & 2); rstd = 1.0f / sqrtf((p[0] + p[1]) * (1.0f / 128.0f) + 1e-6f); }
;                 u32x4 w[2];
; #pragma unroll
;                 for (int bj = 0; bj < 2; ++bj) { const f32x4 v0 = acc[ai][bj][m][0] * rstd * g[bj][0], v1 = acc[ai][bj][m][1] * rstd * g[bj][1];
;                     w[bj].x = cvt_pk_bf16(v0[0], v0[1]); w[bj].y = cvt_pk_bf16(v0[2], v0[3]); w[bj].z = cvt_pk_bf16(v1[0], v1[1]); w[bj].w = cvt_pk_bf16(v1[2], v1[3]); }
;                 const u32x4 snd = lo ? w[1] : w[0];
;                 u32x4 rcv; rcv.x = __shfl_xor(snd.x, 8); rcv.y = __shfl_xor(snd.y, 8); rcv.z = __shfl_xor(snd.z, 8); rcv.w = __shfl_xor(snd.w, 8);
;                 bf16_t* rp = base + (size_t)(ai * HALF + m * 16) * ldc;
;                 *(u32x4*)rp = lo ? w[0] : rcv;
;                 *(u32x4*)(rp + (size_t)8 * ldc) = lo ? rcv : w[1];
.LBB0_425:
	v_pk_mul_f32 v[142:143], v[142:143], v[170:171] op_sel_hi:[1,0]
	v_pk_mul_f32 v[140:141], v[140:141], v[170:171] op_sel_hi:[1,0]
	v_pk_mul_f32 v[138:139], v[138:139], v[170:171] op_sel_hi:[1,0]
	v_pk_mul_f32 v[136:137], v[136:137], v[170:171] op_sel_hi:[1,0]
	v_pk_mul_f32 v[144:145], v[144:145], v[170:171] op_sel_hi:[1,0]
	s_waitcnt vmcnt(0)
	v_pk_mul_f32 v[142:143], v[90:91], v[142:143]
	v_pk_mul_f32 v[140:141], v[96:97], v[140:141]
	v_pk_mul_f32 v[138:139], v[94:95], v[138:139]
	v_pk_mul_f32 v[134:135], v[134:135], v[170:171] op_sel_hi:[1,0]
	v_pk_mul_f32 v[136:137], v[88:89], v[136:137]
	v_pk_mul_f32 v[132:133], v[132:133], v[170:171] op_sel_hi:[1,0]
	v_readlane_b32 s10, v252, 38
	v_pk_mul_f32 v[144:145], v[92:93], v[144:145]
	v_cvt_pk_bf16_f32 v142, v142, v143
	v_pk_mul_f32 v[134:135], v[86:87], v[134:135]
	v_cvt_pk_bf16_f32 v143, v144, v145
	v_cvt_pk_bf16_f32 v138, v138, v139
	v_cvt_pk_bf16_f32 v139, v140, v141
	v_pk_mul_f32 v[130:131], v[130:131], v[170:171] op_sel_hi:[1,0]
	v_pk_mul_f32 v[132:133], v[84:85], v[132:133]
	v_cvt_pk_bf16_f32 v140, v134, v135
	v_cvt_pk_bf16_f32 v141, v136, v137
	v_and_b32_e32 v136, 64, v183
	v_readlane_b32 s11, v252, 39
	v_pk_mul_f32 v[130:131], v[82:83], v[130:131]
	v_add_u32_e32 v136, 64, v136
	v_cvt_pk_bf16_f32 v144, v130, v131
	v_cvt_pk_bf16_f32 v133, v132, v133
	v_xor_b32_e32 v132, 8, v183
	v_lshl_add_u32 v167, s30, 8, v157
	v_mov_b64_e32 v[186:187], s[10:11]
	s_movk_i32 s10, 0x7080
	v_cmp_lt_i32_e32 vcc, v132, v136
	v_mad_i64_i32 v[186:187], s[10:11], v167, s10, v[186:187]
	s_nop 0
	v_cndmask_b32_e32 v132, v183, v132, vcc
	s_lshl_b32 s10, s28, 8
	v_cndmask_b32_e64 v130, v139, v133, s[8:9]
	v_cndmask_b32_e64 v131, v138, v144, s[8:9]
	v_cndmask_b32_e64 v134, v143, v141, s[8:9]
	v_cndmask_b32_e64 v135, v142, v140, s[8:9]
	v_lshlrev_b32_e32 v132, 2, v132
	s_ashr_i32 s11, s10, 31
	s_nop 1
	v_mov_b32_dpp v145, v135 row_ror:8 row_mask:0xf bank_mask:0xf
	s_nop 1
	v_mov_b32_dpp v170, v134 row_ror:8 row_mask:0xf bank_mask:0xf
	s_nop 1
	v_mov_b32_dpp v185, v131 row_ror:8 row_mask:0xf bank_mask:0xf
	s_nop 1
	v_mov_b32_dpp v188, v130 row_ror:8 row_mask:0xf bank_mask:0xf
	v_lshl_add_u64 v[186:187], s[10:11], 1, v[186:187]
	v_lshl_add_u64 v[186:187], v[186:187], 0, s[12:13]
	v_lshl_add_u64 v[186:187], v[186:187], 0, v[154:155]
	v_mov_b32_e32 v167, v155
	v_lshl_add_u64 v[130:131], v[186:187], 0, v[166:167]
	s_waitcnt lgkmcnt(3)
	v_cndmask_b32_e64 v134, v145, v142, s[8:9]
	s_waitcnt lgkmcnt(2)
	v_cndmask_b32_e64 v135, v170, v143, s[8:9]
	s_waitcnt lgkmcnt(1)
	v_cndmask_b32_e64 v136, v185, v138, s[8:9]
	s_waitcnt lgkmcnt(0)
	v_cndmask_b32_e64 v137, v188, v139, s[8:9]
	v_add_co_u32_e32 v138, vcc, 0x38000, v130
	global_store_dwordx4 v[130:131], v[134:137], off
	s_nop 0
	v_addc_co_u32_e32 v139, vcc, 0, v131, vcc
	v_cndmask_b32_e64 v134, v140, v145, s[8:9]
	v_cndmask_b32_e64 v135, v141, v170, s[8:9]
	v_cndmask_b32_e64 v136, v144, v185, s[8:9]
	v_cndmask_b32_e64 v137, v133, v188, s[8:9]
	global_store_dwordx4 v[138:139], v[134:137], off offset:1024
	s_and_b64 vcc, exec, s[6:7]
	s_cbranch_vccnz .LBB0_427
	ds_read_b64 v[134:135], v171
	s_waitcnt lgkmcnt(0)
	v_add_f32_e32 v133, v134, v135
	v_fmamk_f32 v133, v133, 0x3c000000, v181
	v_mul_f32_e32 v134, 0x4f800000, v133
	v_cmp_gt_f32_e32 vcc, s45, v133
	s_nop 1
	v_cndmask_b32_e32 v133, v133, v134, vcc
	v_sqrt_f32_e32 v134, v133
	s_nop 0
	v_add_u32_e32 v135, -1, v134
	v_add_u32_e32 v136, 1, v134
	v_fma_f32 v137, -v135, v134, v133
	v_fma_f32 v138, -v136, v134, v133
	v_cmp_ge_f32_e64 s[10:11], 0, v137
	s_nop 1
	v_cndmask_b32_e64 v134, v134, v135, s[10:11]
	v_cmp_lt_f32_e64 s[10:11], 0, v138
	s_nop 1
	v_cndmask_b32_e64 v134, v134, v136, s[10:11]
	v_mul_f32_e32 v135, 0x37800000, v134
	v_cndmask_b32_e32 v134, v134, v135, vcc
	v_cmp_class_f32_e32 vcc, v133, v182
	s_nop 1
	v_cndmask_b32_e32 v133, v134, v133, vcc
	v_div_scale_f32 v134, s[10:11], v133, v133, 1.0
	v_rcp_f32_e32 v135, v134
	v_div_scale_f32 v136, vcc, 1.0, v133, 1.0
	v_fma_f32 v137, -v134, v135, 1.0
	v_fmac_f32_e32 v135, v137, v135
	v_mul_f32_e32 v137, v136, v135
	v_fma_f32 v138, -v134, v137, v136
	v_fmac_f32_e32 v137, v138, v135
	v_fma_f32 v134, -v134, v137, v136
	v_div_fmas_f32 v134, v134, v135, v137
	v_div_fixup_f32 v168, v134, v133, 1.0
; #define PG8_LAS __attribute__((address_space(3)))
; __device__ __forceinline__ unsigned cvt_pk_bf16(float lo, float hi) { unsigned r; asm volatile("v_cvt_pk_bf16_f32 %0, %1, %2" : "=v"(r) : "v"(lo), "v"(hi)); return r; }
;     __device__ __forceinline__ void operator()(const f32x4 (&acc)[2][2][4][2], const Unit& u, int wr, int wc, int fr, int fq) const {
;     ...
;                 float rstd = 1.f;
;                 if (normed) { const PG8_LAS float* p = part + (ai * HALF + wr * 64 + m * 16 + fr) * 4 + (wc & 2); rstd = 1.0f / sqrtf((p[0] + p[1]) * (1.0f / 128.0f) + 1e-6f); }
;                 u32x4 w[2];
; #pragma unroll
;                 for (int bj = 0; bj < 2; ++bj) { const f32x4 v0 = acc[ai][bj][m][0] * rstd * g[bj][0], v1 = acc[ai][bj][m][1] * rstd * g[bj][1];
;                     w[bj].x = cvt_pk_bf16(v0[0], v0[1]); w[bj].y = cvt_pk_bf16(v0[2], v0[3]); w[bj].z = cvt_pk_bf16(v1[0], v1[1]); w[bj].w = cvt_pk_bf16(v1[2], v1[3]); }
;                 const u32x4 snd = lo ? w[1] : w[0];
;                 u32x4 rcv; rcv.x = __shfl_xor(snd.x, 8); rcv.y = __shfl_xor(snd.y, 8); rcv.z = __shfl_xor(snd.z, 8); rcv.w = __shfl_xor(snd.w, 8);
;                 bf16_t* rp = base + (size_t)(ai * HALF + m * 16) * ldc;
;                 *(u32x4*)rp = lo ? w[0] : rcv;
;                 *(u32x4*)(rp + (size_t)8 * ldc) = lo ? rcv : w[1];
.LBB0_427:
	v_pk_mul_f32 v[126:127], v[126:127], v[168:169] op_sel_hi:[1,0]
	v_pk_mul_f32 v[124:125], v[124:125], v[168:169] op_sel_hi:[1,0]
	v_pk_mul_f32 v[122:123], v[122:123], v[168:169] op_sel_hi:[1,0]
	v_pk_mul_f32 v[120:121], v[120:121], v[168:169] op_sel_hi:[1,0]
	v_pk_mul_f32 v[116:117], v[116:117], v[168:169] op_sel_hi:[1,0]
	v_pk_mul_f32 v[114:115], v[114:115], v[168:169] op_sel_hi:[1,0]
	v_pk_mul_f32 v[128:129], v[128:129], v[168:169] op_sel_hi:[1,0]
	v_pk_mul_f32 v[126:127], v[90:91], v[126:127]
	v_pk_mul_f32 v[124:125], v[96:97], v[124:125]
	v_pk_mul_f32 v[122:123], v[94:95], v[122:123]
	v_pk_mul_f32 v[118:119], v[118:119], v[168:169] op_sel_hi:[1,0]
	v_pk_mul_f32 v[120:121], v[88:89], v[120:121]
	v_pk_mul_f32 v[116:117], v[84:85], v[116:117]
	v_pk_mul_f32 v[114:115], v[82:83], v[114:115]
	v_pk_mul_f32 v[128:129], v[92:93], v[128:129]
	v_cvt_pk_bf16_f32 v126, v126, v127
	v_pk_mul_f32 v[118:119], v[86:87], v[118:119]
	v_cvt_pk_bf16_f32 v127, v128, v129
	v_cvt_pk_bf16_f32 v122, v122, v123
	v_cvt_pk_bf16_f32 v123, v124, v125
	s_mov_b32 s10, 0x70000
	v_cvt_pk_bf16_f32 v124, v118, v119
	v_cvt_pk_bf16_f32 v120, v120, v121
	v_cvt_pk_bf16_f32 v121, v114, v115
	v_cvt_pk_bf16_f32 v125, v116, v117
	v_add_co_u32_e32 v118, vcc, s10, v130
	v_cndmask_b32_e64 v114, v123, v125, s[8:9]
	v_cndmask_b32_e64 v115, v127, v120, s[8:9]
	v_cndmask_b32_e64 v116, v122, v121, s[8:9]
	v_cndmask_b32_e64 v117, v126, v124, s[8:9]
	s_nop 1
	v_mov_b32_dpp v128, v115 row_ror:8 row_mask:0xf bank_mask:0xf
	s_nop 1
	v_mov_b32_dpp v129, v114 row_ror:8 row_mask:0xf bank_mask:0xf
	s_nop 1
	v_mov_b32_dpp v133, v117 row_ror:8 row_mask:0xf bank_mask:0xf
	s_nop 1
	v_mov_b32_dpp v134, v116 row_ror:8 row_mask:0xf bank_mask:0xf
	v_addc_co_u32_e32 v119, vcc, 0, v131, vcc
	s_waitcnt lgkmcnt(3)
	v_cndmask_b32_e64 v115, v128, v127, s[8:9]
	s_waitcnt lgkmcnt(2)
	v_cndmask_b32_e64 v117, v129, v123, s[8:9]
	s_waitcnt lgkmcnt(1)
	v_cndmask_b32_e64 v114, v133, v126, s[8:9]
	s_waitcnt lgkmcnt(0)
	v_cndmask_b32_e64 v116, v134, v122, s[8:9]
	global_store_dwordx4 v[118:119], v[114:117], off offset:2048
	v_add_co_u32_e32 v118, vcc, 0xa8000, v130
	s_nop 0
	v_cndmask_b32_e64 v115, v120, v128, s[8:9]
	v_cndmask_b32_e64 v117, v125, v129, s[8:9]
	v_cndmask_b32_e64 v114, v124, v133, s[8:9]
	v_cndmask_b32_e64 v116, v121, v134, s[8:9]
	v_addc_co_u32_e32 v119, vcc, 0, v131, vcc
	global_store_dwordx4 v[118:119], v[114:117], off offset:3072
	s_and_b64 vcc, exec, s[6:7]
	s_nop 0
	v_mov_b32_e32 v114, 1.0
	v_mov_b32_e32 v116, 1.0
	s_cbranch_vccnz .LBB0_429
	ds_read_b64 v[116:117], v172
	s_waitcnt lgkmcnt(0)
	v_add_f32_e32 v115, v116, v117
	v_fmamk_f32 v115, v115, 0x3c000000, v181
	v_mul_f32_e32 v116, 0x4f800000, v115
	v_cmp_gt_f32_e32 vcc, s45, v115
	s_nop 1
	v_cndmask_b32_e32 v115, v115, v116, vcc
	v_sqrt_f32_e32 v116, v115
	s_nop 0
	v_add_u32_e32 v117, -1, v116
	v_add_u32_e32 v118, 1, v116
	v_fma_f32 v119, -v117, v116, v115
	v_fma_f32 v120, -v118, v116, v115
	v_cmp_ge_f32_e64 s[10:11], 0, v119
	s_nop 1
	v_cndmask_b32_e64 v116, v116, v117, s[10:11]
	v_cmp_lt_f32_e64 s[10:11], 0, v120
	s_nop 1
	v_cndmask_b32_e64 v116, v116, v118, s[10:11]
	v_mul_f32_e32 v117, 0x37800000, v116
	v_cndmask_b32_e32 v116, v116, v117, vcc
	v_cmp_class_f32_e32 vcc, v115, v182
	s_nop 1
	v_cndmask_b32_e32 v115, v116, v115, vcc
	v_div_scale_f32 v116, s[10:11], v115, v115, 1.0
	v_rcp_f32_e32 v117, v116
	v_div_scale_f32 v118, vcc, 1.0, v115, 1.0
	v_fma_f32 v119, -v116, v117, 1.0
	v_fmac_f32_e32 v117, v119, v117
	v_mul_f32_e32 v119, v118, v117
	v_fma_f32 v120, -v116, v119, v118
	v_fmac_f32_e32 v119, v120, v117
	v_fma_f32 v116, -v116, v119, v118
	v_div_fmas_f32 v116, v116, v117, v119
	v_div_fixup_f32 v116, v116, v115, 1.0
.LBB0_429:
	v_pk_mul_f32 v[110:111], v[110:111], v[116:117] op_sel_hi:[1,0]
	v_pk_mul_f32 v[108:109], v[108:109], v[116:117] op_sel_hi:[1,0]
	v_pk_mul_f32 v[106:107], v[106:107], v[116:117] op_sel_hi:[1,0]
	v_pk_mul_f32 v[104:105], v[104:105], v[116:117] op_sel_hi:[1,0]
	v_pk_mul_f32 v[100:101], v[100:101], v[116:117] op_sel_hi:[1,0]
	v_pk_mul_f32 v[98:99], v[98:99], v[116:117] op_sel_hi:[1,0]
	v_pk_mul_f32 v[112:113], v[112:113], v[116:117] op_sel_hi:[1,0]
	v_pk_mul_f32 v[110:111], v[90:91], v[110:111]
	v_pk_mul_f32 v[108:109], v[96:97], v[108:109]
	v_pk_mul_f32 v[106:107], v[94:95], v[106:107]
	v_pk_mul_f32 v[102:103], v[102:103], v[116:117] op_sel_hi:[1,0]
	v_pk_mul_f32 v[104:105], v[88:89], v[104:105]
	v_pk_mul_f32 v[100:101], v[84:85], v[100:101]
	v_pk_mul_f32 v[98:99], v[82:83], v[98:99]
	v_pk_mul_f32 v[112:113], v[92:93], v[112:113]
	v_cvt_pk_bf16_f32 v110, v110, v111
	v_pk_mul_f32 v[102:103], v[86:87], v[102:103]
	v_cvt_pk_bf16_f32 v111, v112, v113
	v_cvt_pk_bf16_f32 v106, v106, v107
	v_cvt_pk_bf16_f32 v107, v108, v109
	s_mov_b32 s10, 0xe1000
	v_cvt_pk_bf16_f32 v108, v102, v103
	v_cvt_pk_bf16_f32 v104, v104, v105
	v_cvt_pk_bf16_f32 v105, v98, v99
	v_cvt_pk_bf16_f32 v109, v100, v101
	v_add_co_u32_e32 v102, vcc, s10, v130
	v_cndmask_b32_e64 v98, v107, v109, s[8:9]
	v_cndmask_b32_e64 v99, v111, v104, s[8:9]
	v_cndmask_b32_e64 v100, v106, v105, s[8:9]
	v_cndmask_b32_e64 v101, v110, v108, s[8:9]
	s_nop 1
	v_mov_b32_dpp v112, v99 row_ror:8 row_mask:0xf bank_mask:0xf
	s_nop 1
	v_mov_b32_dpp v113, v98 row_ror:8 row_mask:0xf bank_mask:0xf
	s_nop 1
	v_mov_b32_dpp v115, v101 row_ror:8 row_mask:0xf bank_mask:0xf
	s_nop 1
	v_mov_b32_dpp v116, v100 row_ror:8 row_mask:0xf bank_mask:0xf
	v_addc_co_u32_e32 v103, vcc, 0, v131, vcc
	s_waitcnt lgkmcnt(3)
	v_cndmask_b32_e64 v99, v112, v111, s[8:9]
	s_waitcnt lgkmcnt(2)
	v_cndmask_b32_e64 v101, v113, v107, s[8:9]
	s_waitcnt lgkmcnt(1)
	v_cndmask_b32_e64 v98, v115, v110, s[8:9]
	s_waitcnt lgkmcnt(0)
	v_cndmask_b32_e64 v100, v116, v106, s[8:9]
	global_store_dwordx4 v[102:103], v[98:101], off
	v_add_co_u32_e32 v102, vcc, 0x119000, v130
	s_nop 0
	v_cndmask_b32_e64 v99, v104, v112, s[8:9]
	v_cndmask_b32_e64 v101, v109, v113, s[8:9]
	v_cndmask_b32_e64 v98, v108, v115, s[8:9]
	v_cndmask_b32_e64 v100, v105, v116, s[8:9]
	v_addc_co_u32_e32 v103, vcc, 0, v131, vcc
	global_store_dwordx4 v[102:103], v[98:101], off offset:1024
	s_and_b64 vcc, exec, s[6:7]
	s_cbranch_vccnz .LBB0_431
; #define PG8_LAS __attribute__((address_space(3)))
; __device__ __forceinline__ unsigned cvt_pk_bf16(float lo, float hi) { unsigned r; asm volatile("v_cvt_pk_bf16_f32 %0, %1, %2" : "=v"(r) : "v"(lo), "v"(hi)); return r; }
;     __device__ __forceinline__ void operator()(const f32x4 (&acc)[2][2][4][2], const Unit& u, int wr, int wc, int fr, int fq) const {
;     ...
;                 float rstd = 1.f;
;                 if (normed) { const PG8_LAS float* p = part + (ai * HALF + wr * 64 + m * 16 + fr) * 4 + (wc & 2); rstd = 1.0f / sqrtf((p[0] + p[1]) * (1.0f / 128.0f) + 1e-6f); }
;                 u32x4 w[2];
; #pragma unroll
;                 for (int bj = 0; bj < 2; ++bj) { const f32x4 v0 = acc[ai][bj][m][0] * rstd * g[bj][0], v1 = acc[ai][bj][m][1] * rstd * g[bj][1];
;                     w[bj].x = cvt_pk_bf16(v0[0], v0[1]); w[bj].y = cvt_pk_bf16(v0[2], v0[3]); w[bj].z = cvt_pk_bf16(v1[0], v1[1]); w[bj].w = cvt_pk_bf16(v1[2], v1[3]); }
;                 const u32x4 snd = lo ? w[1] : w[0];
;                 u32x4 rcv; rcv.x = __shfl_xor(snd.x, 8); rcv.y = __shfl_xor(snd.y, 8); rcv.z = __shfl_xor(snd.z, 8); rcv.w = __shfl_xor(snd.w, 8);
;                 bf16_t* rp = base + (size_t)(ai * HALF + m * 16) * ldc;
;                 *(u32x4*)rp = lo ? w[0] : rcv;
;                 *(u32x4*)(rp + (size_t)8 * ldc) = lo ? rcv : w[1];
	ds_read_b64 v[98:99], v173
	s_waitcnt lgkmcnt(0)
	v_add_f32_e32 v98, v98, v99
	v_fmamk_f32 v98, v98, 0x3c000000, v181
	v_mul_f32_e32 v99, 0x4f800000, v98
	v_cmp_gt_f32_e32 vcc, s45, v98
	s_nop 1
	v_cndmask_b32_e32 v98, v98, v99, vcc
	v_sqrt_f32_e32 v99, v98
	s_nop 0
	v_add_u32_e32 v100, -1, v99
	v_add_u32_e32 v101, 1, v99
	v_fma_f32 v102, -v100, v99, v98
	v_fma_f32 v103, -v101, v99, v98
	v_cmp_ge_f32_e64 s[10:11], 0, v102
	s_nop 1
	v_cndmask_b32_e64 v99, v99, v100, s[10:11]
	v_cmp_lt_f32_e64 s[10:11], 0, v103
	s_nop 1
	v_cndmask_b32_e64 v99, v99, v101, s[10:11]
	v_mul_f32_e32 v100, 0x37800000, v99
	v_cndmask_b32_e32 v99, v99, v100, vcc
	v_cmp_class_f32_e32 vcc, v98, v182
	s_nop 1
	v_cndmask_b32_e32 v98, v99, v98, vcc
	v_div_scale_f32 v99, s[10:11], v98, v98, 1.0
	v_rcp_f32_e32 v100, v99
	v_div_scale_f32 v101, vcc, 1.0, v98, 1.0
	v_fma_f32 v102, -v99, v100, 1.0
	v_fmac_f32_e32 v100, v102, v100
	v_mul_f32_e32 v102, v101, v100
	v_fma_f32 v103, -v99, v102, v101
	v_fmac_f32_e32 v102, v103, v100
	v_fma_f32 v99, -v99, v102, v101
	v_div_fmas_f32 v99, v99, v100, v102
	v_div_fixup_f32 v114, v99, v98, 1.0
.LBB0_431:
	v_pk_mul_f32 v[78:79], v[78:79], v[114:115] op_sel_hi:[1,0]
	v_pk_mul_f32 v[76:77], v[76:77], v[114:115] op_sel_hi:[1,0]
	v_pk_mul_f32 v[74:75], v[74:75], v[114:115] op_sel_hi:[1,0]
	v_pk_mul_f32 v[72:73], v[72:73], v[114:115] op_sel_hi:[1,0]
	v_pk_mul_f32 v[68:69], v[68:69], v[114:115] op_sel_hi:[1,0]
	v_pk_mul_f32 v[66:67], v[66:67], v[114:115] op_sel_hi:[1,0]
	v_pk_mul_f32 v[80:81], v[80:81], v[114:115] op_sel_hi:[1,0]
	v_pk_mul_f32 v[78:79], v[90:91], v[78:79]
	v_pk_mul_f32 v[76:77], v[96:97], v[76:77]
	v_pk_mul_f32 v[74:75], v[94:95], v[74:75]
	v_pk_mul_f32 v[70:71], v[70:71], v[114:115] op_sel_hi:[1,0]
	v_pk_mul_f32 v[72:73], v[88:89], v[72:73]
	v_pk_mul_f32 v[68:69], v[84:85], v[68:69]
	v_pk_mul_f32 v[66:67], v[82:83], v[66:67]
	v_pk_mul_f32 v[80:81], v[92:93], v[80:81]
	v_cvt_pk_bf16_f32 v78, v78, v79
	v_pk_mul_f32 v[70:71], v[86:87], v[70:71]
	v_cvt_pk_bf16_f32 v79, v80, v81
	v_cvt_pk_bf16_f32 v74, v74, v75
	v_cvt_pk_bf16_f32 v75, v76, v77
	s_mov_b32 s10, 0x151000
	v_cvt_pk_bf16_f32 v76, v70, v71
	v_cvt_pk_bf16_f32 v72, v72, v73
	v_cvt_pk_bf16_f32 v73, v66, v67
	v_cvt_pk_bf16_f32 v77, v68, v69
	v_add_co_u32_e32 v70, vcc, s10, v130
	v_cndmask_b32_e64 v66, v75, v77, s[8:9]
	v_cndmask_b32_e64 v67, v79, v72, s[8:9]
	v_cndmask_b32_e64 v68, v74, v73, s[8:9]
	v_cndmask_b32_e64 v69, v78, v76, s[8:9]
	s_nop 1
	v_mov_b32_dpp v80, v67 row_ror:8 row_mask:0xf bank_mask:0xf
	s_nop 1
	v_mov_b32_dpp v81, v66 row_ror:8 row_mask:0xf bank_mask:0xf
	s_nop 1
	v_mov_b32_dpp v98, v69 row_ror:8 row_mask:0xf bank_mask:0xf
	s_nop 1
	v_mov_b32_dpp v99, v68 row_ror:8 row_mask:0xf bank_mask:0xf
	v_addc_co_u32_e32 v71, vcc, 0, v131, vcc
	s_waitcnt lgkmcnt(3)
	v_cndmask_b32_e64 v67, v80, v79, s[8:9]
	s_waitcnt lgkmcnt(2)
	v_cndmask_b32_e64 v69, v81, v75, s[8:9]
	s_waitcnt lgkmcnt(1)
	v_cndmask_b32_e64 v66, v98, v78, s[8:9]
	s_waitcnt lgkmcnt(0)
	v_cndmask_b32_e64 v68, v99, v74, s[8:9]
	global_store_dwordx4 v[70:71], v[66:69], off offset:2048
	v_add_co_u32_e32 v70, vcc, 0x189000, v130
	s_nop 0
	v_cndmask_b32_e64 v67, v72, v80, s[8:9]
	v_cndmask_b32_e64 v69, v77, v81, s[8:9]
	v_cndmask_b32_e64 v66, v76, v98, s[8:9]
	v_cndmask_b32_e64 v68, v73, v99, s[8:9]
	v_addc_co_u32_e32 v71, vcc, 0, v131, vcc
	global_store_dwordx4 v[70:71], v[66:69], off offset:3072
	s_and_b64 vcc, exec, s[6:7]
	s_nop 0
	v_mov_b32_e32 v66, 1.0
	v_mov_b32_e32 v68, 1.0
	s_cbranch_vccnz .LBB0_433
	ds_read_b64 v[68:69], v174
	s_waitcnt lgkmcnt(0)
	v_add_f32_e32 v67, v68, v69
	v_fmamk_f32 v67, v67, 0x3c000000, v181
	v_mul_f32_e32 v68, 0x4f800000, v67
	v_cmp_gt_f32_e32 vcc, s45, v67
	s_nop 1
	v_cndmask_b32_e32 v67, v67, v68, vcc
	v_sqrt_f32_e32 v68, v67
	s_nop 0
	v_add_u32_e32 v69, -1, v68
	v_add_u32_e32 v70, 1, v68
	v_fma_f32 v71, -v69, v68, v67
	v_fma_f32 v72, -v70, v68, v67
	v_cmp_ge_f32_e64 s[10:11], 0, v71
	s_nop 1
	v_cndmask_b32_e64 v68, v68, v69, s[10:11]
	v_cmp_lt_f32_e64 s[10:11], 0, v72
	s_nop 1
	v_cndmask_b32_e64 v68, v68, v70, s[10:11]
	v_mul_f32_e32 v69, 0x37800000, v68
	v_cndmask_b32_e32 v68, v68, v69, vcc
	v_cmp_class_f32_e32 vcc, v67, v182
	s_nop 1
	v_cndmask_b32_e32 v67, v68, v67, vcc
	v_div_scale_f32 v68, s[10:11], v67, v67, 1.0
	v_rcp_f32_e32 v69, v68
	v_div_scale_f32 v70, vcc, 1.0, v67, 1.0
	v_fma_f32 v71, -v68, v69, 1.0
	v_fmac_f32_e32 v69, v71, v69
	v_mul_f32_e32 v71, v70, v69
	v_fma_f32 v72, -v68, v71, v70
	v_fmac_f32_e32 v71, v72, v69
	v_fma_f32 v68, -v68, v71, v70
	v_div_fmas_f32 v68, v68, v69, v71
	v_div_fixup_f32 v68, v68, v67, 1.0
; #define PG8_LAS __attribute__((address_space(3)))
; __device__ __forceinline__ unsigned cvt_pk_bf16(float lo, float hi) { unsigned r; asm volatile("v_cvt_pk_bf16_f32 %0, %1, %2" : "=v"(r) : "v"(lo), "v"(hi)); return r; }
;     __device__ __forceinline__ void operator()(const f32x4 (&acc)[2][2][4][2], const Unit& u, int wr, int wc, int fr, int fq) const {
;     ...
;                 float rstd = 1.f;
;                 if (normed) { const PG8_LAS float* p = part + (ai * HALF + wr * 64 + m * 16 + fr) * 4 + (wc & 2); rstd = 1.0f / sqrtf((p[0] + p[1]) * (1.0f / 128.0f) + 1e-6f); }
;                 u32x4 w[2];
; #pragma unroll
;                 for (int bj = 0; bj < 2; ++bj) { const f32x4 v0 = acc[ai][bj][m][0] * rstd * g[bj][0], v1 = acc[ai][bj][m][1] * rstd * g[bj][1];
;                     w[bj].x = cvt_pk_bf16(v0[0], v0[1]); w[bj].y = cvt_pk_bf16(v0[2], v0[3]); w[bj].z = cvt_pk_bf16(v1[0], v1[1]); w[bj].w = cvt_pk_bf16(v1[2], v1[3]); }
;                 const u32x4 snd = lo ? w[1] : w[0];
;                 u32x4 rcv; rcv.x = __shfl_xor(snd.x, 8); rcv.y = __shfl_xor(snd.y, 8); rcv.z = __shfl_xor(snd.z, 8); rcv.w = __shfl_xor(snd.w, 8);
;                 bf16_t* rp = base + (size_t)(ai * HALF + m * 16) * ldc;
;                 *(u32x4*)rp = lo ? w[0] : rcv;
;                 *(u32x4*)(rp + (size_t)8 * ldc) = lo ? rcv : w[1];
.LBB0_433:
	v_pk_mul_f32 v[62:63], v[62:63], v[68:69] op_sel_hi:[1,0]
	v_pk_mul_f32 v[60:61], v[60:61], v[68:69] op_sel_hi:[1,0]
	v_pk_mul_f32 v[58:59], v[58:59], v[68:69] op_sel_hi:[1,0]
	v_pk_mul_f32 v[56:57], v[56:57], v[68:69] op_sel_hi:[1,0]
	v_pk_mul_f32 v[52:53], v[52:53], v[68:69] op_sel_hi:[1,0]
	v_pk_mul_f32 v[50:51], v[50:51], v[68:69] op_sel_hi:[1,0]
	v_pk_mul_f32 v[64:65], v[64:65], v[68:69] op_sel_hi:[1,0]
	v_pk_mul_f32 v[62:63], v[90:91], v[62:63]
	v_pk_mul_f32 v[60:61], v[96:97], v[60:61]
	v_pk_mul_f32 v[58:59], v[94:95], v[58:59]
	v_pk_mul_f32 v[54:55], v[54:55], v[68:69] op_sel_hi:[1,0]
	v_pk_mul_f32 v[56:57], v[88:89], v[56:57]
	v_pk_mul_f32 v[52:53], v[84:85], v[52:53]
	v_pk_mul_f32 v[50:51], v[82:83], v[50:51]
	v_pk_mul_f32 v[64:65], v[92:93], v[64:65]
	v_cvt_pk_bf16_f32 v62, v62, v63
	v_pk_mul_f32 v[54:55], v[86:87], v[54:55]
	v_cvt_pk_bf16_f32 v63, v64, v65
	v_cvt_pk_bf16_f32 v58, v58, v59
	v_cvt_pk_bf16_f32 v59, v60, v61
	s_mov_b32 s10, 0x384000
	v_cvt_pk_bf16_f32 v60, v54, v55
	v_cvt_pk_bf16_f32 v56, v56, v57
	v_cvt_pk_bf16_f32 v57, v50, v51
	v_cvt_pk_bf16_f32 v61, v52, v53
	v_add_co_u32_e32 v54, vcc, s10, v130
	v_cndmask_b32_e64 v50, v59, v61, s[8:9]
	v_cndmask_b32_e64 v51, v63, v56, s[8:9]
	v_cndmask_b32_e64 v52, v58, v57, s[8:9]
	v_cndmask_b32_e64 v53, v62, v60, s[8:9]
	s_nop 1
	v_mov_b32_dpp v64, v51 row_ror:8 row_mask:0xf bank_mask:0xf
	s_nop 1
	v_mov_b32_dpp v65, v50 row_ror:8 row_mask:0xf bank_mask:0xf
	s_nop 1
	v_mov_b32_dpp v67, v53 row_ror:8 row_mask:0xf bank_mask:0xf
	s_nop 1
	v_mov_b32_dpp v68, v52 row_ror:8 row_mask:0xf bank_mask:0xf
	v_addc_co_u32_e32 v55, vcc, 0, v131, vcc
	s_waitcnt lgkmcnt(3)
	v_cndmask_b32_e64 v51, v64, v63, s[8:9]
	s_waitcnt lgkmcnt(2)
	v_cndmask_b32_e64 v53, v65, v59, s[8:9]
	s_waitcnt lgkmcnt(1)
	v_cndmask_b32_e64 v50, v67, v62, s[8:9]
	s_waitcnt lgkmcnt(0)
	v_cndmask_b32_e64 v52, v68, v58, s[8:9]
	global_store_dwordx4 v[54:55], v[50:53], off
	v_add_co_u32_e32 v54, vcc, 0x3bc000, v130
	s_nop 0
	v_cndmask_b32_e64 v51, v56, v64, s[8:9]
	v_cndmask_b32_e64 v53, v61, v65, s[8:9]
	v_cndmask_b32_e64 v50, v60, v67, s[8:9]
	v_cndmask_b32_e64 v52, v57, v68, s[8:9]
	v_addc_co_u32_e32 v55, vcc, 0, v131, vcc
	global_store_dwordx4 v[54:55], v[50:53], off offset:1024
	s_and_b64 vcc, exec, s[6:7]
	s_cbranch_vccnz .LBB0_435
	ds_read_b64 v[50:51], v175
	s_waitcnt lgkmcnt(0)
	v_add_f32_e32 v50, v50, v51
	v_fmamk_f32 v50, v50, 0x3c000000, v181
	v_mul_f32_e32 v51, 0x4f800000, v50
	v_cmp_gt_f32_e32 vcc, s45, v50
	s_nop 1
	v_cndmask_b32_e32 v50, v50, v51, vcc
	v_sqrt_f32_e32 v51, v50
	s_nop 0
	v_add_u32_e32 v52, -1, v51
	v_add_u32_e32 v53, 1, v51
	v_fma_f32 v54, -v52, v51, v50
	v_fma_f32 v55, -v53, v51, v50
	v_cmp_ge_f32_e64 s[10:11], 0, v54
	s_nop 1
	v_cndmask_b32_e64 v51, v51, v52, s[10:11]
	v_cmp_lt_f32_e64 s[10:11], 0, v55
	s_nop 1
	v_cndmask_b32_e64 v51, v51, v53, s[10:11]
	v_mul_f32_e32 v52, 0x37800000, v51
	v_cndmask_b32_e32 v51, v51, v52, vcc
	v_cmp_class_f32_e32 vcc, v50, v182
	s_nop 1
	v_cndmask_b32_e32 v50, v51, v50, vcc
	v_div_scale_f32 v51, s[10:11], v50, v50, 1.0
	v_rcp_f32_e32 v52, v51
	v_div_scale_f32 v53, vcc, 1.0, v50, 1.0
	v_fma_f32 v54, -v51, v52, 1.0
	v_fmac_f32_e32 v52, v54, v52
	v_mul_f32_e32 v54, v53, v52
	v_fma_f32 v55, -v51, v54, v53
	v_fmac_f32_e32 v54, v55, v52
	v_fma_f32 v51, -v51, v54, v53
	v_div_fmas_f32 v51, v51, v52, v54
	v_div_fixup_f32 v66, v51, v50, 1.0
.LBB0_435:
	v_pk_mul_f32 v[46:47], v[46:47], v[66:67] op_sel_hi:[1,0]
	v_pk_mul_f32 v[44:45], v[44:45], v[66:67] op_sel_hi:[1,0]
	v_pk_mul_f32 v[42:43], v[42:43], v[66:67] op_sel_hi:[1,0]
	v_pk_mul_f32 v[40:41], v[40:41], v[66:67] op_sel_hi:[1,0]
	v_pk_mul_f32 v[36:37], v[36:37], v[66:67] op_sel_hi:[1,0]
	v_pk_mul_f32 v[34:35], v[34:35], v[66:67] op_sel_hi:[1,0]
	v_pk_mul_f32 v[48:49], v[48:49], v[66:67] op_sel_hi:[1,0]
	v_pk_mul_f32 v[46:47], v[90:91], v[46:47]
	v_pk_mul_f32 v[44:45], v[96:97], v[44:45]
	v_pk_mul_f32 v[42:43], v[94:95], v[42:43]
	v_pk_mul_f32 v[38:39], v[38:39], v[66:67] op_sel_hi:[1,0]
	v_pk_mul_f32 v[40:41], v[88:89], v[40:41]
	v_pk_mul_f32 v[36:37], v[84:85], v[36:37]
	v_pk_mul_f32 v[34:35], v[82:83], v[34:35]
	v_pk_mul_f32 v[48:49], v[92:93], v[48:49]
	v_cvt_pk_bf16_f32 v46, v46, v47
	v_pk_mul_f32 v[38:39], v[86:87], v[38:39]
	v_cvt_pk_bf16_f32 v47, v48, v49
	v_cvt_pk_bf16_f32 v42, v42, v43
	v_cvt_pk_bf16_f32 v43, v44, v45
	s_mov_b32 s10, 0x3f4000
	v_cvt_pk_bf16_f32 v44, v38, v39
	v_cvt_pk_bf16_f32 v40, v40, v41
	v_cvt_pk_bf16_f32 v41, v34, v35
	v_cvt_pk_bf16_f32 v45, v36, v37
	v_add_co_u32_e32 v38, vcc, s10, v130
	v_cndmask_b32_e64 v34, v43, v45, s[8:9]
	v_cndmask_b32_e64 v35, v47, v40, s[8:9]
	v_cndmask_b32_e64 v36, v42, v41, s[8:9]
	v_cndmask_b32_e64 v37, v46, v44, s[8:9]
	s_nop 1
	v_mov_b32_dpp v48, v35 row_ror:8 row_mask:0xf bank_mask:0xf
	s_nop 1
	v_mov_b32_dpp v49, v34 row_ror:8 row_mask:0xf bank_mask:0xf
	s_nop 1
	v_mov_b32_dpp v50, v37 row_ror:8 row_mask:0xf bank_mask:0xf
	s_nop 1
	v_mov_b32_dpp v51, v36 row_ror:8 row_mask:0xf bank_mask:0xf
	v_addc_co_u32_e32 v39, vcc, 0, v131, vcc
	s_waitcnt lgkmcnt(3)
	v_cndmask_b32_e64 v35, v48, v47, s[8:9]
	s_waitcnt lgkmcnt(2)
	v_cndmask_b32_e64 v37, v49, v43, s[8:9]
	s_waitcnt lgkmcnt(1)
	v_cndmask_b32_e64 v34, v50, v46, s[8:9]
	s_waitcnt lgkmcnt(0)
	v_cndmask_b32_e64 v36, v51, v42, s[8:9]
	global_store_dwordx4 v[38:39], v[34:37], off offset:2048
	v_add_co_u32_e32 v38, vcc, 0x42c000, v130
	s_nop 0
	v_cndmask_b32_e64 v35, v40, v48, s[8:9]
	v_cndmask_b32_e64 v37, v45, v49, s[8:9]
	v_cndmask_b32_e64 v34, v44, v50, s[8:9]
	v_cndmask_b32_e64 v36, v41, v51, s[8:9]
	v_addc_co_u32_e32 v39, vcc, 0, v131, vcc
	global_store_dwordx4 v[38:39], v[34:37], off offset:3072
	s_and_b64 vcc, exec, s[6:7]
	s_nop 0
	v_mov_b32_e32 v34, 1.0
	v_mov_b32_e32 v36, 1.0
	s_cbranch_vccnz .LBB0_437
	ds_read_b64 v[36:37], v176
	s_waitcnt lgkmcnt(0)
	v_add_f32_e32 v35, v36, v37
	v_fmamk_f32 v35, v35, 0x3c000000, v181
	v_mul_f32_e32 v36, 0x4f800000, v35
	v_cmp_gt_f32_e32 vcc, s45, v35
	s_nop 1
	v_cndmask_b32_e32 v35, v35, v36, vcc
	v_sqrt_f32_e32 v36, v35
	s_nop 0
	v_add_u32_e32 v37, -1, v36
	v_add_u32_e32 v38, 1, v36
	v_fma_f32 v39, -v37, v36, v35
	v_fma_f32 v40, -v38, v36, v35
	v_cmp_ge_f32_e64 s[10:11], 0, v39
	s_nop 1
	v_cndmask_b32_e64 v36, v36, v37, s[10:11]
	v_cmp_lt_f32_e64 s[10:11], 0, v40
	s_nop 1
	v_cndmask_b32_e64 v36, v36, v38, s[10:11]
	v_mul_f32_e32 v37, 0x37800000, v36
	v_cndmask_b32_e32 v36, v36, v37, vcc
	v_cmp_class_f32_e32 vcc, v35, v182
	s_nop 1
	v_cndmask_b32_e32 v35, v36, v35, vcc
	v_div_scale_f32 v36, s[10:11], v35, v35, 1.0
	v_rcp_f32_e32 v37, v36
	v_div_scale_f32 v38, vcc, 1.0, v35, 1.0
	v_fma_f32 v39, -v36, v37, 1.0
	v_fmac_f32_e32 v37, v39, v37
	v_mul_f32_e32 v39, v38, v37
	v_fma_f32 v40, -v36, v39, v38
	v_fmac_f32_e32 v39, v40, v37
	v_fma_f32 v36, -v36, v39, v38
	v_div_fmas_f32 v36, v36, v37, v39
	v_div_fixup_f32 v36, v36, v35, 1.0
; #define PG8_LAS __attribute__((address_space(3)))
; __device__ __forceinline__ unsigned cvt_pk_bf16(float lo, float hi) { unsigned r; asm volatile("v_cvt_pk_bf16_f32 %0, %1, %2" : "=v"(r) : "v"(lo), "v"(hi)); return r; }
;     __device__ __forceinline__ void operator()(const f32x4 (&acc)[2][2][4][2], const Unit& u, int wr, int wc, int fr, int fq) const {
;     ...
;                 float rstd = 1.f;
;                 if (normed) { const PG8_LAS float* p = part + (ai * HALF + wr * 64 + m * 16 + fr) * 4 + (wc & 2); rstd = 1.0f / sqrtf((p[0] + p[1]) * (1.0f / 128.0f) + 1e-6f); }
;                 u32x4 w[2];
; #pragma unroll
;                 for (int bj = 0; bj < 2; ++bj) { const f32x4 v0 = acc[ai][bj][m][0] * rstd * g[bj][0], v1 = acc[ai][bj][m][1] * rstd * g[bj][1];
;                     w[bj].x = cvt_pk_bf16(v0[0], v0[1]); w[bj].y = cvt_pk_bf16(v0[2], v0[3]); w[bj].z = cvt_pk_bf16(v1[0], v1[1]); w[bj].w = cvt_pk_bf16(v1[2], v1[3]); }
;                 const u32x4 snd = lo ? w[1] : w[0];
;                 u32x4 rcv; rcv.x = __shfl_xor(snd.x, 8); rcv.y = __shfl_xor(snd.y, 8); rcv.z = __shfl_xor(snd.z, 8); rcv.w = __shfl_xor(snd.w, 8);
;                 bf16_t* rp = base + (size_t)(ai * HALF + m * 16) * ldc;
;                 *(u32x4*)rp = lo ? w[0] : rcv;
;                 *(u32x4*)(rp + (size_t)8 * ldc) = lo ? rcv : w[1];
;                 asm volatile("" ::: "memory");
;             }
.LBB0_437:
	v_pk_mul_f32 v[30:31], v[30:31], v[36:37] op_sel_hi:[1,0]
	v_pk_mul_f32 v[28:29], v[28:29], v[36:37] op_sel_hi:[1,0]
	v_pk_mul_f32 v[26:27], v[26:27], v[36:37] op_sel_hi:[1,0]
	v_pk_mul_f32 v[24:25], v[24:25], v[36:37] op_sel_hi:[1,0]
	v_pk_mul_f32 v[20:21], v[20:21], v[36:37] op_sel_hi:[1,0]
	v_pk_mul_f32 v[18:19], v[18:19], v[36:37] op_sel_hi:[1,0]
	v_pk_mul_f32 v[32:33], v[32:33], v[36:37] op_sel_hi:[1,0]
	v_pk_mul_f32 v[30:31], v[90:91], v[30:31]
	v_pk_mul_f32 v[28:29], v[96:97], v[28:29]
	v_pk_mul_f32 v[26:27], v[94:95], v[26:27]
	v_pk_mul_f32 v[22:23], v[22:23], v[36:37] op_sel_hi:[1,0]
	v_pk_mul_f32 v[24:25], v[88:89], v[24:25]
	v_pk_mul_f32 v[20:21], v[84:85], v[20:21]
	v_pk_mul_f32 v[18:19], v[82:83], v[18:19]
	v_pk_mul_f32 v[32:33], v[92:93], v[32:33]
	v_cvt_pk_bf16_f32 v30, v30, v31
	v_pk_mul_f32 v[22:23], v[86:87], v[22:23]
	v_cvt_pk_bf16_f32 v31, v32, v33
	v_cvt_pk_bf16_f32 v26, v26, v27
	v_cvt_pk_bf16_f32 v27, v28, v29
	s_mov_b32 s10, 0x465000
	v_cvt_pk_bf16_f32 v28, v22, v23
	v_cvt_pk_bf16_f32 v24, v24, v25
	v_cvt_pk_bf16_f32 v25, v18, v19
	v_cvt_pk_bf16_f32 v29, v20, v21
	v_add_co_u32_e32 v22, vcc, s10, v130
	v_cndmask_b32_e64 v18, v27, v29, s[8:9]
	v_cndmask_b32_e64 v19, v31, v24, s[8:9]
	v_cndmask_b32_e64 v20, v26, v25, s[8:9]
	v_cndmask_b32_e64 v21, v30, v28, s[8:9]
	s_nop 1
	v_mov_b32_dpp v32, v19 row_ror:8 row_mask:0xf bank_mask:0xf
	s_nop 1
	v_mov_b32_dpp v33, v18 row_ror:8 row_mask:0xf bank_mask:0xf
	s_nop 1
	v_mov_b32_dpp v35, v21 row_ror:8 row_mask:0xf bank_mask:0xf
	s_nop 1
	v_mov_b32_dpp v36, v20 row_ror:8 row_mask:0xf bank_mask:0xf
	v_addc_co_u32_e32 v23, vcc, 0, v131, vcc
	s_waitcnt lgkmcnt(3)
	v_cndmask_b32_e64 v19, v32, v31, s[8:9]
	s_waitcnt lgkmcnt(2)
	v_cndmask_b32_e64 v21, v33, v27, s[8:9]
	s_waitcnt lgkmcnt(1)
	v_cndmask_b32_e64 v18, v35, v30, s[8:9]
	s_waitcnt lgkmcnt(0)
	v_cndmask_b32_e64 v20, v36, v26, s[8:9]
	global_store_dwordx4 v[22:23], v[18:21], off
	v_add_co_u32_e32 v22, vcc, 0x49d000, v130
	s_nop 0
	v_cndmask_b32_e64 v19, v24, v32, s[8:9]
	v_cndmask_b32_e64 v21, v29, v33, s[8:9]
	v_cndmask_b32_e64 v18, v28, v35, s[8:9]
	v_cndmask_b32_e64 v20, v25, v36, s[8:9]
	v_addc_co_u32_e32 v23, vcc, 0, v131, vcc
	global_store_dwordx4 v[22:23], v[18:21], off offset:1024
	s_and_b64 vcc, exec, s[6:7]
	s_cbranch_vccnz .LBB0_439
	ds_read_b64 v[18:19], v177
	s_waitcnt lgkmcnt(0)
	v_add_f32_e32 v18, v18, v19
	v_fmamk_f32 v18, v18, 0x3c000000, v181
	v_mul_f32_e32 v19, 0x4f800000, v18
	v_cmp_gt_f32_e32 vcc, s45, v18
	s_nop 1
	v_cndmask_b32_e32 v18, v18, v19, vcc
	v_sqrt_f32_e32 v19, v18
	s_nop 0
	v_add_u32_e32 v20, -1, v19
	v_add_u32_e32 v21, 1, v19
	v_fma_f32 v22, -v20, v19, v18
	v_fma_f32 v23, -v21, v19, v18
	v_cmp_ge_f32_e64 s[6:7], 0, v22
	s_nop 1
	v_cndmask_b32_e64 v19, v19, v20, s[6:7]
	v_cmp_lt_f32_e64 s[6:7], 0, v23
	s_nop 1
	v_cndmask_b32_e64 v19, v19, v21, s[6:7]
	v_mul_f32_e32 v20, 0x37800000, v19
	v_cndmask_b32_e32 v19, v19, v20, vcc
	v_cmp_class_f32_e32 vcc, v18, v182
	s_nop 1
	v_cndmask_b32_e32 v18, v19, v18, vcc
	v_div_scale_f32 v19, s[6:7], v18, v18, 1.0
	v_rcp_f32_e32 v20, v19
	v_div_scale_f32 v21, vcc, 1.0, v18, 1.0
	v_fma_f32 v22, -v19, v20, 1.0
	v_fmac_f32_e32 v20, v22, v20
	v_mul_f32_e32 v22, v21, v20
	v_fma_f32 v23, -v19, v22, v21
	v_fmac_f32_e32 v22, v23, v20
	v_fma_f32 v19, -v19, v22, v21
	v_div_fmas_f32 v19, v19, v20, v22
	v_div_fixup_f32 v34, v19, v18, 1.0
.LBB0_439:
	v_pk_mul_f32 v[14:15], v[14:15], v[34:35] op_sel_hi:[1,0]
	v_pk_mul_f32 v[12:13], v[12:13], v[34:35] op_sel_hi:[1,0]
	v_pk_mul_f32 v[10:11], v[10:11], v[34:35] op_sel_hi:[1,0]
	v_pk_mul_f32 v[8:9], v[8:9], v[34:35] op_sel_hi:[1,0]
	v_pk_mul_f32 v[4:5], v[4:5], v[34:35] op_sel_hi:[1,0]
	v_pk_mul_f32 v[2:3], v[2:3], v[34:35] op_sel_hi:[1,0]
	v_pk_mul_f32 v[16:17], v[16:17], v[34:35] op_sel_hi:[1,0]
	v_pk_mul_f32 v[14:15], v[90:91], v[14:15]
	v_pk_mul_f32 v[12:13], v[96:97], v[12:13]
	v_pk_mul_f32 v[10:11], v[94:95], v[10:11]
	v_pk_mul_f32 v[6:7], v[6:7], v[34:35] op_sel_hi:[1,0]
	v_pk_mul_f32 v[8:9], v[88:89], v[8:9]
	v_pk_mul_f32 v[4:5], v[84:85], v[4:5]
	v_pk_mul_f32 v[2:3], v[82:83], v[2:3]
	v_pk_mul_f32 v[16:17], v[92:93], v[16:17]
	v_cvt_pk_bf16_f32 v14, v14, v15
	v_pk_mul_f32 v[6:7], v[86:87], v[6:7]
	v_cvt_pk_bf16_f32 v15, v16, v17
	v_cvt_pk_bf16_f32 v10, v10, v11
	v_cvt_pk_bf16_f32 v11, v12, v13
	s_mov_b32 s6, 0x4d5000
	v_cvt_pk_bf16_f32 v12, v6, v7
	v_cvt_pk_bf16_f32 v8, v8, v9
	v_cvt_pk_bf16_f32 v9, v2, v3
	v_cvt_pk_bf16_f32 v13, v4, v5
	v_add_co_u32_e32 v6, vcc, s6, v130
	v_cndmask_b32_e64 v2, v11, v13, s[8:9]
	v_cndmask_b32_e64 v3, v15, v8, s[8:9]
	v_cndmask_b32_e64 v4, v10, v9, s[8:9]
	v_cndmask_b32_e64 v5, v14, v12, s[8:9]
	s_nop 1
	v_mov_b32_dpp v16, v3 row_ror:8 row_mask:0xf bank_mask:0xf
	s_nop 1
	v_mov_b32_dpp v17, v2 row_ror:8 row_mask:0xf bank_mask:0xf
	s_nop 1
	v_mov_b32_dpp v18, v5 row_ror:8 row_mask:0xf bank_mask:0xf
	s_nop 1
	v_mov_b32_dpp v19, v4 row_ror:8 row_mask:0xf bank_mask:0xf
	v_addc_co_u32_e32 v7, vcc, 0, v131, vcc
	s_waitcnt lgkmcnt(3)
	v_cndmask_b32_e64 v3, v16, v15, s[8:9]
	s_waitcnt lgkmcnt(2)
	v_cndmask_b32_e64 v5, v17, v11, s[8:9]
	s_waitcnt lgkmcnt(1)
	v_cndmask_b32_e64 v2, v18, v14, s[8:9]
	s_waitcnt lgkmcnt(0)
	v_cndmask_b32_e64 v4, v19, v10, s[8:9]
	global_store_dwordx4 v[6:7], v[2:5], off offset:2048
	v_add_co_u32_e32 v6, vcc, 0x50d000, v130
	s_nop 0
	v_cndmask_b32_e64 v3, v8, v16, s[8:9]
	v_cndmask_b32_e64 v5, v13, v17, s[8:9]
	v_cndmask_b32_e64 v2, v12, v18, s[8:9]
	v_cndmask_b32_e64 v4, v9, v19, s[8:9]
	v_addc_co_u32_e32 v7, vcc, 0, v131, vcc
	global_store_dwordx4 v[6:7], v[2:5], off offset:3072
	s_andn2_b64 vcc, exec, s[4:5]
	s_mov_b64 s[4:5], -1
	s_cbranch_vccnz .LBB0_394
	s_andn2_b64 vcc, exec, s[14:15]
	s_cbranch_vccnz .LBB0_393
	s_barrier
	s_branch .LBB0_393

; #define LAS __attribute__((address_space(3)))
; __device__ __forceinline__ float siluf_(float x) { return x * __builtin_amdgcn_rcpf(1.0f + __builtin_amdgcn_exp2f(-1.4426950408889634f * x)); }
; __device__ __forceinline__ float sum16(float v) {
; #pragma unroll
;     for (int o = 1; o < 16; o <<= 1) v += __shfl_xor(v, o);
;     return v;
; template <int NW>
; __device__ __forceinline__ void gp_stage0_compute(Frame& F, int cidx, const LAS float* Gs, LAS unsigned char* tiles, int w, int lane, const GpTaps<NW>& tp) {
;     ...
;         if (pi < 192) {
;             const int type = pi >> 6, i = pi & 63;
;             float acc[8];
; #pragma unroll
;             for (int e = 0; e < 8; ++e) acc[e] = 0.f;
; #pragma unroll
;             for (int tap = 0; tap < 4; ++tap) {
;                 const v4u xv = tp.xw[it][tap];
;                 const LAS float* cw = cwl + (type * 4 + tap) * 128 + c * 8;
;                 const f32x4 c0 = *(const LAS f32x4*)cw, c1 = *(const LAS f32x4*)(cw + 4);
;                 acc[0] += bflo(xv.x) * c0.x; acc[1] += bfhi(xv.x) * c0.y; acc[2] += bflo(xv.y) * c0.z; acc[3] += bfhi(xv.y) * c0.w;
;                 acc[4] += bflo(xv.z) * c1.x; acc[5] += bfhi(xv.z) * c1.y; acc[6] += bflo(xv.w) * c1.z; acc[7] += bfhi(xv.w) * c1.w;
;             }
;             float ss = 0.f;
; #pragma unroll
;             for (int e = 0; e < 8; ++e) { acc[e] = siluf_(acc[e]); ss += acc[e] * acc[e]; }
;             ss = sum16(ss);
.LBB0_923:
	s_mul_i32 s41, s88, 0xf000
	v_and_b32_e32 v98, 15, v107
	s_mul_hi_i32 s40, s88, 0xf000
	s_add_u32 s38, s82, s41
	s_waitcnt lgkmcnt(0)
	s_barrier
	s_addc_u32 s39, s83, s40
	s_add_i32 s42, 0, 0x20800
	v_lshlrev_b32_e32 v100, 4, v98
	v_mov_b32_e32 v101, 0
	v_writelane_b32 v252, s42, 50
	v_lshl_add_u32 v102, v98, 5, s42
	v_lshl_add_u64 v[98:99], s[38:39], 0, v[100:101]
	s_mov_b64 s[38:39], 0x37404200
	s_movk_i32 s42, 0xc0
	v_lshl_add_u64 v[98:99], v[98:99], 0, s[38:39]
	v_cmp_gt_i32_e32 vcc, s42, v106
	s_and_saveexec_b64 s[38:39], vcc
	s_cbranch_execz .LBB0_926
	s_waitcnt vmcnt(23)
	v_cndmask_b32_e64 v101, v90, 0, s[30:31]
	v_cndmask_b32_e64 v107, v91, 0, s[30:31]
	v_cndmask_b32_e64 v128, v92, 0, s[30:31]
	v_cndmask_b32_e64 v105, v93, 0, s[30:31]
	s_ashr_i32 s30, s60, 10
	v_lshl_add_u32 v104, s30, 11, v102
	s_waitcnt vmcnt(22)
	v_cndmask_b32_e64 v129, v86, 0, s[34:35]
	v_cndmask_b32_e64 v130, v87, 0, s[34:35]
	v_cndmask_b32_e64 v131, v88, 0, s[34:35]
	v_cndmask_b32_e64 v132, v89, 0, s[34:35]
	s_waitcnt vmcnt(21)
	v_cndmask_b32_e64 v133, v94, 0, s[36:37]
	v_cndmask_b32_e64 v134, v95, 0, s[36:37]
	v_cndmask_b32_e64 v135, v96, 0, s[36:37]
	v_cndmask_b32_e64 v136, v97, 0, s[36:37]
	ds_read_b128 v[86:89], v104
	ds_read_b128 v[90:93], v104 offset:16
	ds_read_b128 v[94:97], v104 offset:512
	ds_read_b128 v[108:111], v104 offset:528
	ds_read_b128 v[112:115], v104 offset:1024
	ds_read_b128 v[116:119], v104 offset:1040
	ds_read_b128 v[120:123], v104 offset:1536
	ds_read_b128 v[124:127], v104 offset:1552
	v_mbcnt_lo_u32_b32 v104, -1, 0
	v_mbcnt_hi_u32_b32 v137, -1, v104
	v_and_b32_e32 v104, 64, v137
	v_add_u32_e32 v138, 64, v104
	v_lshlrev_b32_e32 v104, 16, v105
	v_and_b32_e32 v105, 0xffff0000, v105
	s_waitcnt lgkmcnt(6)
	v_pk_fma_f32 v[92:93], v[92:93], v[104:105], 0 op_sel_hi:[1,1,0]
	v_lshlrev_b32_e32 v104, 16, v132
	v_and_b32_e32 v105, 0xffff0000, v132
	s_waitcnt lgkmcnt(4)
	v_pk_fma_f32 v[92:93], v[110:111], v[104:105], v[92:93]
	v_lshlrev_b32_e32 v104, 16, v136
	v_and_b32_e32 v105, 0xffff0000, v136
	s_waitcnt lgkmcnt(2)
	v_pk_fma_f32 v[92:93], v[118:119], v[104:105], v[92:93]
	s_waitcnt vmcnt(20)
	v_lshlrev_b32_e32 v104, 16, v85
	v_and_b32_e32 v105, 0xffff0000, v85
	s_waitcnt lgkmcnt(0)
	v_pk_fma_f32 v[92:93], v[126:127], v[104:105], v[92:93]
	v_xor_b32_e32 v110, 1, v137
	v_mul_f32_e32 v85, 0xbfb8aa3b, v92
	v_exp_f32_e32 v85, v85
	v_mul_f32_e32 v104, 0xbfb8aa3b, v93
	v_exp_f32_e32 v105, v104
	v_cmp_lt_i32_e32 vcc, v110, v138
	v_add_f32_e32 v85, 1.0, v85
	v_rcp_f32_e32 v104, v85
	v_add_f32_e32 v85, 1.0, v105
	v_rcp_f32_e32 v105, v85
	v_cndmask_b32_e32 v85, v137, v110, vcc
	v_lshlrev_b32_e32 v110, 2, v85
	s_cmp_lt_i32 s30, 2
	v_pk_mul_f32 v[92:93], v[92:93], v[104:105]
	v_lshlrev_b32_e32 v104, 16, v128
	v_and_b32_e32 v105, 0xffff0000, v128
	v_pk_fma_f32 v[90:91], v[90:91], v[104:105], 0 op_sel_hi:[1,1,0]
	v_lshlrev_b32_e32 v104, 16, v131
	v_and_b32_e32 v105, 0xffff0000, v131
	v_pk_fma_f32 v[90:91], v[108:109], v[104:105], v[90:91]
	v_lshlrev_b32_e32 v104, 16, v135
	v_and_b32_e32 v105, 0xffff0000, v135
	v_pk_fma_f32 v[90:91], v[116:117], v[104:105], v[90:91]
	v_lshlrev_b32_e32 v104, 16, v84
	v_and_b32_e32 v105, 0xffff0000, v84
	v_pk_fma_f32 v[84:85], v[124:125], v[104:105], v[90:91]
	v_lshlrev_b32_e32 v108, 16, v107
	v_mul_f32_e32 v90, 0xbfb8aa3b, v84
	v_exp_f32_e32 v104, v90
	v_mul_f32_e32 v90, 0xbfb8aa3b, v85
	v_exp_f32_e32 v105, v90
	v_and_b32_e32 v109, 0xffff0000, v107
	v_pk_fma_f32 v[88:89], v[88:89], v[108:109], 0 op_sel_hi:[1,1,0]
	v_lshlrev_b32_e32 v108, 16, v130
	v_and_b32_e32 v109, 0xffff0000, v130
	v_add_f32_e32 v104, 1.0, v104
	v_add_f32_e32 v105, 1.0, v105
	v_pk_fma_f32 v[88:89], v[96:97], v[108:109], v[88:89]
	v_lshlrev_b32_e32 v96, 16, v134
	v_and_b32_e32 v97, 0xffff0000, v134
	v_rcp_f32_e32 v104, v104
	v_rcp_f32_e32 v105, v105
	v_pk_fma_f32 v[88:89], v[114:115], v[96:97], v[88:89]
	v_lshlrev_b32_e32 v96, 16, v83
	v_and_b32_e32 v97, 0xffff0000, v83
	v_pk_fma_f32 v[88:89], v[122:123], v[96:97], v[88:89]
	v_pk_mul_f32 v[84:85], v[84:85], v[104:105]
	v_mul_f32_e32 v83, 0xbfb8aa3b, v88
	v_exp_f32_e32 v83, v83
	v_lshlrev_b32_e32 v104, 16, v101
	v_and_b32_e32 v105, 0xffff0000, v101
	v_pk_fma_f32 v[86:87], v[86:87], v[104:105], 0 op_sel_hi:[1,1,0]
	v_lshlrev_b32_e32 v104, 16, v129
	v_and_b32_e32 v105, 0xffff0000, v129
	v_pk_fma_f32 v[86:87], v[94:95], v[104:105], v[86:87]
	v_lshlrev_b32_e32 v94, 16, v133
	v_and_b32_e32 v95, 0xffff0000, v133
	v_mul_f32_e32 v96, 0xbfb8aa3b, v89
	v_add_f32_e32 v83, 1.0, v83
	v_pk_fma_f32 v[86:87], v[112:113], v[94:95], v[86:87]
	v_lshlrev_b32_e32 v94, 16, v82
	v_and_b32_e32 v95, 0xffff0000, v82
	v_exp_f32_e32 v97, v96
	v_rcp_f32_e32 v96, v83
	v_pk_fma_f32 v[82:83], v[120:121], v[94:95], v[86:87]
	v_pk_mul_f32 v[94:95], v[84:85], v[84:85]
	v_mul_f32_e32 v86, 0xbfb8aa3b, v82
	v_mul_f32_e32 v87, 0xbfb8aa3b, v83
	v_exp_f32_e32 v86, v86
	v_exp_f32_e32 v87, v87
	v_add_f32_e32 v97, 1.0, v97
	v_rcp_f32_e32 v97, v97
	v_add_f32_e32 v86, 1.0, v86
	v_add_f32_e32 v87, 1.0, v87
	v_rcp_f32_e32 v86, v86
	v_rcp_f32_e32 v87, v87
	v_pk_mul_f32 v[96:97], v[88:89], v[96:97]
	v_pk_mul_f32 v[90:91], v[92:93], v[92:93]
	v_pk_mul_f32 v[88:89], v[96:97], v[96:97]
	v_pk_mul_f32 v[82:83], v[82:83], v[86:87]
	s_mulk_i32 s30, 0x4400
	v_pk_mul_f32 v[86:87], v[82:83], v[82:83]
	s_nop 0
	v_add_f32_e32 v86, v86, v87
	v_add_f32_e32 v86, v88, v86
	v_add_f32_e32 v86, v89, v86
	v_add_f32_e32 v86, v94, v86
	v_add_f32_e32 v86, v95, v86
	v_add_f32_e32 v86, v90, v86
	v_add_f32_e32 v86, v91, v86
	s_nop 1
	v_mov_b32_dpp v87, v86 quad_perm:[1,0,3,2] row_mask:0xf bank_mask:0xf
	v_xor_b32_e32 v88, 2, v137
	v_cmp_lt_i32_e32 vcc, v88, v138
	s_waitcnt lgkmcnt(0)
; #define GAS __attribute__((address_space(1)))
; #define LAS __attribute__((address_space(3)))
; __device__ __forceinline__ float siluf_(float x) { return x * __builtin_amdgcn_rcpf(1.0f + __builtin_amdgcn_exp2f(-1.4426950408889634f * x)); }
; __device__ __forceinline__ unsigned gcvtpk(float lo, float hi) { gf32x2 v = {lo, hi}; gbf16x2 b = __builtin_convertvector(v, gbf16x2); return __builtin_bit_cast(unsigned, b); }
; __device__ __forceinline__ float sum16(float v) {
; #pragma unroll
;     for (int o = 1; o < 16; o <<= 1) v += __shfl_xor(v, o);
;     return v;
; }
; template <int NW>
; __device__ __forceinline__ void gp_stage0_compute(Frame& F, int cidx, const LAS float* Gs, LAS unsigned char* tiles, int w, int lane, const GpTaps<NW>& tp) {
;     ...
; #pragma unroll
;             for (int tap = 0; tap < 4; ++tap) {
;                 const v4u xv = tp.xw[it][tap];
;                 const LAS float* cw = cwl + (type * 4 + tap) * 128 + c * 8;
;                 const f32x4 c0 = *(const LAS f32x4*)cw, c1 = *(const LAS f32x4*)(cw + 4);
;                 acc[0] += bflo(xv.x) * c0.x; acc[1] += bfhi(xv.x) * c0.y; acc[2] += bflo(xv.y) * c0.z; acc[3] += bfhi(xv.y) * c0.w;
;                 acc[4] += bflo(xv.z) * c1.x; acc[5] += bfhi(xv.z) * c1.y; acc[6] += bflo(xv.w) * c1.z; acc[7] += bfhi(xv.w) * c1.w;
;             }
;             float ss = 0.f;
; #pragma unroll
;             for (int e = 0; e < 8; ++e) { acc[e] = siluf_(acc[e]); ss += acc[e] * acc[e]; }
;             ss = sum16(ss);
;             float sc = 1.0f;
;             if (type < 2) sc = __builtin_amdgcn_rsqf(ss + EPS);
;             if (type == 0) sc *= 0.08838834764831845f;
; #pragma unroll
;             for (int e = 0; e < 8; ++e) acc[e] *= sc;
;             const v4u o = {gcvtpk(acc[0], acc[1]), gcvtpk(acc[2], acc[3]), gcvtpk(acc[4], acc[5]), gcvtpk(acc[6], acc[7])};
;             *(LAS v4u*)(tiles + type * GP_TILE + i * GP_TS + c * 16) = o;
;             if (type == 0) {
;                 const float e_ = Gs[128 + i];
;                 v2u w0 = {gcvtpk(acc[0] * e_, acc[1] * e_), gcvtpk(acc[2] * e_, acc[3] * e_)}, w1 = {gcvtpk(acc[4] * e_, acc[5] * e_), gcvtpk(acc[6] * e_, acc[7] * e_)};
;                 *(GAS v2u*)(CH + CH_Q + i * RS_W + c * 16) = w0; *(GAS v2u*)(CH + CH_Q + i * RS_W + c * 16 + 8) = w1;
;             }
	v_add_f32_e32 v86, v86, v87
	v_cndmask_b32_e32 v88, v137, v88, vcc
	v_lshlrev_b32_e32 v88, 2, v88
	s_nop 1
	v_mov_b32_dpp v87, v86 quad_perm:[2,3,0,1] row_mask:0xf bank_mask:0xf
	v_xor_b32_e32 v88, 4, v137
	v_cmp_lt_i32_e32 vcc, v88, v138
	s_waitcnt lgkmcnt(0)
	v_add_f32_e32 v86, v86, v87
	v_cndmask_b32_e32 v88, v137, v88, vcc
	v_lshlrev_b32_e32 v88, 2, v88
	s_nop 1
	v_mov_b32_dpp v87, v86 row_half_mirror row_mask:0xf bank_mask:0xf
	v_xor_b32_e32 v88, 8, v137
	v_cmp_lt_i32_e32 vcc, v88, v138
	s_waitcnt lgkmcnt(0)
	v_add_f32_e32 v86, v86, v87
	v_cndmask_b32_e32 v88, v137, v88, vcc
	v_lshlrev_b32_e32 v88, 2, v88
	s_nop 1
	v_mov_b32_dpp v87, v86 row_mirror row_mask:0xf bank_mask:0xf
	s_cselect_b64 vcc, -1, 0
	s_cmp_lt_u32 s33, 64
	s_waitcnt lgkmcnt(0)
	v_add_f32_e32 v86, v86, v87
	v_add_f32_e32 v86, 0x358637bd, v86
	v_rsq_f32_e32 v86, v86
	s_nop 0
	v_cndmask_b32_e32 v86, 1.0, v86, vcc
	v_mul_f32_e32 v87, 0x3db504f3, v86
	s_cselect_b64 vcc, -1, 0
	v_cndmask_b32_e32 v90, v86, v87, vcc
	v_pk_mul_f32 v[88:89], v[82:83], v[90:91] op_sel_hi:[1,0]
	v_pk_mul_f32 v[86:87], v[96:97], v[90:91] op_sel_hi:[1,0]
	v_pk_mul_f32 v[84:85], v[84:85], v[90:91] op_sel_hi:[1,0]
	v_pk_mul_f32 v[82:83], v[92:93], v[90:91] op_sel_hi:[1,0]
	v_and_b32_e32 v90, 63, v106
	s_add_i32 s30, s30, 0
	v_mul_u32_u24_e32 v91, 0x110, v90
	s_cmp_gt_u32 s33, 63
	v_cvt_pk_bf16_f32 v92, v88, v89
	v_cvt_pk_bf16_f32 v93, v86, v87
	v_cvt_pk_bf16_f32 v94, v84, v85
	v_cvt_pk_bf16_f32 v95, v82, v83
	v_add3_u32 v91, s30, v91, v100
	ds_write_b128 v91, v[92:95] offset:28672
	s_cbranch_scc1 .LBB0_926
	v_lshl_add_u32 v91, v106, 2, 0
	ds_read_b32 v92, v91 offset:512
	s_waitcnt lgkmcnt(0)
	v_pk_mul_f32 v[86:87], v[86:87], v[92:93] op_sel_hi:[1,0]
	v_pk_mul_f32 v[82:83], v[82:83], v[92:93] op_sel_hi:[1,0]
	v_pk_mul_f32 v[88:89], v[88:89], v[92:93] op_sel_hi:[1,0]
	v_pk_mul_f32 v[94:95], v[84:85], v[92:93] op_sel_hi:[1,0]
	v_cvt_pk_bf16_f32 v85, v86, v87
	v_cvt_pk_bf16_f32 v87, v82, v83
	v_mul_u32_u24_e32 v82, 0x108, v90
	v_mov_b32_e32 v83, 0
	v_cvt_pk_bf16_f32 v84, v88, v89
	v_cvt_pk_bf16_f32 v86, v94, v95
	v_lshl_add_u64 v[82:83], v[98:99], 0, v[82:83]
	global_store_dwordx4 v[82:83], v[84:87], off
.LBB0_926:
	s_or_b64 exec, exec, s[38:39]
	s_add_i32 s34, s33, 32
	s_waitcnt vmcnt(20)
	v_or_b32_e32 v82, s34, v103
	v_cmp_gt_i32_e32 vcc, s42, v82
	s_and_saveexec_b64 s[30:31], vcc
	s_cbranch_execz .LBB0_929
	s_waitcnt vmcnt(19)
	v_cndmask_b32_e64 v83, v74, 0, s[24:25]
	v_cndmask_b32_e64 v101, v75, 0, s[24:25]
	v_cndmask_b32_e64 v112, v76, 0, s[24:25]
	v_cndmask_b32_e64 v97, v77, 0, s[24:25]
	s_ashr_i32 s24, s34, 6
	v_lshl_add_u32 v96, s24, 11, v102
	s_waitcnt vmcnt(18)
	v_cndmask_b32_e64 v113, v70, 0, s[26:27]
	v_cndmask_b32_e64 v114, v71, 0, s[26:27]
	v_cndmask_b32_e64 v115, v72, 0, s[26:27]
	v_cndmask_b32_e64 v116, v73, 0, s[26:27]
	s_waitcnt vmcnt(17)
	v_cndmask_b32_e64 v117, v78, 0, s[28:29]
	v_cndmask_b32_e64 v118, v79, 0, s[28:29]
	v_cndmask_b32_e64 v119, v80, 0, s[28:29]
	v_cndmask_b32_e64 v120, v81, 0, s[28:29]
	ds_read_b128 v[70:73], v96
	ds_read_b128 v[74:77], v96 offset:16
	ds_read_b128 v[78:81], v96 offset:512
	ds_read_b128 v[84:87], v96 offset:528
	ds_read_b128 v[88:91], v96 offset:1024
	ds_read_b128 v[92:95], v96 offset:1040
	ds_read_b128 v[104:107], v96 offset:1536
	ds_read_b128 v[108:111], v96 offset:1552
	v_mbcnt_lo_u32_b32 v96, -1, 0
	v_mbcnt_hi_u32_b32 v121, -1, v96
	v_and_b32_e32 v96, 64, v121
	v_add_u32_e32 v122, 64, v96
	v_lshlrev_b32_e32 v96, 16, v97
	v_and_b32_e32 v97, 0xffff0000, v97
	s_waitcnt lgkmcnt(6)
	v_pk_fma_f32 v[76:77], v[76:77], v[96:97], 0 op_sel_hi:[1,1,0]
	v_lshlrev_b32_e32 v96, 16, v116
	v_and_b32_e32 v97, 0xffff0000, v116
	s_waitcnt lgkmcnt(4)
	v_pk_fma_f32 v[76:77], v[86:87], v[96:97], v[76:77]
	v_lshlrev_b32_e32 v86, 16, v120
	v_and_b32_e32 v87, 0xffff0000, v120
	s_waitcnt lgkmcnt(2)
	v_pk_fma_f32 v[76:77], v[94:95], v[86:87], v[76:77]
	s_waitcnt vmcnt(16)
	v_lshlrev_b32_e32 v86, 16, v69
	v_and_b32_e32 v87, 0xffff0000, v69
	s_waitcnt lgkmcnt(0)
	v_pk_fma_f32 v[76:77], v[110:111], v[86:87], v[76:77]
	v_xor_b32_e32 v94, 1, v121
	v_mul_f32_e32 v69, 0xbfb8aa3b, v76
	v_exp_f32_e32 v69, v69
	v_mul_f32_e32 v86, 0xbfb8aa3b, v77
	v_exp_f32_e32 v87, v86
	v_cmp_lt_i32_e32 vcc, v94, v122
	v_add_f32_e32 v69, 1.0, v69
	v_rcp_f32_e32 v86, v69
	v_add_f32_e32 v69, 1.0, v87
	v_rcp_f32_e32 v87, v69
	v_cndmask_b32_e32 v69, v121, v94, vcc
	v_lshlrev_b32_e32 v94, 2, v69
	s_cmp_lt_i32 s24, 2
	v_pk_mul_f32 v[76:77], v[76:77], v[86:87]
	v_lshlrev_b32_e32 v86, 16, v112
	v_and_b32_e32 v87, 0xffff0000, v112
	v_pk_fma_f32 v[74:75], v[74:75], v[86:87], 0 op_sel_hi:[1,1,0]
	v_lshlrev_b32_e32 v86, 16, v115
	v_and_b32_e32 v87, 0xffff0000, v115
	v_pk_fma_f32 v[74:75], v[84:85], v[86:87], v[74:75]
	v_lshlrev_b32_e32 v84, 16, v119
	v_and_b32_e32 v85, 0xffff0000, v119
	v_pk_fma_f32 v[74:75], v[92:93], v[84:85], v[74:75]
	v_lshlrev_b32_e32 v84, 16, v68
	v_and_b32_e32 v85, 0xffff0000, v68
	v_pk_fma_f32 v[68:69], v[108:109], v[84:85], v[74:75]
	v_lshlrev_b32_e32 v86, 16, v101
	v_mul_f32_e32 v74, 0xbfb8aa3b, v68
	v_exp_f32_e32 v84, v74
	v_mul_f32_e32 v74, 0xbfb8aa3b, v69
	v_exp_f32_e32 v85, v74
	v_and_b32_e32 v87, 0xffff0000, v101
	v_pk_fma_f32 v[72:73], v[72:73], v[86:87], 0 op_sel_hi:[1,1,0]
	v_lshlrev_b32_e32 v86, 16, v114
	v_and_b32_e32 v87, 0xffff0000, v114
	v_add_f32_e32 v84, 1.0, v84
	v_add_f32_e32 v85, 1.0, v85
	v_pk_fma_f32 v[72:73], v[80:81], v[86:87], v[72:73]
	v_lshlrev_b32_e32 v80, 16, v118
	v_and_b32_e32 v81, 0xffff0000, v118
	v_rcp_f32_e32 v84, v84
	v_rcp_f32_e32 v85, v85
	v_pk_fma_f32 v[72:73], v[90:91], v[80:81], v[72:73]
	v_lshlrev_b32_e32 v80, 16, v67
	v_and_b32_e32 v81, 0xffff0000, v67
; #define GAS __attribute__((address_space(1)))
; #define LAS __attribute__((address_space(3)))
; __device__ __forceinline__ float siluf_(float x) { return x * __builtin_amdgcn_rcpf(1.0f + __builtin_amdgcn_exp2f(-1.4426950408889634f * x)); }
; __device__ __forceinline__ unsigned gcvtpk(float lo, float hi) { gf32x2 v = {lo, hi}; gbf16x2 b = __builtin_convertvector(v, gbf16x2); return __builtin_bit_cast(unsigned, b); }
; __device__ __forceinline__ float sum16(float v) {
; #pragma unroll
;     for (int o = 1; o < 16; o <<= 1) v += __shfl_xor(v, o);
;     return v;
; }
; template <int NW>
; __device__ __forceinline__ void gp_stage0_compute(Frame& F, int cidx, const LAS float* Gs, LAS unsigned char* tiles, int w, int lane, const GpTaps<NW>& tp) {
;     ...
; #pragma unroll
;             for (int tap = 0; tap < 4; ++tap) {
;                 const v4u xv = tp.xw[it][tap];
;                 const LAS float* cw = cwl + (type * 4 + tap) * 128 + c * 8;
;                 const f32x4 c0 = *(const LAS f32x4*)cw, c1 = *(const LAS f32x4*)(cw + 4);
;                 acc[0] += bflo(xv.x) * c0.x; acc[1] += bfhi(xv.x) * c0.y; acc[2] += bflo(xv.y) * c0.z; acc[3] += bfhi(xv.y) * c0.w;
;                 acc[4] += bflo(xv.z) * c1.x; acc[5] += bfhi(xv.z) * c1.y; acc[6] += bflo(xv.w) * c1.z; acc[7] += bfhi(xv.w) * c1.w;
;             }
;             float ss = 0.f;
; #pragma unroll
;             for (int e = 0; e < 8; ++e) { acc[e] = siluf_(acc[e]); ss += acc[e] * acc[e]; }
;             ss = sum16(ss);
;             float sc = 1.0f;
;             if (type < 2) sc = __builtin_amdgcn_rsqf(ss + EPS);
;             if (type == 0) sc *= 0.08838834764831845f;
; #pragma unroll
;             for (int e = 0; e < 8; ++e) acc[e] *= sc;
;             const v4u o = {gcvtpk(acc[0], acc[1]), gcvtpk(acc[2], acc[3]), gcvtpk(acc[4], acc[5]), gcvtpk(acc[6], acc[7])};
;             *(LAS v4u*)(tiles + type * GP_TILE + i * GP_TS + c * 16) = o;
;             if (type == 0) {
;                 const float e_ = Gs[128 + i];
;                 v2u w0 = {gcvtpk(acc[0] * e_, acc[1] * e_), gcvtpk(acc[2] * e_, acc[3] * e_)}, w1 = {gcvtpk(acc[4] * e_, acc[5] * e_), gcvtpk(acc[6] * e_, acc[7] * e_)};
;                 *(GAS v2u*)(CH + CH_Q + i * RS_W + c * 16) = w0; *(GAS v2u*)(CH + CH_Q + i * RS_W + c * 16 + 8) = w1;
;             }
	v_pk_fma_f32 v[72:73], v[106:107], v[80:81], v[72:73]
	v_pk_mul_f32 v[68:69], v[68:69], v[84:85]
	v_mul_f32_e32 v67, 0xbfb8aa3b, v72
	v_exp_f32_e32 v67, v67
	v_lshlrev_b32_e32 v84, 16, v83
	v_and_b32_e32 v85, 0xffff0000, v83
	v_pk_fma_f32 v[70:71], v[70:71], v[84:85], 0 op_sel_hi:[1,1,0]
	v_lshlrev_b32_e32 v84, 16, v113
	v_and_b32_e32 v85, 0xffff0000, v113
	v_pk_fma_f32 v[70:71], v[78:79], v[84:85], v[70:71]
	v_lshlrev_b32_e32 v78, 16, v117
	v_and_b32_e32 v79, 0xffff0000, v117
	v_mul_f32_e32 v80, 0xbfb8aa3b, v73
	v_add_f32_e32 v67, 1.0, v67
	v_pk_fma_f32 v[70:71], v[88:89], v[78:79], v[70:71]
	v_lshlrev_b32_e32 v78, 16, v66
	v_and_b32_e32 v79, 0xffff0000, v66
	v_exp_f32_e32 v81, v80
	v_rcp_f32_e32 v80, v67
	v_pk_fma_f32 v[66:67], v[104:105], v[78:79], v[70:71]
	v_pk_mul_f32 v[78:79], v[68:69], v[68:69]
	v_mul_f32_e32 v70, 0xbfb8aa3b, v66
	v_mul_f32_e32 v71, 0xbfb8aa3b, v67
	v_exp_f32_e32 v70, v70
	v_exp_f32_e32 v71, v71
	v_add_f32_e32 v81, 1.0, v81
	v_rcp_f32_e32 v81, v81
	v_add_f32_e32 v70, 1.0, v70
	v_add_f32_e32 v71, 1.0, v71
	v_rcp_f32_e32 v70, v70
	v_rcp_f32_e32 v71, v71
	v_pk_mul_f32 v[80:81], v[72:73], v[80:81]
	v_pk_mul_f32 v[74:75], v[76:77], v[76:77]
	v_pk_mul_f32 v[72:73], v[80:81], v[80:81]
	v_pk_mul_f32 v[66:67], v[66:67], v[70:71]
	s_mulk_i32 s24, 0x4400
	v_pk_mul_f32 v[70:71], v[66:67], v[66:67]
	s_nop 0
	v_add_f32_e32 v70, v70, v71
	v_add_f32_e32 v70, v72, v70
	v_add_f32_e32 v70, v73, v70
	v_add_f32_e32 v70, v78, v70
	v_add_f32_e32 v70, v79, v70
	v_add_f32_e32 v70, v74, v70
	v_add_f32_e32 v70, v75, v70
	s_nop 1
	v_mov_b32_dpp v71, v70 quad_perm:[1,0,3,2] row_mask:0xf bank_mask:0xf
	v_xor_b32_e32 v72, 2, v121
	v_cmp_lt_i32_e32 vcc, v72, v122
	s_waitcnt lgkmcnt(0)
	v_add_f32_e32 v70, v70, v71
	v_cndmask_b32_e32 v72, v121, v72, vcc
	v_lshlrev_b32_e32 v72, 2, v72
	s_nop 1
	v_mov_b32_dpp v71, v70 quad_perm:[2,3,0,1] row_mask:0xf bank_mask:0xf
	v_xor_b32_e32 v72, 4, v121
	v_cmp_lt_i32_e32 vcc, v72, v122
	s_waitcnt lgkmcnt(0)
	v_add_f32_e32 v70, v70, v71
	v_cndmask_b32_e32 v72, v121, v72, vcc
	v_lshlrev_b32_e32 v72, 2, v72
	s_nop 1
	v_mov_b32_dpp v71, v70 row_half_mirror row_mask:0xf bank_mask:0xf
	v_xor_b32_e32 v72, 8, v121
	v_cmp_lt_i32_e32 vcc, v72, v122
	s_waitcnt lgkmcnt(0)
	v_add_f32_e32 v70, v70, v71
	v_cndmask_b32_e32 v72, v121, v72, vcc
	v_lshlrev_b32_e32 v72, 2, v72
	s_nop 1
	v_mov_b32_dpp v71, v70 row_mirror row_mask:0xf bank_mask:0xf
	s_cselect_b64 vcc, -1, 0
	s_cmp_lt_u32 s34, 64
	s_waitcnt lgkmcnt(0)
	v_add_f32_e32 v70, v70, v71
	v_add_f32_e32 v70, 0x358637bd, v70
	v_rsq_f32_e32 v70, v70
	s_nop 0
	v_cndmask_b32_e32 v70, 1.0, v70, vcc
	v_mul_f32_e32 v71, 0x3db504f3, v70
	s_cselect_b64 vcc, -1, 0
	v_cndmask_b32_e32 v74, v70, v71, vcc
	v_pk_mul_f32 v[72:73], v[66:67], v[74:75] op_sel_hi:[1,0]
	v_pk_mul_f32 v[70:71], v[80:81], v[74:75] op_sel_hi:[1,0]
	v_pk_mul_f32 v[68:69], v[68:69], v[74:75] op_sel_hi:[1,0]
	v_pk_mul_f32 v[66:67], v[76:77], v[74:75] op_sel_hi:[1,0]
	v_and_b32_e32 v74, 63, v82
	s_add_i32 s24, s24, 0
	v_mul_u32_u24_e32 v75, 0x110, v74
	s_cmp_gt_u32 s34, 63
	v_cvt_pk_bf16_f32 v76, v72, v73
	v_cvt_pk_bf16_f32 v77, v70, v71
	v_cvt_pk_bf16_f32 v78, v68, v69
	v_cvt_pk_bf16_f32 v79, v66, v67
	v_add3_u32 v75, s24, v75, v100
	ds_write_b128 v75, v[76:79] offset:28672
	s_cbranch_scc1 .LBB0_929
	v_add_u32_e32 v75, s33, v103
	v_lshl_add_u32 v75, v75, 2, 0
	ds_read_b32 v76, v75 offset:640
	s_waitcnt lgkmcnt(0)
	v_pk_mul_f32 v[70:71], v[70:71], v[76:77] op_sel_hi:[1,0]
	v_pk_mul_f32 v[66:67], v[66:67], v[76:77] op_sel_hi:[1,0]
	v_pk_mul_f32 v[72:73], v[72:73], v[76:77] op_sel_hi:[1,0]
	v_pk_mul_f32 v[78:79], v[68:69], v[76:77] op_sel_hi:[1,0]
	v_cvt_pk_bf16_f32 v69, v70, v71
	v_cvt_pk_bf16_f32 v71, v66, v67
	v_mul_u32_u24_e32 v66, 0x108, v74
	v_mov_b32_e32 v67, 0
	v_cvt_pk_bf16_f32 v68, v72, v73
	v_cvt_pk_bf16_f32 v70, v78, v79
	v_lshl_add_u64 v[66:67], v[98:99], 0, v[66:67]
	global_store_dwordx4 v[66:67], v[68:71], off
.LBB0_929:
	s_or_b64 exec, exec, s[30:31]
	s_add_i32 s27, s33, 64
	s_waitcnt vmcnt(16)
	v_or_b32_e32 v66, s27, v103
	s_movk_i32 s26, 0xc0
	v_cmp_gt_i32_e32 vcc, s26, v66
	s_and_saveexec_b64 s[24:25], vcc
	s_cbranch_execz .LBB0_932
	s_waitcnt vmcnt(15)
	v_cndmask_b32_e64 v67, v58, 0, s[18:19]
	v_cndmask_b32_e64 v90, v59, 0, s[18:19]
	v_cndmask_b32_e64 v91, v60, 0, s[18:19]
	v_cndmask_b32_e64 v89, v61, 0, s[18:19]
	s_ashr_i32 s18, s27, 6
	v_mbcnt_lo_u32_b32 v88, -1, 0
	v_lshl_add_u32 v84, s18, 11, v102
	v_mbcnt_hi_u32_b32 v105, -1, v88
	s_waitcnt vmcnt(14)
	v_cndmask_b32_e64 v92, v54, 0, s[20:21]
	v_cndmask_b32_e64 v93, v55, 0, s[20:21]
	v_cndmask_b32_e64 v94, v56, 0, s[20:21]
	v_cndmask_b32_e64 v95, v57, 0, s[20:21]
	s_waitcnt vmcnt(13)
	v_cndmask_b32_e64 v96, v62, 0, s[22:23]
	v_cndmask_b32_e64 v97, v63, 0, s[22:23]
	v_cndmask_b32_e64 v101, v64, 0, s[22:23]
	v_cndmask_b32_e64 v104, v65, 0, s[22:23]
	ds_read_b128 v[54:57], v84
	ds_read_b128 v[58:61], v84 offset:16
	ds_read_b128 v[62:65], v84 offset:512
	ds_read_b128 v[68:71], v84 offset:528
	ds_read_b128 v[72:75], v84 offset:1024
	ds_read_b128 v[76:79], v84 offset:1040
	ds_read_b128 v[80:83], v84 offset:1536
	ds_read_b128 v[84:87], v84 offset:1552
	v_and_b32_e32 v88, 64, v105
	v_add_u32_e32 v106, 64, v88
	v_lshlrev_b32_e32 v88, 16, v89
	v_and_b32_e32 v89, 0xffff0000, v89
	s_waitcnt lgkmcnt(6)
	v_pk_fma_f32 v[60:61], v[60:61], v[88:89], 0 op_sel_hi:[1,1,0]
	v_lshlrev_b32_e32 v88, 16, v95
	v_and_b32_e32 v89, 0xffff0000, v95
	s_waitcnt lgkmcnt(4)
	v_pk_fma_f32 v[60:61], v[70:71], v[88:89], v[60:61]
	v_lshlrev_b32_e32 v70, 16, v104
	v_and_b32_e32 v71, 0xffff0000, v104
	s_waitcnt lgkmcnt(2)
	v_pk_fma_f32 v[60:61], v[78:79], v[70:71], v[60:61]
	s_waitcnt vmcnt(12)
; #define GAS __attribute__((address_space(1)))
; #define LAS __attribute__((address_space(3)))
; __device__ __forceinline__ float siluf_(float x) { return x * __builtin_amdgcn_rcpf(1.0f + __builtin_amdgcn_exp2f(-1.4426950408889634f * x)); }
; __device__ __forceinline__ unsigned gcvtpk(float lo, float hi) { gf32x2 v = {lo, hi}; gbf16x2 b = __builtin_convertvector(v, gbf16x2); return __builtin_bit_cast(unsigned, b); }
; __device__ __forceinline__ float sum16(float v) {
; #pragma unroll
;     for (int o = 1; o < 16; o <<= 1) v += __shfl_xor(v, o);
;     return v;
; }
; template <int NW>
; __device__ __forceinline__ void gp_stage0_compute(Frame& F, int cidx, const LAS float* Gs, LAS unsigned char* tiles, int w, int lane, const GpTaps<NW>& tp) {
;     ...
; #pragma unroll
;             for (int tap = 0; tap < 4; ++tap) {
;                 const v4u xv = tp.xw[it][tap];
;                 const LAS float* cw = cwl + (type * 4 + tap) * 128 + c * 8;
;                 const f32x4 c0 = *(const LAS f32x4*)cw, c1 = *(const LAS f32x4*)(cw + 4);
;                 acc[0] += bflo(xv.x) * c0.x; acc[1] += bfhi(xv.x) * c0.y; acc[2] += bflo(xv.y) * c0.z; acc[3] += bfhi(xv.y) * c0.w;
;                 acc[4] += bflo(xv.z) * c1.x; acc[5] += bfhi(xv.z) * c1.y; acc[6] += bflo(xv.w) * c1.z; acc[7] += bfhi(xv.w) * c1.w;
;             }
;             float ss = 0.f;
; #pragma unroll
;             for (int e = 0; e < 8; ++e) { acc[e] = siluf_(acc[e]); ss += acc[e] * acc[e]; }
;             ss = sum16(ss);
;             float sc = 1.0f;
;             if (type < 2) sc = __builtin_amdgcn_rsqf(ss + EPS);
;             if (type == 0) sc *= 0.08838834764831845f;
; #pragma unroll
;             for (int e = 0; e < 8; ++e) acc[e] *= sc;
;             const v4u o = {gcvtpk(acc[0], acc[1]), gcvtpk(acc[2], acc[3]), gcvtpk(acc[4], acc[5]), gcvtpk(acc[6], acc[7])};
;             *(LAS v4u*)(tiles + type * GP_TILE + i * GP_TS + c * 16) = o;
;             if (type == 0) {
;                 const float e_ = Gs[128 + i];
;                 v2u w0 = {gcvtpk(acc[0] * e_, acc[1] * e_), gcvtpk(acc[2] * e_, acc[3] * e_)}, w1 = {gcvtpk(acc[4] * e_, acc[5] * e_), gcvtpk(acc[6] * e_, acc[7] * e_)};
;                 *(GAS v2u*)(CH + CH_Q + i * RS_W + c * 16) = w0; *(GAS v2u*)(CH + CH_Q + i * RS_W + c * 16 + 8) = w1;
;             }
	v_lshlrev_b32_e32 v70, 16, v53
	v_and_b32_e32 v71, 0xffff0000, v53
	s_waitcnt lgkmcnt(0)
	v_pk_fma_f32 v[60:61], v[86:87], v[70:71], v[60:61]
	v_xor_b32_e32 v78, 1, v105
	v_mul_f32_e32 v53, 0xbfb8aa3b, v60
	v_exp_f32_e32 v53, v53
	v_mul_f32_e32 v70, 0xbfb8aa3b, v61
	v_exp_f32_e32 v71, v70
	v_cmp_lt_i32_e32 vcc, v78, v106
	v_add_f32_e32 v53, 1.0, v53
	v_rcp_f32_e32 v70, v53
	v_add_f32_e32 v53, 1.0, v71
	v_rcp_f32_e32 v71, v53
	v_cndmask_b32_e32 v53, v105, v78, vcc
	v_lshlrev_b32_e32 v78, 2, v53
	s_cmp_lt_i32 s18, 2
	v_pk_mul_f32 v[60:61], v[60:61], v[70:71]
	v_lshlrev_b32_e32 v70, 16, v91
	v_and_b32_e32 v71, 0xffff0000, v91
	v_pk_fma_f32 v[58:59], v[58:59], v[70:71], 0 op_sel_hi:[1,1,0]
	v_lshlrev_b32_e32 v70, 16, v94
	v_and_b32_e32 v71, 0xffff0000, v94
	v_pk_fma_f32 v[58:59], v[68:69], v[70:71], v[58:59]
	v_lshlrev_b32_e32 v68, 16, v101
	v_and_b32_e32 v69, 0xffff0000, v101
	v_pk_fma_f32 v[58:59], v[76:77], v[68:69], v[58:59]
	v_lshlrev_b32_e32 v68, 16, v52
	v_and_b32_e32 v69, 0xffff0000, v52
	v_pk_fma_f32 v[52:53], v[84:85], v[68:69], v[58:59]
	v_lshlrev_b32_e32 v70, 16, v90
	v_mul_f32_e32 v58, 0xbfb8aa3b, v52
	v_exp_f32_e32 v68, v58
	v_mul_f32_e32 v58, 0xbfb8aa3b, v53
	v_exp_f32_e32 v69, v58
	v_and_b32_e32 v71, 0xffff0000, v90
	v_pk_fma_f32 v[56:57], v[56:57], v[70:71], 0 op_sel_hi:[1,1,0]
	v_lshlrev_b32_e32 v70, 16, v93
	v_and_b32_e32 v71, 0xffff0000, v93
	v_add_f32_e32 v68, 1.0, v68
	v_add_f32_e32 v69, 1.0, v69
	v_pk_fma_f32 v[56:57], v[64:65], v[70:71], v[56:57]
	v_lshlrev_b32_e32 v64, 16, v97
	v_and_b32_e32 v65, 0xffff0000, v97
	v_rcp_f32_e32 v68, v68
	v_rcp_f32_e32 v69, v69
	v_pk_fma_f32 v[56:57], v[74:75], v[64:65], v[56:57]
	v_lshlrev_b32_e32 v64, 16, v51
	v_and_b32_e32 v65, 0xffff0000, v51
	v_pk_fma_f32 v[56:57], v[82:83], v[64:65], v[56:57]
	v_pk_mul_f32 v[52:53], v[52:53], v[68:69]
	v_mul_f32_e32 v51, 0xbfb8aa3b, v56
	v_exp_f32_e32 v51, v51
	v_lshlrev_b32_e32 v68, 16, v67
	v_and_b32_e32 v69, 0xffff0000, v67
	v_pk_fma_f32 v[54:55], v[54:55], v[68:69], 0 op_sel_hi:[1,1,0]
	v_lshlrev_b32_e32 v68, 16, v92
	v_and_b32_e32 v69, 0xffff0000, v92
	v_pk_fma_f32 v[54:55], v[62:63], v[68:69], v[54:55]
	v_lshlrev_b32_e32 v62, 16, v96
	v_and_b32_e32 v63, 0xffff0000, v96
	v_mul_f32_e32 v64, 0xbfb8aa3b, v57
	v_add_f32_e32 v51, 1.0, v51
	v_pk_fma_f32 v[54:55], v[72:73], v[62:63], v[54:55]
	v_lshlrev_b32_e32 v62, 16, v50
	v_and_b32_e32 v63, 0xffff0000, v50
	v_exp_f32_e32 v65, v64
	v_rcp_f32_e32 v64, v51
	v_pk_fma_f32 v[50:51], v[80:81], v[62:63], v[54:55]
	v_pk_mul_f32 v[62:63], v[52:53], v[52:53]
	v_mul_f32_e32 v54, 0xbfb8aa3b, v50
	v_mul_f32_e32 v55, 0xbfb8aa3b, v51
	v_exp_f32_e32 v54, v54
	v_exp_f32_e32 v55, v55
	v_add_f32_e32 v65, 1.0, v65
	v_rcp_f32_e32 v65, v65
	v_add_f32_e32 v54, 1.0, v54
	v_add_f32_e32 v55, 1.0, v55
	v_rcp_f32_e32 v54, v54
	v_rcp_f32_e32 v55, v55
	v_pk_mul_f32 v[64:65], v[56:57], v[64:65]
	v_pk_mul_f32 v[58:59], v[60:61], v[60:61]
	v_pk_mul_f32 v[56:57], v[64:65], v[64:65]
	v_pk_mul_f32 v[50:51], v[50:51], v[54:55]
	s_mulk_i32 s18, 0x4400
	v_pk_mul_f32 v[54:55], v[50:51], v[50:51]
	s_nop 0
	v_add_f32_e32 v54, v54, v55
	v_add_f32_e32 v54, v56, v54
	v_add_f32_e32 v54, v57, v54
	v_add_f32_e32 v54, v62, v54
	v_add_f32_e32 v54, v63, v54
	v_add_f32_e32 v54, v58, v54
	v_add_f32_e32 v54, v59, v54
	s_nop 1
	v_mov_b32_dpp v55, v54 quad_perm:[1,0,3,2] row_mask:0xf bank_mask:0xf
	v_xor_b32_e32 v56, 2, v105
	v_cmp_lt_i32_e32 vcc, v56, v106
	s_waitcnt lgkmcnt(0)
	v_add_f32_e32 v54, v54, v55
	v_cndmask_b32_e32 v56, v105, v56, vcc
	v_lshlrev_b32_e32 v56, 2, v56
	s_nop 1
	v_mov_b32_dpp v55, v54 quad_perm:[2,3,0,1] row_mask:0xf bank_mask:0xf
	v_xor_b32_e32 v56, 4, v105
	v_cmp_lt_i32_e32 vcc, v56, v106
	s_waitcnt lgkmcnt(0)
	v_add_f32_e32 v54, v54, v55
	v_cndmask_b32_e32 v56, v105, v56, vcc
	v_lshlrev_b32_e32 v56, 2, v56
	s_nop 1
	v_mov_b32_dpp v55, v54 row_half_mirror row_mask:0xf bank_mask:0xf
	v_xor_b32_e32 v56, 8, v105
	v_cmp_lt_i32_e32 vcc, v56, v106
	s_waitcnt lgkmcnt(0)
	v_add_f32_e32 v54, v54, v55
	v_cndmask_b32_e32 v56, v105, v56, vcc
	v_lshlrev_b32_e32 v56, 2, v56
	s_nop 1
	v_mov_b32_dpp v55, v54 row_mirror row_mask:0xf bank_mask:0xf
	s_cselect_b64 vcc, -1, 0
	s_cmp_gt_u32 s33, 0xffffffbf
	s_waitcnt lgkmcnt(0)
	v_add_f32_e32 v54, v54, v55
	v_add_f32_e32 v54, 0x358637bd, v54
	v_rsq_f32_e32 v54, v54
	s_nop 0
	v_cndmask_b32_e32 v54, 1.0, v54, vcc
	v_mul_f32_e32 v55, 0x3db504f3, v54
	s_cselect_b64 vcc, -1, 0
	v_cndmask_b32_e32 v58, v54, v55, vcc
	v_pk_mul_f32 v[56:57], v[50:51], v[58:59] op_sel_hi:[1,0]
	v_pk_mul_f32 v[54:55], v[64:65], v[58:59] op_sel_hi:[1,0]
	v_pk_mul_f32 v[52:53], v[52:53], v[58:59] op_sel_hi:[1,0]
	v_pk_mul_f32 v[50:51], v[60:61], v[58:59] op_sel_hi:[1,0]
	v_and_b32_e32 v58, 63, v66
	s_add_i32 s18, s18, 0
	v_mul_u32_u24_e32 v59, 0x110, v58
	s_cmp_lt_u32 s33, 0xffffffc0
	v_cvt_pk_bf16_f32 v60, v56, v57
	v_cvt_pk_bf16_f32 v61, v54, v55
	v_cvt_pk_bf16_f32 v62, v52, v53
	v_cvt_pk_bf16_f32 v63, v50, v51
	v_add3_u32 v59, s18, v59, v100
	ds_write_b128 v59, v[60:63] offset:28672
	s_cbranch_scc1 .LBB0_932
	v_add_u32_e32 v59, s33, v103
	v_lshl_add_u32 v59, v59, 2, 0
	ds_read_b32 v60, v59 offset:768
	s_waitcnt lgkmcnt(0)
	v_pk_mul_f32 v[54:55], v[54:55], v[60:61] op_sel_hi:[1,0]
	v_pk_mul_f32 v[50:51], v[50:51], v[60:61] op_sel_hi:[1,0]
	v_pk_mul_f32 v[56:57], v[56:57], v[60:61] op_sel_hi:[1,0]
	v_pk_mul_f32 v[62:63], v[52:53], v[60:61] op_sel_hi:[1,0]
	v_cvt_pk_bf16_f32 v53, v54, v55
	v_cvt_pk_bf16_f32 v55, v50, v51
	v_mul_u32_u24_e32 v50, 0x108, v58
	v_mov_b32_e32 v51, 0
	v_cvt_pk_bf16_f32 v52, v56, v57
	v_cvt_pk_bf16_f32 v54, v62, v63
	v_lshl_add_u64 v[50:51], v[98:99], 0, v[50:51]
	global_store_dwordx4 v[50:51], v[52:55], off
; #define GAS __attribute__((address_space(1)))
; #define LAS __attribute__((address_space(3)))
; __device__ __forceinline__ float siluf_(float x) { return x * __builtin_amdgcn_rcpf(1.0f + __builtin_amdgcn_exp2f(-1.4426950408889634f * x)); }
; __device__ __forceinline__ float sum16(float v) {
; #pragma unroll
;     for (int o = 1; o < 16; o <<= 1) v += __shfl_xor(v, o);
;     return v;
; }
; template <int NW>
; __device__ __forceinline__ void gp_stage0_compute(Frame& F, int cidx, const LAS float* Gs, LAS unsigned char* tiles, int w, int lane, const GpTaps<NW>& tp) {
;     ...
;             float acc[8];
; #pragma unroll
;             for (int e = 0; e < 8; ++e) acc[e] = 0.f;
; #pragma unroll
;             for (int tap = 0; tap < 4; ++tap) {
;                 const v4u xv = tp.xw[it][tap];
;                 const LAS float* cw = cwl + (type * 4 + tap) * 128 + c * 8;
;                 const f32x4 c0 = *(const LAS f32x4*)cw, c1 = *(const LAS f32x4*)(cw + 4);
;                 acc[0] += bflo(xv.x) * c0.x; acc[1] += bfhi(xv.x) * c0.y; acc[2] += bflo(xv.y) * c0.z; acc[3] += bfhi(xv.y) * c0.w;
;                 acc[4] += bflo(xv.z) * c1.x; acc[5] += bfhi(xv.z) * c1.y; acc[6] += bflo(xv.w) * c1.z; acc[7] += bfhi(xv.w) * c1.w;
;             }
;             float ss = 0.f;
; #pragma unroll
;             for (int e = 0; e < 8; ++e) { acc[e] = siluf_(acc[e]); ss += acc[e] * acc[e]; }
;             ss = sum16(ss);
;             float sc = 1.0f;
;             if (type < 2) sc = __builtin_amdgcn_rsqf(ss + EPS);
;             if (type == 0) sc *= 0.08838834764831845f;
; #pragma unroll
;             for (int e = 0; e < 8; ++e) acc[e] *= sc;
;             const v4u o = {gcvtpk(acc[0], acc[1]), gcvtpk(acc[2], acc[3]), gcvtpk(acc[4], acc[5]), gcvtpk(acc[6], acc[7])};
;             *(LAS v4u*)(tiles + type * GP_TILE + i * GP_TS + c * 16) = o;
;             if (type == 0) {
;                 const float e_ = Gs[128 + i];
;                 v2u w0 = {gcvtpk(acc[0] * e_, acc[1] * e_), gcvtpk(acc[2] * e_, acc[3] * e_)}, w1 = {gcvtpk(acc[4] * e_, acc[5] * e_), gcvtpk(acc[6] * e_, acc[7] * e_)};
;                 *(GAS v2u*)(CH + CH_Q + i * RS_W + c * 16) = w0; *(GAS v2u*)(CH + CH_Q + i * RS_W + c * 16 + 8) = w1;
;             }
.LBB0_932:
	s_or_b64 exec, exec, s[24:25]
	s_add_i32 s20, s33, 0x60
	s_waitcnt vmcnt(12)
	v_or_b32_e32 v50, s20, v103
	v_cmp_gt_i32_e32 vcc, s26, v50
	s_and_saveexec_b64 s[18:19], vcc
	s_cbranch_execz .LBB0_935
	s_waitcnt vmcnt(11)
	v_cndmask_b32_e64 v51, v42, 0, s[12:13]
	v_cndmask_b32_e64 v74, v43, 0, s[12:13]
	v_cndmask_b32_e64 v75, v44, 0, s[12:13]
	v_cndmask_b32_e64 v73, v45, 0, s[12:13]
	s_ashr_i32 s12, s20, 6
	v_mbcnt_lo_u32_b32 v72, -1, 0
	v_lshl_add_u32 v68, s12, 11, v102
	v_mbcnt_hi_u32_b32 v84, -1, v72
	s_waitcnt vmcnt(10)
	v_cndmask_b32_e64 v76, v38, 0, s[14:15]
	v_cndmask_b32_e64 v77, v39, 0, s[14:15]
	v_cndmask_b32_e64 v78, v40, 0, s[14:15]
	v_cndmask_b32_e64 v79, v41, 0, s[14:15]
	s_waitcnt vmcnt(9)
	v_cndmask_b32_e64 v80, v46, 0, s[16:17]
	v_cndmask_b32_e64 v81, v47, 0, s[16:17]
	v_cndmask_b32_e64 v82, v48, 0, s[16:17]
	v_cndmask_b32_e64 v83, v49, 0, s[16:17]
	ds_read_b128 v[38:41], v68
	ds_read_b128 v[42:45], v68 offset:16
	ds_read_b128 v[46:49], v68 offset:512
	ds_read_b128 v[52:55], v68 offset:528
	ds_read_b128 v[56:59], v68 offset:1024
	ds_read_b128 v[60:63], v68 offset:1040
	ds_read_b128 v[64:67], v68 offset:1536
	ds_read_b128 v[68:71], v68 offset:1552
	v_and_b32_e32 v72, 64, v84
	v_add_u32_e32 v85, 64, v72
	v_lshlrev_b32_e32 v72, 16, v73
	v_and_b32_e32 v73, 0xffff0000, v73
	s_waitcnt lgkmcnt(6)
	v_pk_fma_f32 v[44:45], v[44:45], v[72:73], 0 op_sel_hi:[1,1,0]
	v_lshlrev_b32_e32 v72, 16, v79
	v_and_b32_e32 v73, 0xffff0000, v79
	s_waitcnt lgkmcnt(4)
	v_pk_fma_f32 v[44:45], v[54:55], v[72:73], v[44:45]
	v_lshlrev_b32_e32 v54, 16, v83
	v_and_b32_e32 v55, 0xffff0000, v83
	s_waitcnt lgkmcnt(2)
	v_pk_fma_f32 v[44:45], v[62:63], v[54:55], v[44:45]
	s_waitcnt vmcnt(8)
	v_lshlrev_b32_e32 v54, 16, v37
	v_and_b32_e32 v55, 0xffff0000, v37
	s_waitcnt lgkmcnt(0)
	v_pk_fma_f32 v[44:45], v[70:71], v[54:55], v[44:45]
	v_xor_b32_e32 v62, 1, v84
	v_mul_f32_e32 v37, 0xbfb8aa3b, v44
	v_exp_f32_e32 v37, v37
	v_mul_f32_e32 v54, 0xbfb8aa3b, v45
	v_exp_f32_e32 v55, v54
	v_cmp_lt_i32_e32 vcc, v62, v85
	v_add_f32_e32 v37, 1.0, v37
	v_rcp_f32_e32 v54, v37
	v_add_f32_e32 v37, 1.0, v55
	v_rcp_f32_e32 v55, v37
	v_cndmask_b32_e32 v37, v84, v62, vcc
	v_lshlrev_b32_e32 v62, 2, v37
	s_cmp_lt_i32 s12, 2
	v_pk_mul_f32 v[44:45], v[44:45], v[54:55]
	v_lshlrev_b32_e32 v54, 16, v75
	v_and_b32_e32 v55, 0xffff0000, v75
	v_pk_fma_f32 v[42:43], v[42:43], v[54:55], 0 op_sel_hi:[1,1,0]
	v_lshlrev_b32_e32 v54, 16, v78
	v_and_b32_e32 v55, 0xffff0000, v78
	v_pk_fma_f32 v[42:43], v[52:53], v[54:55], v[42:43]
	v_lshlrev_b32_e32 v52, 16, v82
	v_and_b32_e32 v53, 0xffff0000, v82
	v_pk_fma_f32 v[42:43], v[60:61], v[52:53], v[42:43]
	v_lshlrev_b32_e32 v52, 16, v36
	v_and_b32_e32 v53, 0xffff0000, v36
	v_pk_fma_f32 v[36:37], v[68:69], v[52:53], v[42:43]
	v_lshlrev_b32_e32 v54, 16, v74
	v_mul_f32_e32 v42, 0xbfb8aa3b, v36
	v_exp_f32_e32 v52, v42
	v_mul_f32_e32 v42, 0xbfb8aa3b, v37
	v_exp_f32_e32 v53, v42
	v_and_b32_e32 v55, 0xffff0000, v74
	v_pk_fma_f32 v[40:41], v[40:41], v[54:55], 0 op_sel_hi:[1,1,0]
	v_lshlrev_b32_e32 v54, 16, v77
	v_and_b32_e32 v55, 0xffff0000, v77
	v_add_f32_e32 v52, 1.0, v52
	v_add_f32_e32 v53, 1.0, v53
	v_pk_fma_f32 v[40:41], v[48:49], v[54:55], v[40:41]
	v_lshlrev_b32_e32 v48, 16, v81
	v_and_b32_e32 v49, 0xffff0000, v81
	v_rcp_f32_e32 v52, v52
	v_rcp_f32_e32 v53, v53
	v_pk_fma_f32 v[40:41], v[58:59], v[48:49], v[40:41]
	v_lshlrev_b32_e32 v48, 16, v35
	v_and_b32_e32 v49, 0xffff0000, v35
	v_pk_fma_f32 v[40:41], v[66:67], v[48:49], v[40:41]
	v_pk_mul_f32 v[36:37], v[36:37], v[52:53]
	v_mul_f32_e32 v35, 0xbfb8aa3b, v40
	v_exp_f32_e32 v35, v35
	v_lshlrev_b32_e32 v52, 16, v51
	v_and_b32_e32 v53, 0xffff0000, v51
	v_pk_fma_f32 v[38:39], v[38:39], v[52:53], 0 op_sel_hi:[1,1,0]
	v_lshlrev_b32_e32 v52, 16, v76
	v_and_b32_e32 v53, 0xffff0000, v76
	v_pk_fma_f32 v[38:39], v[46:47], v[52:53], v[38:39]
	v_lshlrev_b32_e32 v46, 16, v80
	v_and_b32_e32 v47, 0xffff0000, v80
	v_mul_f32_e32 v48, 0xbfb8aa3b, v41
	v_add_f32_e32 v35, 1.0, v35
	v_pk_fma_f32 v[38:39], v[56:57], v[46:47], v[38:39]
	v_lshlrev_b32_e32 v46, 16, v34
	v_and_b32_e32 v47, 0xffff0000, v34
	v_exp_f32_e32 v49, v48
	v_rcp_f32_e32 v48, v35
	v_pk_fma_f32 v[34:35], v[64:65], v[46:47], v[38:39]
	v_pk_mul_f32 v[46:47], v[36:37], v[36:37]
	v_mul_f32_e32 v38, 0xbfb8aa3b, v34
	v_mul_f32_e32 v39, 0xbfb8aa3b, v35
	v_exp_f32_e32 v38, v38
	v_exp_f32_e32 v39, v39
	v_add_f32_e32 v49, 1.0, v49
	v_rcp_f32_e32 v49, v49
	v_add_f32_e32 v38, 1.0, v38
	v_add_f32_e32 v39, 1.0, v39
	v_rcp_f32_e32 v38, v38
	v_rcp_f32_e32 v39, v39
	v_pk_mul_f32 v[48:49], v[40:41], v[48:49]
	v_pk_mul_f32 v[42:43], v[44:45], v[44:45]
	v_pk_mul_f32 v[40:41], v[48:49], v[48:49]
	v_pk_mul_f32 v[34:35], v[34:35], v[38:39]
	s_mulk_i32 s12, 0x4400
	v_pk_mul_f32 v[38:39], v[34:35], v[34:35]
	s_nop 0
	v_add_f32_e32 v38, v38, v39
	v_add_f32_e32 v38, v40, v38
	v_add_f32_e32 v38, v41, v38
	v_add_f32_e32 v38, v46, v38
	v_add_f32_e32 v38, v47, v38
	v_add_f32_e32 v38, v42, v38
	v_add_f32_e32 v38, v43, v38
	s_nop 1
	v_mov_b32_dpp v39, v38 quad_perm:[1,0,3,2] row_mask:0xf bank_mask:0xf
	v_xor_b32_e32 v40, 2, v84
	v_cmp_lt_i32_e32 vcc, v40, v85
	s_waitcnt lgkmcnt(0)
	v_add_f32_e32 v38, v38, v39
	v_cndmask_b32_e32 v40, v84, v40, vcc
	v_lshlrev_b32_e32 v40, 2, v40
	s_nop 1
	v_mov_b32_dpp v39, v38 quad_perm:[2,3,0,1] row_mask:0xf bank_mask:0xf
	v_xor_b32_e32 v40, 4, v84
	v_cmp_lt_i32_e32 vcc, v40, v85
	s_waitcnt lgkmcnt(0)
	v_add_f32_e32 v38, v38, v39
	v_cndmask_b32_e32 v40, v84, v40, vcc
	v_lshlrev_b32_e32 v40, 2, v40
	s_nop 1
	v_mov_b32_dpp v39, v38 row_half_mirror row_mask:0xf bank_mask:0xf
	v_xor_b32_e32 v40, 8, v84
	v_cmp_lt_i32_e32 vcc, v40, v85
	s_waitcnt lgkmcnt(0)
	v_add_f32_e32 v38, v38, v39
	v_cndmask_b32_e32 v40, v84, v40, vcc
	v_lshlrev_b32_e32 v40, 2, v40
	s_nop 1
	v_mov_b32_dpp v39, v38 row_mirror row_mask:0xf bank_mask:0xf
	s_cselect_b64 vcc, -1, 0
	s_cmp_lt_u32 s20, 64
	s_waitcnt lgkmcnt(0)
	v_add_f32_e32 v38, v38, v39
	v_add_f32_e32 v38, 0x358637bd, v38
	v_rsq_f32_e32 v38, v38
	s_nop 0
	v_cndmask_b32_e32 v38, 1.0, v38, vcc
	v_mul_f32_e32 v39, 0x3db504f3, v38
	s_cselect_b64 vcc, -1, 0
	v_cndmask_b32_e32 v42, v38, v39, vcc
	v_pk_mul_f32 v[40:41], v[34:35], v[42:43] op_sel_hi:[1,0]
	v_pk_mul_f32 v[38:39], v[48:49], v[42:43] op_sel_hi:[1,0]
	v_pk_mul_f32 v[36:37], v[36:37], v[42:43] op_sel_hi:[1,0]
	v_pk_mul_f32 v[34:35], v[44:45], v[42:43] op_sel_hi:[1,0]
	v_and_b32_e32 v42, 63, v50
	s_add_i32 s12, s12, 0
	v_mul_u32_u24_e32 v43, 0x110, v42
	s_cmp_gt_u32 s20, 63
	v_cvt_pk_bf16_f32 v44, v40, v41
	v_cvt_pk_bf16_f32 v45, v38, v39
	v_cvt_pk_bf16_f32 v46, v36, v37
	v_cvt_pk_bf16_f32 v47, v34, v35
	v_add3_u32 v43, s12, v43, v100
	ds_write_b128 v43, v[44:47] offset:28672
	s_cbranch_scc1 .LBB0_935
; #define GAS __attribute__((address_space(1)))
; #define LAS __attribute__((address_space(3)))
; __device__ __forceinline__ float siluf_(float x) { return x * __builtin_amdgcn_rcpf(1.0f + __builtin_amdgcn_exp2f(-1.4426950408889634f * x)); }
; __device__ __forceinline__ float sum16(float v) {
; #pragma unroll
;     for (int o = 1; o < 16; o <<= 1) v += __shfl_xor(v, o);
;     return v;
; }
; template <int NW>
; __device__ __forceinline__ void gp_stage0_compute(Frame& F, int cidx, const LAS float* Gs, LAS unsigned char* tiles, int w, int lane, const GpTaps<NW>& tp) {
;     ...
;             float acc[8];
; #pragma unroll
;             for (int e = 0; e < 8; ++e) acc[e] = 0.f;
; #pragma unroll
;             for (int tap = 0; tap < 4; ++tap) {
;                 const v4u xv = tp.xw[it][tap];
;                 const LAS float* cw = cwl + (type * 4 + tap) * 128 + c * 8;
;                 const f32x4 c0 = *(const LAS f32x4*)cw, c1 = *(const LAS f32x4*)(cw + 4);
;                 acc[0] += bflo(xv.x) * c0.x; acc[1] += bfhi(xv.x) * c0.y; acc[2] += bflo(xv.y) * c0.z; acc[3] += bfhi(xv.y) * c0.w;
;                 acc[4] += bflo(xv.z) * c1.x; acc[5] += bfhi(xv.z) * c1.y; acc[6] += bflo(xv.w) * c1.z; acc[7] += bfhi(xv.w) * c1.w;
;             }
;             float ss = 0.f;
; #pragma unroll
;             for (int e = 0; e < 8; ++e) { acc[e] = siluf_(acc[e]); ss += acc[e] * acc[e]; }
;             ss = sum16(ss);
;             float sc = 1.0f;
;             if (type < 2) sc = __builtin_amdgcn_rsqf(ss + EPS);
;             if (type == 0) sc *= 0.08838834764831845f;
; #pragma unroll
;             for (int e = 0; e < 8; ++e) acc[e] *= sc;
;             const v4u o = {gcvtpk(acc[0], acc[1]), gcvtpk(acc[2], acc[3]), gcvtpk(acc[4], acc[5]), gcvtpk(acc[6], acc[7])};
;             *(LAS v4u*)(tiles + type * GP_TILE + i * GP_TS + c * 16) = o;
;             if (type == 0) {
;                 const float e_ = Gs[128 + i];
;                 v2u w0 = {gcvtpk(acc[0] * e_, acc[1] * e_), gcvtpk(acc[2] * e_, acc[3] * e_)}, w1 = {gcvtpk(acc[4] * e_, acc[5] * e_), gcvtpk(acc[6] * e_, acc[7] * e_)};
;                 *(GAS v2u*)(CH + CH_Q + i * RS_W + c * 16) = w0; *(GAS v2u*)(CH + CH_Q + i * RS_W + c * 16 + 8) = w1;
;             }
	v_add_u32_e32 v43, s33, v103
	v_lshl_add_u32 v43, v43, 2, 0
	ds_read_b32 v44, v43 offset:896
	s_waitcnt lgkmcnt(0)
	v_pk_mul_f32 v[38:39], v[38:39], v[44:45] op_sel_hi:[1,0]
	v_pk_mul_f32 v[34:35], v[34:35], v[44:45] op_sel_hi:[1,0]
	v_pk_mul_f32 v[40:41], v[40:41], v[44:45] op_sel_hi:[1,0]
	v_pk_mul_f32 v[46:47], v[36:37], v[44:45] op_sel_hi:[1,0]
	v_cvt_pk_bf16_f32 v37, v38, v39
	v_cvt_pk_bf16_f32 v39, v34, v35
	v_mul_u32_u24_e32 v34, 0x108, v42
	v_mov_b32_e32 v35, 0
	v_cvt_pk_bf16_f32 v36, v40, v41
	v_cvt_pk_bf16_f32 v38, v46, v47
	v_lshl_add_u64 v[34:35], v[98:99], 0, v[34:35]
	global_store_dwordx4 v[34:35], v[36:39], off
.LBB0_935:
	s_or_b64 exec, exec, s[18:19]
	s_add_i32 s15, s33, 0x80
	s_waitcnt vmcnt(8)
	v_or_b32_e32 v34, s15, v103
	s_movk_i32 s14, 0xc0
	v_cmp_gt_i32_e32 vcc, s14, v34
	s_and_saveexec_b64 s[12:13], vcc
	s_cbranch_execz .LBB0_938
	s_waitcnt vmcnt(7)
	v_cndmask_b32_e64 v35, v26, 0, s[6:7]
	v_cndmask_b32_e64 v58, v27, 0, s[6:7]
	v_cndmask_b32_e64 v59, v28, 0, s[6:7]
	v_cndmask_b32_e64 v57, v29, 0, s[6:7]
	s_ashr_i32 s6, s15, 6
	v_mbcnt_lo_u32_b32 v56, -1, 0
	v_lshl_add_u32 v52, s6, 11, v102
	v_mbcnt_hi_u32_b32 v68, -1, v56
	s_waitcnt vmcnt(6)
	v_cndmask_b32_e64 v60, v22, 0, s[8:9]
	v_cndmask_b32_e64 v61, v23, 0, s[8:9]
	v_cndmask_b32_e64 v62, v24, 0, s[8:9]
	v_cndmask_b32_e64 v63, v25, 0, s[8:9]
	s_waitcnt vmcnt(5)
	v_cndmask_b32_e64 v64, v30, 0, s[10:11]
	v_cndmask_b32_e64 v65, v31, 0, s[10:11]
	v_cndmask_b32_e64 v66, v32, 0, s[10:11]
	v_cndmask_b32_e64 v67, v33, 0, s[10:11]
	ds_read_b128 v[22:25], v52
	ds_read_b128 v[26:29], v52 offset:16
	ds_read_b128 v[30:33], v52 offset:512
	ds_read_b128 v[36:39], v52 offset:528
	ds_read_b128 v[40:43], v52 offset:1024
	ds_read_b128 v[44:47], v52 offset:1040
	ds_read_b128 v[48:51], v52 offset:1536
	ds_read_b128 v[52:55], v52 offset:1552
	v_and_b32_e32 v56, 64, v68
	v_add_u32_e32 v69, 64, v56
	v_lshlrev_b32_e32 v56, 16, v57
	v_and_b32_e32 v57, 0xffff0000, v57
	s_waitcnt lgkmcnt(6)
	v_pk_fma_f32 v[28:29], v[28:29], v[56:57], 0 op_sel_hi:[1,1,0]
	v_lshlrev_b32_e32 v56, 16, v63
	v_and_b32_e32 v57, 0xffff0000, v63
	s_waitcnt lgkmcnt(4)
	v_pk_fma_f32 v[28:29], v[38:39], v[56:57], v[28:29]
	v_lshlrev_b32_e32 v38, 16, v67
	v_and_b32_e32 v39, 0xffff0000, v67
	s_waitcnt lgkmcnt(2)
	v_pk_fma_f32 v[28:29], v[46:47], v[38:39], v[28:29]
	s_waitcnt vmcnt(4)
	v_lshlrev_b32_e32 v38, 16, v21
	v_and_b32_e32 v39, 0xffff0000, v21
	s_waitcnt lgkmcnt(0)
	v_pk_fma_f32 v[28:29], v[54:55], v[38:39], v[28:29]
	v_xor_b32_e32 v46, 1, v68
	v_mul_f32_e32 v21, 0xbfb8aa3b, v28
	v_exp_f32_e32 v21, v21
	v_mul_f32_e32 v38, 0xbfb8aa3b, v29
	v_exp_f32_e32 v39, v38
	v_cmp_lt_i32_e32 vcc, v46, v69
	v_add_f32_e32 v21, 1.0, v21
	v_rcp_f32_e32 v38, v21
	v_add_f32_e32 v21, 1.0, v39
	v_rcp_f32_e32 v39, v21
	v_cndmask_b32_e32 v21, v68, v46, vcc
	v_lshlrev_b32_e32 v46, 2, v21
	s_cmp_lt_i32 s6, 2
	v_pk_mul_f32 v[28:29], v[28:29], v[38:39]
	v_lshlrev_b32_e32 v38, 16, v59
	v_and_b32_e32 v39, 0xffff0000, v59
	v_pk_fma_f32 v[26:27], v[26:27], v[38:39], 0 op_sel_hi:[1,1,0]
	v_lshlrev_b32_e32 v38, 16, v62
	v_and_b32_e32 v39, 0xffff0000, v62
	v_pk_fma_f32 v[26:27], v[36:37], v[38:39], v[26:27]
	v_lshlrev_b32_e32 v36, 16, v66
	v_and_b32_e32 v37, 0xffff0000, v66
	v_pk_fma_f32 v[26:27], v[44:45], v[36:37], v[26:27]
	v_lshlrev_b32_e32 v36, 16, v20
	v_and_b32_e32 v37, 0xffff0000, v20
	v_pk_fma_f32 v[20:21], v[52:53], v[36:37], v[26:27]
	v_lshlrev_b32_e32 v38, 16, v58
	v_mul_f32_e32 v26, 0xbfb8aa3b, v20
	v_exp_f32_e32 v36, v26
	v_mul_f32_e32 v26, 0xbfb8aa3b, v21
	v_exp_f32_e32 v37, v26
	v_and_b32_e32 v39, 0xffff0000, v58
	v_pk_fma_f32 v[24:25], v[24:25], v[38:39], 0 op_sel_hi:[1,1,0]
	v_lshlrev_b32_e32 v38, 16, v61
	v_and_b32_e32 v39, 0xffff0000, v61
	v_add_f32_e32 v36, 1.0, v36
	v_add_f32_e32 v37, 1.0, v37
	v_pk_fma_f32 v[24:25], v[32:33], v[38:39], v[24:25]
	v_lshlrev_b32_e32 v32, 16, v65
	v_and_b32_e32 v33, 0xffff0000, v65
	v_rcp_f32_e32 v36, v36
	v_rcp_f32_e32 v37, v37
	v_pk_fma_f32 v[24:25], v[42:43], v[32:33], v[24:25]
	v_lshlrev_b32_e32 v32, 16, v19
	v_and_b32_e32 v33, 0xffff0000, v19
	v_pk_fma_f32 v[24:25], v[50:51], v[32:33], v[24:25]
	v_pk_mul_f32 v[20:21], v[20:21], v[36:37]
	v_mul_f32_e32 v19, 0xbfb8aa3b, v24
	v_exp_f32_e32 v19, v19
	v_lshlrev_b32_e32 v36, 16, v35
	v_and_b32_e32 v37, 0xffff0000, v35
	v_pk_fma_f32 v[22:23], v[22:23], v[36:37], 0 op_sel_hi:[1,1,0]
	v_lshlrev_b32_e32 v36, 16, v60
	v_and_b32_e32 v37, 0xffff0000, v60
	v_pk_fma_f32 v[22:23], v[30:31], v[36:37], v[22:23]
	v_lshlrev_b32_e32 v30, 16, v64
	v_and_b32_e32 v31, 0xffff0000, v64
	v_mul_f32_e32 v32, 0xbfb8aa3b, v25
	v_add_f32_e32 v19, 1.0, v19
	v_pk_fma_f32 v[22:23], v[40:41], v[30:31], v[22:23]
	v_lshlrev_b32_e32 v30, 16, v18
	v_and_b32_e32 v31, 0xffff0000, v18
	v_exp_f32_e32 v33, v32
	v_rcp_f32_e32 v32, v19
	v_pk_fma_f32 v[18:19], v[48:49], v[30:31], v[22:23]
	v_pk_mul_f32 v[30:31], v[20:21], v[20:21]
	v_mul_f32_e32 v22, 0xbfb8aa3b, v18
	v_mul_f32_e32 v23, 0xbfb8aa3b, v19
	v_exp_f32_e32 v22, v22
	v_exp_f32_e32 v23, v23
	v_add_f32_e32 v33, 1.0, v33
	v_rcp_f32_e32 v33, v33
	v_add_f32_e32 v22, 1.0, v22
	v_add_f32_e32 v23, 1.0, v23
	v_rcp_f32_e32 v22, v22
	v_rcp_f32_e32 v23, v23
	v_pk_mul_f32 v[32:33], v[24:25], v[32:33]
	v_pk_mul_f32 v[26:27], v[28:29], v[28:29]
	v_pk_mul_f32 v[24:25], v[32:33], v[32:33]
	v_pk_mul_f32 v[18:19], v[18:19], v[22:23]
	s_mulk_i32 s6, 0x4400
	v_pk_mul_f32 v[22:23], v[18:19], v[18:19]
	s_nop 0
	v_add_f32_e32 v22, v22, v23
	v_add_f32_e32 v22, v24, v22
	v_add_f32_e32 v22, v25, v22
	v_add_f32_e32 v22, v30, v22
	v_add_f32_e32 v22, v31, v22
	v_add_f32_e32 v22, v26, v22
	v_add_f32_e32 v22, v27, v22
	s_nop 1
	v_mov_b32_dpp v23, v22 quad_perm:[1,0,3,2] row_mask:0xf bank_mask:0xf
	v_xor_b32_e32 v24, 2, v68
	v_cmp_lt_i32_e32 vcc, v24, v69
	s_waitcnt lgkmcnt(0)
; #define GAS __attribute__((address_space(1)))
; #define LAS __attribute__((address_space(3)))
; __device__ __forceinline__ float siluf_(float x) { return x * __builtin_amdgcn_rcpf(1.0f + __builtin_amdgcn_exp2f(-1.4426950408889634f * x)); }
; __device__ __forceinline__ unsigned gcvtpk(float lo, float hi) { gf32x2 v = {lo, hi}; gbf16x2 b = __builtin_convertvector(v, gbf16x2); return __builtin_bit_cast(unsigned, b); }
; __device__ __forceinline__ float sum16(float v) {
; #pragma unroll
;     for (int o = 1; o < 16; o <<= 1) v += __shfl_xor(v, o);
;     return v;
; }
; template <int NW>
; __device__ __forceinline__ void gp_stage0_compute(Frame& F, int cidx, const LAS float* Gs, LAS unsigned char* tiles, int w, int lane, const GpTaps<NW>& tp) {
;     ...
;             float ss = 0.f;
; #pragma unroll
;             for (int e = 0; e < 8; ++e) { acc[e] = siluf_(acc[e]); ss += acc[e] * acc[e]; }
;             ss = sum16(ss);
;             float sc = 1.0f;
;             if (type < 2) sc = __builtin_amdgcn_rsqf(ss + EPS);
;             if (type == 0) sc *= 0.08838834764831845f;
; #pragma unroll
;             for (int e = 0; e < 8; ++e) acc[e] *= sc;
;             const v4u o = {gcvtpk(acc[0], acc[1]), gcvtpk(acc[2], acc[3]), gcvtpk(acc[4], acc[5]), gcvtpk(acc[6], acc[7])};
;             *(LAS v4u*)(tiles + type * GP_TILE + i * GP_TS + c * 16) = o;
;             if (type == 0) {
;                 const float e_ = Gs[128 + i];
;                 v2u w0 = {gcvtpk(acc[0] * e_, acc[1] * e_), gcvtpk(acc[2] * e_, acc[3] * e_)}, w1 = {gcvtpk(acc[4] * e_, acc[5] * e_), gcvtpk(acc[6] * e_, acc[7] * e_)};
;                 *(GAS v2u*)(CH + CH_Q + i * RS_W + c * 16) = w0; *(GAS v2u*)(CH + CH_Q + i * RS_W + c * 16 + 8) = w1;
;             }
	v_add_f32_e32 v22, v22, v23
	v_cndmask_b32_e32 v24, v68, v24, vcc
	v_lshlrev_b32_e32 v24, 2, v24
	s_nop 1
	v_mov_b32_dpp v23, v22 quad_perm:[2,3,0,1] row_mask:0xf bank_mask:0xf
	v_xor_b32_e32 v24, 4, v68
	v_cmp_lt_i32_e32 vcc, v24, v69
	s_waitcnt lgkmcnt(0)
	v_add_f32_e32 v22, v22, v23
	v_cndmask_b32_e32 v24, v68, v24, vcc
	v_lshlrev_b32_e32 v24, 2, v24
	s_nop 1
	v_mov_b32_dpp v23, v22 row_half_mirror row_mask:0xf bank_mask:0xf
	v_xor_b32_e32 v24, 8, v68
	v_cmp_lt_i32_e32 vcc, v24, v69
	s_waitcnt lgkmcnt(0)
	v_add_f32_e32 v22, v22, v23
	v_cndmask_b32_e32 v24, v68, v24, vcc
	v_lshlrev_b32_e32 v24, 2, v24
	s_nop 1
	v_mov_b32_dpp v23, v22 row_mirror row_mask:0xf bank_mask:0xf
	s_cselect_b64 vcc, -1, 0
	s_cmp_lt_u32 s15, 64
	s_waitcnt lgkmcnt(0)
	v_add_f32_e32 v22, v22, v23
	v_add_f32_e32 v22, 0x358637bd, v22
	v_rsq_f32_e32 v22, v22
	s_nop 0
	v_cndmask_b32_e32 v22, 1.0, v22, vcc
	v_mul_f32_e32 v23, 0x3db504f3, v22
	s_cselect_b64 vcc, -1, 0
	v_cndmask_b32_e32 v26, v22, v23, vcc
	v_pk_mul_f32 v[24:25], v[18:19], v[26:27] op_sel_hi:[1,0]
	v_pk_mul_f32 v[22:23], v[32:33], v[26:27] op_sel_hi:[1,0]
	v_pk_mul_f32 v[20:21], v[20:21], v[26:27] op_sel_hi:[1,0]
	v_pk_mul_f32 v[18:19], v[28:29], v[26:27] op_sel_hi:[1,0]
	v_and_b32_e32 v26, 63, v34
	s_add_i32 s6, s6, 0
	v_mul_u32_u24_e32 v27, 0x110, v26
	s_cmp_gt_u32 s15, 63
	v_cvt_pk_bf16_f32 v28, v24, v25
	v_cvt_pk_bf16_f32 v29, v22, v23
	v_cvt_pk_bf16_f32 v30, v20, v21
	v_cvt_pk_bf16_f32 v31, v18, v19
	v_add3_u32 v27, s6, v27, v100
	ds_write_b128 v27, v[28:31] offset:28672
	s_cbranch_scc1 .LBB0_938
	v_add_u32_e32 v27, s33, v103
	v_lshl_add_u32 v27, v27, 2, 0
	ds_read_b32 v28, v27 offset:1024
	s_waitcnt lgkmcnt(0)
	v_pk_mul_f32 v[22:23], v[22:23], v[28:29] op_sel_hi:[1,0]
	v_pk_mul_f32 v[18:19], v[18:19], v[28:29] op_sel_hi:[1,0]
	v_pk_mul_f32 v[24:25], v[24:25], v[28:29] op_sel_hi:[1,0]
	v_pk_mul_f32 v[30:31], v[20:21], v[28:29] op_sel_hi:[1,0]
	v_cvt_pk_bf16_f32 v21, v22, v23
	v_cvt_pk_bf16_f32 v23, v18, v19
	v_mul_u32_u24_e32 v18, 0x108, v26
	v_mov_b32_e32 v19, 0
	v_cvt_pk_bf16_f32 v20, v24, v25
	v_cvt_pk_bf16_f32 v22, v30, v31
	v_lshl_add_u64 v[18:19], v[98:99], 0, v[18:19]
	global_store_dwordx4 v[18:19], v[20:23], off
.LBB0_938:
	v_writelane_b32 v252, s88, 40
	s_nop 1
	v_writelane_b32 v252, s89, 41
	v_writelane_b32 v252, s84, 42
	s_nop 1
	v_writelane_b32 v252, s85, 43
	v_writelane_b32 v252, s86, 44
	s_nop 1
	v_writelane_b32 v252, s87, 45
	s_or_b64 exec, exec, s[12:13]
	s_add_i32 s8, s33, 0xa0
	s_waitcnt vmcnt(4)
	v_or_b32_e32 v18, s8, v103
	v_cmp_gt_i32_e32 vcc, s14, v18
	s_and_saveexec_b64 s[6:7], vcc
	s_cbranch_execz .LBB0_941
; #define GAS __attribute__((address_space(1)))
; #define LAS __attribute__((address_space(3)))
; __device__ __forceinline__ float siluf_(float x) { return x * __builtin_amdgcn_rcpf(1.0f + __builtin_amdgcn_exp2f(-1.4426950408889634f * x)); }
; __device__ __forceinline__ float sum16(float v) {
; #pragma unroll
;     for (int o = 1; o < 16; o <<= 1) v += __shfl_xor(v, o);
;     return v;
; }
; template <int NW>
; __device__ __forceinline__ void gp_stage0_compute(Frame& F, int cidx, const LAS float* Gs, LAS unsigned char* tiles, int w, int lane, const GpTaps<NW>& tp) {
;     ...
;             float acc[8];
; #pragma unroll
;             for (int e = 0; e < 8; ++e) acc[e] = 0.f;
; #pragma unroll
;             for (int tap = 0; tap < 4; ++tap) {
;                 const v4u xv = tp.xw[it][tap];
;                 const LAS float* cw = cwl + (type * 4 + tap) * 128 + c * 8;
;                 const f32x4 c0 = *(const LAS f32x4*)cw, c1 = *(const LAS f32x4*)(cw + 4);
;                 acc[0] += bflo(xv.x) * c0.x; acc[1] += bfhi(xv.x) * c0.y; acc[2] += bflo(xv.y) * c0.z; acc[3] += bfhi(xv.y) * c0.w;
;                 acc[4] += bflo(xv.z) * c1.x; acc[5] += bfhi(xv.z) * c1.y; acc[6] += bflo(xv.w) * c1.z; acc[7] += bfhi(xv.w) * c1.w;
;             }
;             float ss = 0.f;
; #pragma unroll
;             for (int e = 0; e < 8; ++e) { acc[e] = siluf_(acc[e]); ss += acc[e] * acc[e]; }
;             ss = sum16(ss);
;             float sc = 1.0f;
;             if (type < 2) sc = __builtin_amdgcn_rsqf(ss + EPS);
;             if (type == 0) sc *= 0.08838834764831845f;
; #pragma unroll
;             for (int e = 0; e < 8; ++e) acc[e] *= sc;
;             const v4u o = {gcvtpk(acc[0], acc[1]), gcvtpk(acc[2], acc[3]), gcvtpk(acc[4], acc[5]), gcvtpk(acc[6], acc[7])};
;             *(LAS v4u*)(tiles + type * GP_TILE + i * GP_TS + c * 16) = o;
;             if (type == 0) {
;                 const float e_ = Gs[128 + i];
;                 v2u w0 = {gcvtpk(acc[0] * e_, acc[1] * e_), gcvtpk(acc[2] * e_, acc[3] * e_)}, w1 = {gcvtpk(acc[4] * e_, acc[5] * e_), gcvtpk(acc[6] * e_, acc[7] * e_)};
;                 *(GAS v2u*)(CH + CH_Q + i * RS_W + c * 16) = w0; *(GAS v2u*)(CH + CH_Q + i * RS_W + c * 16 + 8) = w1;
;             }
	s_waitcnt vmcnt(3)
	v_cndmask_b32_e64 v19, v10, 0, s[0:1]
	v_cndmask_b32_e64 v42, v11, 0, s[0:1]
	v_cndmask_b32_e64 v43, v12, 0, s[0:1]
	v_cndmask_b32_e64 v41, v13, 0, s[0:1]
	s_ashr_i32 s0, s8, 6
	v_mbcnt_lo_u32_b32 v40, -1, 0
	v_lshl_add_u32 v36, s0, 11, v102
	v_mbcnt_hi_u32_b32 v52, -1, v40
	s_waitcnt vmcnt(2)
	v_cndmask_b32_e64 v44, v6, 0, s[68:69]
	v_cndmask_b32_e64 v45, v7, 0, s[68:69]
	v_cndmask_b32_e64 v46, v8, 0, s[68:69]
	v_cndmask_b32_e64 v47, v9, 0, s[68:69]
	s_waitcnt vmcnt(1)
	v_cndmask_b32_e64 v48, v14, 0, s[4:5]
	v_cndmask_b32_e64 v49, v15, 0, s[4:5]
	v_cndmask_b32_e64 v50, v16, 0, s[4:5]
	v_cndmask_b32_e64 v51, v17, 0, s[4:5]
	ds_read_b128 v[6:9], v36
	ds_read_b128 v[10:13], v36 offset:16
	ds_read_b128 v[14:17], v36 offset:512
	ds_read_b128 v[20:23], v36 offset:528
	ds_read_b128 v[24:27], v36 offset:1024
	ds_read_b128 v[28:31], v36 offset:1040
	ds_read_b128 v[32:35], v36 offset:1536
	ds_read_b128 v[36:39], v36 offset:1552
	v_and_b32_e32 v40, 64, v52
	v_add_u32_e32 v53, 64, v40
	v_lshlrev_b32_e32 v40, 16, v41
	v_and_b32_e32 v41, 0xffff0000, v41
	s_waitcnt lgkmcnt(6)
	v_pk_fma_f32 v[12:13], v[12:13], v[40:41], 0 op_sel_hi:[1,1,0]
	v_lshlrev_b32_e32 v40, 16, v47
	v_and_b32_e32 v41, 0xffff0000, v47
	s_waitcnt lgkmcnt(4)
	v_pk_fma_f32 v[12:13], v[22:23], v[40:41], v[12:13]
	v_lshlrev_b32_e32 v22, 16, v51
	v_and_b32_e32 v23, 0xffff0000, v51
	s_waitcnt lgkmcnt(2)
	v_pk_fma_f32 v[12:13], v[30:31], v[22:23], v[12:13]
	s_waitcnt vmcnt(0)
	v_lshlrev_b32_e32 v22, 16, v5
	v_and_b32_e32 v23, 0xffff0000, v5
	s_waitcnt lgkmcnt(0)
	v_pk_fma_f32 v[12:13], v[38:39], v[22:23], v[12:13]
	v_xor_b32_e32 v30, 1, v52
	v_mul_f32_e32 v5, 0xbfb8aa3b, v12
	v_exp_f32_e32 v5, v5
	v_mul_f32_e32 v22, 0xbfb8aa3b, v13
	v_exp_f32_e32 v23, v22
	v_cmp_lt_i32_e32 vcc, v30, v53
	v_add_f32_e32 v5, 1.0, v5
	v_rcp_f32_e32 v22, v5
	v_add_f32_e32 v5, 1.0, v23
	v_rcp_f32_e32 v23, v5
	v_cndmask_b32_e32 v5, v52, v30, vcc
	v_lshlrev_b32_e32 v30, 2, v5
	s_cmp_lt_i32 s0, 2
	v_pk_mul_f32 v[12:13], v[12:13], v[22:23]
	v_lshlrev_b32_e32 v22, 16, v43
	v_and_b32_e32 v23, 0xffff0000, v43
	v_pk_fma_f32 v[10:11], v[10:11], v[22:23], 0 op_sel_hi:[1,1,0]
	v_lshlrev_b32_e32 v22, 16, v46
	v_and_b32_e32 v23, 0xffff0000, v46
	v_pk_fma_f32 v[10:11], v[20:21], v[22:23], v[10:11]
	v_lshlrev_b32_e32 v20, 16, v50
	v_and_b32_e32 v21, 0xffff0000, v50
	v_pk_fma_f32 v[10:11], v[28:29], v[20:21], v[10:11]
	v_lshlrev_b32_e32 v20, 16, v4
	v_and_b32_e32 v21, 0xffff0000, v4
	v_pk_fma_f32 v[4:5], v[36:37], v[20:21], v[10:11]
	v_lshlrev_b32_e32 v22, 16, v42
	v_mul_f32_e32 v10, 0xbfb8aa3b, v4
	v_exp_f32_e32 v20, v10
	v_mul_f32_e32 v10, 0xbfb8aa3b, v5
	v_exp_f32_e32 v21, v10
	v_and_b32_e32 v23, 0xffff0000, v42
	v_pk_fma_f32 v[8:9], v[8:9], v[22:23], 0 op_sel_hi:[1,1,0]
	v_lshlrev_b32_e32 v22, 16, v45
	v_and_b32_e32 v23, 0xffff0000, v45
	v_add_f32_e32 v20, 1.0, v20
	v_add_f32_e32 v21, 1.0, v21
	v_pk_fma_f32 v[8:9], v[16:17], v[22:23], v[8:9]
	v_lshlrev_b32_e32 v16, 16, v49
	v_and_b32_e32 v17, 0xffff0000, v49
	v_rcp_f32_e32 v20, v20
	v_rcp_f32_e32 v21, v21
	v_pk_fma_f32 v[8:9], v[26:27], v[16:17], v[8:9]
	v_lshlrev_b32_e32 v16, 16, v3
	v_and_b32_e32 v17, 0xffff0000, v3
	v_pk_fma_f32 v[8:9], v[34:35], v[16:17], v[8:9]
	v_pk_mul_f32 v[4:5], v[4:5], v[20:21]
	v_mul_f32_e32 v3, 0xbfb8aa3b, v8
	v_exp_f32_e32 v3, v3
	v_lshlrev_b32_e32 v20, 16, v19
	v_and_b32_e32 v21, 0xffff0000, v19
	v_pk_fma_f32 v[6:7], v[6:7], v[20:21], 0 op_sel_hi:[1,1,0]
	v_lshlrev_b32_e32 v20, 16, v44
	v_and_b32_e32 v21, 0xffff0000, v44
	v_pk_fma_f32 v[6:7], v[14:15], v[20:21], v[6:7]
	v_lshlrev_b32_e32 v14, 16, v48
	v_and_b32_e32 v15, 0xffff0000, v48
	v_mul_f32_e32 v16, 0xbfb8aa3b, v9
	v_add_f32_e32 v3, 1.0, v3
	v_pk_fma_f32 v[6:7], v[24:25], v[14:15], v[6:7]
	v_lshlrev_b32_e32 v14, 16, v2
	v_and_b32_e32 v15, 0xffff0000, v2
	v_exp_f32_e32 v17, v16
	v_rcp_f32_e32 v16, v3
	v_pk_fma_f32 v[2:3], v[32:33], v[14:15], v[6:7]
	v_pk_mul_f32 v[14:15], v[4:5], v[4:5]
	v_mul_f32_e32 v6, 0xbfb8aa3b, v2
	v_mul_f32_e32 v7, 0xbfb8aa3b, v3
	v_exp_f32_e32 v6, v6
	v_exp_f32_e32 v7, v7
	v_add_f32_e32 v17, 1.0, v17
	v_rcp_f32_e32 v17, v17
	v_add_f32_e32 v6, 1.0, v6
	v_add_f32_e32 v7, 1.0, v7
	v_rcp_f32_e32 v6, v6
	v_rcp_f32_e32 v7, v7
	v_pk_mul_f32 v[16:17], v[8:9], v[16:17]
	v_pk_mul_f32 v[10:11], v[12:13], v[12:13]
	v_pk_mul_f32 v[8:9], v[16:17], v[16:17]
	v_pk_mul_f32 v[2:3], v[2:3], v[6:7]
	s_mulk_i32 s0, 0x4400
	v_pk_mul_f32 v[6:7], v[2:3], v[2:3]
	s_nop 0
	v_add_f32_e32 v6, v6, v7
	v_add_f32_e32 v6, v8, v6
	v_add_f32_e32 v6, v9, v6
	v_add_f32_e32 v6, v14, v6
	v_add_f32_e32 v6, v15, v6
	v_add_f32_e32 v6, v10, v6
	v_add_f32_e32 v6, v11, v6
	s_nop 1
	v_mov_b32_dpp v7, v6 quad_perm:[1,0,3,2] row_mask:0xf bank_mask:0xf
	v_xor_b32_e32 v8, 2, v52
	v_cmp_lt_i32_e32 vcc, v8, v53
	s_waitcnt lgkmcnt(0)
	v_add_f32_e32 v6, v6, v7
	v_cndmask_b32_e32 v8, v52, v8, vcc
	v_lshlrev_b32_e32 v8, 2, v8
	s_nop 1
	v_mov_b32_dpp v7, v6 quad_perm:[2,3,0,1] row_mask:0xf bank_mask:0xf
	v_xor_b32_e32 v8, 4, v52
	v_cmp_lt_i32_e32 vcc, v8, v53
	s_waitcnt lgkmcnt(0)
	v_add_f32_e32 v6, v6, v7
	v_cndmask_b32_e32 v8, v52, v8, vcc
	v_lshlrev_b32_e32 v8, 2, v8
	s_nop 1
	v_mov_b32_dpp v7, v6 row_half_mirror row_mask:0xf bank_mask:0xf
	v_xor_b32_e32 v8, 8, v52
	v_cmp_lt_i32_e32 vcc, v8, v53
	s_waitcnt lgkmcnt(0)
	v_add_f32_e32 v6, v6, v7
	v_cndmask_b32_e32 v8, v52, v8, vcc
	v_lshlrev_b32_e32 v8, 2, v8
	s_nop 1
	v_mov_b32_dpp v7, v6 row_mirror row_mask:0xf bank_mask:0xf
	s_cselect_b64 vcc, -1, 0
	s_cmp_lt_u32 s8, 64
	s_waitcnt lgkmcnt(0)
	v_add_f32_e32 v6, v6, v7
	v_add_f32_e32 v6, 0x358637bd, v6
	v_rsq_f32_e32 v6, v6
	s_nop 0
	v_cndmask_b32_e32 v6, 1.0, v6, vcc
	v_mul_f32_e32 v7, 0x3db504f3, v6
	s_cselect_b64 vcc, -1, 0
	v_cndmask_b32_e32 v10, v6, v7, vcc
	v_pk_mul_f32 v[8:9], v[2:3], v[10:11] op_sel_hi:[1,0]
	v_pk_mul_f32 v[6:7], v[16:17], v[10:11] op_sel_hi:[1,0]
	v_pk_mul_f32 v[4:5], v[4:5], v[10:11] op_sel_hi:[1,0]
	v_pk_mul_f32 v[2:3], v[12:13], v[10:11] op_sel_hi:[1,0]
	v_and_b32_e32 v10, 63, v18
	s_add_i32 s0, s0, 0
	v_mul_u32_u24_e32 v11, 0x110, v10
	s_cmp_gt_u32 s8, 63
	v_cvt_pk_bf16_f32 v12, v8, v9
	v_cvt_pk_bf16_f32 v13, v6, v7
	v_cvt_pk_bf16_f32 v14, v4, v5
	v_cvt_pk_bf16_f32 v15, v2, v3
	v_add3_u32 v11, s0, v11, v100
	ds_write_b128 v11, v[12:15] offset:28672
	s_cbranch_scc1 .LBB0_941
	v_add_u32_e32 v11, s33, v103
	v_lshl_add_u32 v11, v11, 2, 0
	ds_read_b32 v12, v11 offset:1152
	s_waitcnt lgkmcnt(0)
	v_pk_mul_f32 v[6:7], v[6:7], v[12:13] op_sel_hi:[1,0]
	v_pk_mul_f32 v[2:3], v[2:3], v[12:13] op_sel_hi:[1,0]
	v_pk_mul_f32 v[8:9], v[8:9], v[12:13] op_sel_hi:[1,0]
	v_pk_mul_f32 v[14:15], v[4:5], v[12:13] op_sel_hi:[1,0]
	v_cvt_pk_bf16_f32 v5, v6, v7
	v_cvt_pk_bf16_f32 v7, v2, v3
	v_mul_u32_u24_e32 v2, 0x108, v10
	v_mov_b32_e32 v3, 0
	v_cvt_pk_bf16_f32 v4, v8, v9
	v_cvt_pk_bf16_f32 v6, v14, v15
	v_lshl_add_u64 v[2:3], v[98:99], 0, v[2:3]
	global_store_dwordx4 v[2:3], v[4:7], off

; #define GAS __attribute__((address_space(1)))
; #define LAS __attribute__((address_space(3)))
; __device__ __forceinline__ float siluf_(float x) { return x * __builtin_amdgcn_rcpf(1.0f + __builtin_amdgcn_exp2f(-1.4426950408889634f * x)); }
; template <int NW>
; __device__ __forceinline__ void gp_stage0_compute(Frame& F, int cidx, const LAS float* Gs, LAS unsigned char* tiles, int w, int lane, const GpTaps<NW>& tp) {
;     ...
;             float acc[8];
; #pragma unroll
;             for (int e = 0; e < 8; ++e) acc[e] = 0.f;
; #pragma unroll
;             for (int tap = 0; tap < 4; ++tap) {
;                 const v4u xv = tp.xw[it][tap];
;                 const LAS float* cw = cwl + (type * 4 + tap) * 128 + c * 8;
;                 const f32x4 c0 = *(const LAS f32x4*)cw, c1 = *(const LAS f32x4*)(cw + 4);
;                 acc[0] += bflo(xv.x) * c0.x; acc[1] += bfhi(xv.x) * c0.y; acc[2] += bflo(xv.y) * c0.z; acc[3] += bfhi(xv.y) * c0.w;
;                 acc[4] += bflo(xv.z) * c1.x; acc[5] += bfhi(xv.z) * c1.y; acc[6] += bflo(xv.w) * c1.z; acc[7] += bfhi(xv.w) * c1.w;
;             }
;             float ss = 0.f;
; #pragma unroll
;             for (int e = 0; e < 8; ++e) { acc[e] = siluf_(acc[e]); ss += acc[e] * acc[e]; }
;             ss = sum16(ss);
;             float sc = 1.0f;
;             if (type < 2) sc = __builtin_amdgcn_rsqf(ss + EPS);
;             if (type == 0) sc *= 0.08838834764831845f;
; #pragma unroll
;             for (int e = 0; e < 8; ++e) acc[e] *= sc;
;             const v4u o = {gcvtpk(acc[0], acc[1]), gcvtpk(acc[2], acc[3]), gcvtpk(acc[4], acc[5]), gcvtpk(acc[6], acc[7])};
;             *(LAS v4u*)(tiles + type * GP_TILE + i * GP_TS + c * 16) = o;
;             if (type == 0) {
;                 const float e_ = Gs[128 + i];
;                 v2u w0 = {gcvtpk(acc[0] * e_, acc[1] * e_), gcvtpk(acc[2] * e_, acc[3] * e_)}, w1 = {gcvtpk(acc[4] * e_, acc[5] * e_), gcvtpk(acc[6] * e_, acc[7] * e_)};
;                 *(GAS v2u*)(CH + CH_Q + i * RS_W + c * 16) = w0; *(GAS v2u*)(CH + CH_Q + i * RS_W + c * 16 + 8) = w1;
;             }
; __device__ __forceinline__ void gdn_chunk_prep(Frame& F) {
;     ...
;             GP_BAR();
;             if (has_next) gp_stage0_compute<7>(F, ncidx, (const LAS float*)(F.lds + GP_TAB + (cur ^ 1) * 1024), F.lds + GP_TILES + (cur ^ 1) * GP_SET, wave - 1, lane, tp);
.LBB0_1060:
	s_waitcnt lgkmcnt(0)
	s_barrier
	s_and_b64 vcc, exec, s[72:73]
	s_cbranch_vccnz .LBB0_1083
	s_xor_b32 s11, s2, 1
	s_lshl_b32 s2, s11, 10
	s_add_i32 s2, s2, 0
	s_mul_i32 s11, s11, 0xc800
	s_add_i32 s11, s2, s11
	s_mul_i32 s18, s10, 0xf000
	v_and_b32_e32 v114, 15, v129
	s_mul_hi_i32 s19, s10, 0xf000
	s_add_u32 s18, s82, s18
	v_readlane_b32 s22, v252, 50
	s_addc_u32 s19, s83, s19
	s_nop 0
	v_lshl_add_u32 v129, v114, 5, s22
	v_lshlrev_b32_e32 v114, 4, v114
	v_lshl_add_u64 v[116:117], s[18:19], 0, v[114:115]
	s_mov_b64 s[18:19], 0x37404200
	v_lshl_add_u64 v[116:117], v[116:117], 0, s[18:19]
	s_movk_i32 s18, 0xc0
	v_cmp_gt_i32_e32 vcc, s18, v130
	s_and_saveexec_b64 s[72:73], vcc
	s_cbranch_execz .LBB0_1064
	v_readlane_b32 s18, v252, 61
	s_waitcnt vmcnt(27)
	v_cndmask_b32_e64 v131, v106, 0, s[66:67]
	v_cndmask_b32_e64 v154, v107, 0, s[66:67]
	v_add_u32_e32 v148, s18, v129
	v_cndmask_b32_e64 v155, v108, 0, s[66:67]
	v_cndmask_b32_e64 v153, v109, 0, s[66:67]
	s_waitcnt vmcnt(26)
	v_cndmask_b32_e64 v156, v102, 0, s[68:69]
	v_cndmask_b32_e64 v157, v103, 0, s[68:69]
	v_cndmask_b32_e64 v158, v104, 0, s[68:69]
	v_cndmask_b32_e64 v159, v105, 0, s[68:69]
	s_waitcnt vmcnt(25)
	v_cndmask_b32_e64 v160, v110, 0, s[70:71]
	v_cndmask_b32_e64 v161, v111, 0, s[70:71]
	v_cndmask_b32_e64 v162, v112, 0, s[70:71]
	v_cndmask_b32_e64 v163, v113, 0, s[70:71]
	ds_read_b128 v[102:105], v148
	ds_read_b128 v[106:109], v148 offset:16
	ds_read_b128 v[110:113], v148 offset:512
	ds_read_b128 v[132:135], v148 offset:528
	ds_read_b128 v[136:139], v148 offset:1024
	ds_read_b128 v[140:143], v148 offset:1040
	ds_read_b128 v[144:147], v148 offset:1536
	ds_read_b128 v[148:151], v148 offset:1552
	v_and_b32_e32 v152, 64, v122
	v_add_u32_e32 v164, 64, v152
	v_lshlrev_b32_e32 v152, 16, v153
	v_and_b32_e32 v153, 0xffff0000, v153
	s_waitcnt lgkmcnt(6)
	v_pk_fma_f32 v[108:109], v[108:109], v[152:153], 0 op_sel_hi:[1,1,0]
	v_lshlrev_b32_e32 v152, 16, v159
	v_and_b32_e32 v153, 0xffff0000, v159
	s_waitcnt lgkmcnt(4)
	v_pk_fma_f32 v[108:109], v[134:135], v[152:153], v[108:109]
	v_lshlrev_b32_e32 v134, 16, v163
	v_and_b32_e32 v135, 0xffff0000, v163
	s_waitcnt lgkmcnt(2)
	v_pk_fma_f32 v[108:109], v[142:143], v[134:135], v[108:109]
	s_waitcnt vmcnt(24)
	v_lshlrev_b32_e32 v134, 16, v101
	v_and_b32_e32 v135, 0xffff0000, v101
	s_waitcnt lgkmcnt(0)
	v_pk_fma_f32 v[108:109], v[150:151], v[134:135], v[108:109]
	v_xor_b32_e32 v142, 1, v122
	v_mul_f32_e32 v101, 0xbfb8aa3b, v108
	v_exp_f32_e32 v101, v101
	v_mul_f32_e32 v134, 0xbfb8aa3b, v109
	v_exp_f32_e32 v135, v134
	v_cmp_lt_i32_e32 vcc, v142, v164
	v_add_f32_e32 v101, 1.0, v101
	v_rcp_f32_e32 v134, v101
	v_add_f32_e32 v101, 1.0, v135
	v_rcp_f32_e32 v135, v101
	v_cndmask_b32_e32 v101, v122, v142, vcc
	v_lshlrev_b32_e32 v142, 2, v101
	v_readlane_b32 s18, v252, 62
	v_pk_mul_f32 v[108:109], v[108:109], v[134:135]
	v_lshlrev_b32_e32 v134, 16, v155
	v_and_b32_e32 v135, 0xffff0000, v155
	v_pk_fma_f32 v[106:107], v[106:107], v[134:135], 0 op_sel_hi:[1,1,0]
	v_lshlrev_b32_e32 v134, 16, v158
	v_and_b32_e32 v135, 0xffff0000, v158
	v_pk_fma_f32 v[106:107], v[132:133], v[134:135], v[106:107]
	v_lshlrev_b32_e32 v132, 16, v162
	v_and_b32_e32 v133, 0xffff0000, v162
	v_pk_fma_f32 v[106:107], v[140:141], v[132:133], v[106:107]
	v_lshlrev_b32_e32 v132, 16, v100
	v_and_b32_e32 v133, 0xffff0000, v100
	v_pk_fma_f32 v[100:101], v[148:149], v[132:133], v[106:107]
	v_lshlrev_b32_e32 v134, 16, v154
	v_mul_f32_e32 v106, 0xbfb8aa3b, v100
	v_exp_f32_e32 v132, v106
	v_mul_f32_e32 v106, 0xbfb8aa3b, v101
	v_exp_f32_e32 v133, v106
	v_and_b32_e32 v135, 0xffff0000, v154
	v_pk_fma_f32 v[104:105], v[104:105], v[134:135], 0 op_sel_hi:[1,1,0]
	v_lshlrev_b32_e32 v134, 16, v157
	v_and_b32_e32 v135, 0xffff0000, v157
	v_add_f32_e32 v132, 1.0, v132
	v_add_f32_e32 v133, 1.0, v133
	v_pk_fma_f32 v[104:105], v[112:113], v[134:135], v[104:105]
	v_lshlrev_b32_e32 v112, 16, v161
	v_and_b32_e32 v113, 0xffff0000, v161
	v_rcp_f32_e32 v132, v132
	v_rcp_f32_e32 v133, v133
	v_pk_fma_f32 v[104:105], v[138:139], v[112:113], v[104:105]
	v_lshlrev_b32_e32 v112, 16, v99
	v_and_b32_e32 v113, 0xffff0000, v99
	v_pk_fma_f32 v[104:105], v[146:147], v[112:113], v[104:105]
	v_pk_mul_f32 v[100:101], v[100:101], v[132:133]
	v_mul_f32_e32 v99, 0xbfb8aa3b, v104
	v_exp_f32_e32 v99, v99
	v_lshlrev_b32_e32 v132, 16, v131
	v_and_b32_e32 v133, 0xffff0000, v131
	v_pk_fma_f32 v[102:103], v[102:103], v[132:133], 0 op_sel_hi:[1,1,0]
	v_lshlrev_b32_e32 v132, 16, v156
	v_and_b32_e32 v133, 0xffff0000, v156
	v_pk_fma_f32 v[102:103], v[110:111], v[132:133], v[102:103]
	v_lshlrev_b32_e32 v110, 16, v160
	v_and_b32_e32 v111, 0xffff0000, v160
	v_mul_f32_e32 v112, 0xbfb8aa3b, v105
	v_add_f32_e32 v99, 1.0, v99
	v_pk_fma_f32 v[102:103], v[136:137], v[110:111], v[102:103]
	v_lshlrev_b32_e32 v110, 16, v98
	v_and_b32_e32 v111, 0xffff0000, v98
	v_exp_f32_e32 v113, v112
	v_rcp_f32_e32 v112, v99
	v_pk_fma_f32 v[98:99], v[144:145], v[110:111], v[102:103]
	v_pk_mul_f32 v[110:111], v[100:101], v[100:101]
	v_mul_f32_e32 v102, 0xbfb8aa3b, v98
	v_mul_f32_e32 v103, 0xbfb8aa3b, v99
	v_exp_f32_e32 v102, v102
	v_exp_f32_e32 v103, v103
	v_add_f32_e32 v113, 1.0, v113
	v_rcp_f32_e32 v113, v113
	v_add_f32_e32 v102, 1.0, v102
	v_add_f32_e32 v103, 1.0, v103
	v_rcp_f32_e32 v102, v102
	v_rcp_f32_e32 v103, v103
	v_pk_mul_f32 v[112:113], v[104:105], v[112:113]
	v_pk_mul_f32 v[106:107], v[108:109], v[108:109]
	v_pk_mul_f32 v[104:105], v[112:113], v[112:113]
	v_pk_mul_f32 v[98:99], v[98:99], v[102:103]
	v_readlane_b32 s19, v252, 63
	v_pk_mul_f32 v[102:103], v[98:99], v[98:99]
	v_readlane_b32 s22, v251, 0
	v_add_f32_e32 v102, v102, v103
	v_add_f32_e32 v102, v104, v102
	v_add_f32_e32 v102, v105, v102
	v_add_f32_e32 v102, v110, v102
	v_add_f32_e32 v102, v111, v102
	v_add_f32_e32 v102, v106, v102
	v_add_f32_e32 v102, v107, v102
	s_nop 1
	v_mov_b32_dpp v103, v102 quad_perm:[1,0,3,2] row_mask:0xf bank_mask:0xf
	v_xor_b32_e32 v104, 2, v122
	v_cmp_lt_i32_e32 vcc, v104, v164
	v_readlane_b32 s23, v251, 1
	s_waitcnt lgkmcnt(0)
; #define GAS __attribute__((address_space(1)))
; #define LAS __attribute__((address_space(3)))
; __device__ __forceinline__ float siluf_(float x) { return x * __builtin_amdgcn_rcpf(1.0f + __builtin_amdgcn_exp2f(-1.4426950408889634f * x)); }
; __device__ __forceinline__ float sum16(float v) {
; #pragma unroll
;     for (int o = 1; o < 16; o <<= 1) v += __shfl_xor(v, o);
;     return v;
; }
; template <int NW>
; __device__ __forceinline__ void gp_stage0_compute(Frame& F, int cidx, const LAS float* Gs, LAS unsigned char* tiles, int w, int lane, const GpTaps<NW>& tp) {
;     ...
;             float acc[8];
; #pragma unroll
;             for (int e = 0; e < 8; ++e) acc[e] = 0.f;
; #pragma unroll
;             for (int tap = 0; tap < 4; ++tap) {
;                 const v4u xv = tp.xw[it][tap];
;                 const LAS float* cw = cwl + (type * 4 + tap) * 128 + c * 8;
;                 const f32x4 c0 = *(const LAS f32x4*)cw, c1 = *(const LAS f32x4*)(cw + 4);
;                 acc[0] += bflo(xv.x) * c0.x; acc[1] += bfhi(xv.x) * c0.y; acc[2] += bflo(xv.y) * c0.z; acc[3] += bfhi(xv.y) * c0.w;
;                 acc[4] += bflo(xv.z) * c1.x; acc[5] += bfhi(xv.z) * c1.y; acc[6] += bflo(xv.w) * c1.z; acc[7] += bfhi(xv.w) * c1.w;
;             }
;             float ss = 0.f;
; #pragma unroll
;             for (int e = 0; e < 8; ++e) { acc[e] = siluf_(acc[e]); ss += acc[e] * acc[e]; }
;             ss = sum16(ss);
;             float sc = 1.0f;
;             if (type < 2) sc = __builtin_amdgcn_rsqf(ss + EPS);
;             if (type == 0) sc *= 0.08838834764831845f;
; #pragma unroll
;             for (int e = 0; e < 8; ++e) acc[e] *= sc;
;             const v4u o = {gcvtpk(acc[0], acc[1]), gcvtpk(acc[2], acc[3]), gcvtpk(acc[4], acc[5]), gcvtpk(acc[6], acc[7])};
;             *(LAS v4u*)(tiles + type * GP_TILE + i * GP_TS + c * 16) = o;
;             if (type == 0) {
;                 const float e_ = Gs[128 + i];
;                 v2u w0 = {gcvtpk(acc[0] * e_, acc[1] * e_), gcvtpk(acc[2] * e_, acc[3] * e_)}, w1 = {gcvtpk(acc[4] * e_, acc[5] * e_), gcvtpk(acc[6] * e_, acc[7] * e_)};
;                 *(GAS v2u*)(CH + CH_Q + i * RS_W + c * 16) = w0; *(GAS v2u*)(CH + CH_Q + i * RS_W + c * 16 + 8) = w1;
;             }
	v_add_f32_e32 v102, v102, v103
	v_cndmask_b32_e32 v104, v122, v104, vcc
	v_lshlrev_b32_e32 v104, 2, v104
	s_nop 1
	v_mov_b32_dpp v103, v102 quad_perm:[2,3,0,1] row_mask:0xf bank_mask:0xf
	v_xor_b32_e32 v104, 4, v122
	v_cmp_lt_i32_e32 vcc, v104, v164
	s_waitcnt lgkmcnt(0)
	v_add_f32_e32 v102, v102, v103
	v_cndmask_b32_e32 v104, v122, v104, vcc
	v_lshlrev_b32_e32 v104, 2, v104
	s_nop 1
	v_mov_b32_dpp v103, v102 row_half_mirror row_mask:0xf bank_mask:0xf
	v_xor_b32_e32 v104, 8, v122
	v_cmp_lt_i32_e32 vcc, v104, v164
	s_waitcnt lgkmcnt(0)
	v_add_f32_e32 v102, v102, v103
	v_cndmask_b32_e32 v104, v122, v104, vcc
	v_lshlrev_b32_e32 v104, 2, v104
	s_nop 1
	v_mov_b32_dpp v103, v102 row_mirror row_mask:0xf bank_mask:0xf
	s_andn2_b64 vcc, exec, s[22:23]
	s_waitcnt lgkmcnt(0)
	v_add_f32_e32 v102, v102, v103
	v_add_f32_e32 v102, 0x358637bd, v102
	v_rsq_f32_e32 v102, v102
	s_nop 0
	v_cndmask_b32_e64 v102, 1.0, v102, s[18:19]
	v_mul_f32_e32 v103, 0x3db504f3, v102
	v_cndmask_b32_e64 v106, v102, v103, s[22:23]
	v_pk_mul_f32 v[104:105], v[98:99], v[106:107] op_sel_hi:[1,0]
	v_pk_mul_f32 v[102:103], v[112:113], v[106:107] op_sel_hi:[1,0]
	v_pk_mul_f32 v[100:101], v[100:101], v[106:107] op_sel_hi:[1,0]
	v_pk_mul_f32 v[98:99], v[108:109], v[106:107] op_sel_hi:[1,0]
	v_and_b32_e32 v106, 63, v130
	v_readlane_b32 s18, v250, 6
	s_add_i32 s18, s11, s18
	v_mul_u32_u24_e32 v107, 0x110, v106
	v_cvt_pk_bf16_f32 v108, v104, v105
	v_cvt_pk_bf16_f32 v109, v102, v103
	v_cvt_pk_bf16_f32 v110, v100, v101
	v_cvt_pk_bf16_f32 v111, v98, v99
	v_add3_u32 v107, s18, v107, v114
	ds_write_b128 v107, v[108:111] offset:28672
	s_cbranch_vccnz .LBB0_1064
	v_lshl_add_u32 v107, v130, 2, s2
	ds_read_b32 v108, v107 offset:512
	s_waitcnt lgkmcnt(0)
	v_pk_mul_f32 v[102:103], v[102:103], v[108:109] op_sel_hi:[1,0]
	v_pk_mul_f32 v[98:99], v[98:99], v[108:109] op_sel_hi:[1,0]
	v_pk_mul_f32 v[104:105], v[104:105], v[108:109] op_sel_hi:[1,0]
	v_pk_mul_f32 v[110:111], v[100:101], v[108:109] op_sel_hi:[1,0]
	v_cvt_pk_bf16_f32 v101, v102, v103
	v_cvt_pk_bf16_f32 v103, v98, v99
	v_mul_u32_u24_e32 v98, 0x108, v106
	v_mov_b32_e32 v99, v115
	v_cvt_pk_bf16_f32 v100, v104, v105
	v_cvt_pk_bf16_f32 v102, v110, v111
	v_lshl_add_u64 v[98:99], v[116:117], 0, v[98:99]
	global_store_dwordx4 v[98:99], v[100:103], off
.LBB0_1064:
	s_or_b64 exec, exec, s[72:73]
	v_readlane_b32 s18, v251, 5
	s_movk_i32 s26, 0xc0
	s_waitcnt vmcnt(24)
	v_or_b32_e32 v98, s18, v128
	v_cmp_gt_i32_e32 vcc, s26, v98
	s_and_saveexec_b64 s[66:67], vcc
	s_cbranch_execz .LBB0_1067
	v_readlane_b32 s18, v251, 2
	s_waitcnt vmcnt(23)
	v_cndmask_b32_e64 v99, v90, 0, s[60:61]
	v_cndmask_b32_e64 v138, v91, 0, s[60:61]
	v_add_u32_e32 v112, s18, v129
	v_cndmask_b32_e64 v139, v92, 0, s[60:61]
	v_cndmask_b32_e64 v113, v93, 0, s[60:61]
	s_waitcnt vmcnt(22)
	v_cndmask_b32_e64 v140, v86, 0, s[62:63]
	v_cndmask_b32_e64 v141, v87, 0, s[62:63]
	v_cndmask_b32_e64 v142, v88, 0, s[62:63]
	v_cndmask_b32_e64 v143, v89, 0, s[62:63]
	s_waitcnt vmcnt(21)
	v_cndmask_b32_e64 v144, v94, 0, s[64:65]
	v_cndmask_b32_e64 v145, v95, 0, s[64:65]
	v_cndmask_b32_e64 v146, v96, 0, s[64:65]
	v_cndmask_b32_e64 v147, v97, 0, s[64:65]
	ds_read_b128 v[86:89], v112
	ds_read_b128 v[90:93], v112 offset:16
	ds_read_b128 v[94:97], v112 offset:512
	ds_read_b128 v[100:103], v112 offset:528
	ds_read_b128 v[104:107], v112 offset:1024
	ds_read_b128 v[108:111], v112 offset:1040
	ds_read_b128 v[130:133], v112 offset:1536
	ds_read_b128 v[134:137], v112 offset:1552
	v_and_b32_e32 v112, 64, v122
	v_add_u32_e32 v148, 64, v112
	v_lshlrev_b32_e32 v112, 16, v113
	v_and_b32_e32 v113, 0xffff0000, v113
	s_waitcnt lgkmcnt(6)
	v_pk_fma_f32 v[92:93], v[92:93], v[112:113], 0 op_sel_hi:[1,1,0]
	v_lshlrev_b32_e32 v112, 16, v143
	v_and_b32_e32 v113, 0xffff0000, v143
	s_waitcnt lgkmcnt(4)
	v_pk_fma_f32 v[92:93], v[102:103], v[112:113], v[92:93]
	v_lshlrev_b32_e32 v102, 16, v147
	v_and_b32_e32 v103, 0xffff0000, v147
	s_waitcnt lgkmcnt(2)
	v_pk_fma_f32 v[92:93], v[110:111], v[102:103], v[92:93]
	s_waitcnt vmcnt(20)
	v_lshlrev_b32_e32 v102, 16, v85
	v_and_b32_e32 v103, 0xffff0000, v85
	s_waitcnt lgkmcnt(0)
	v_pk_fma_f32 v[92:93], v[136:137], v[102:103], v[92:93]
	v_xor_b32_e32 v110, 1, v122
	v_mul_f32_e32 v85, 0xbfb8aa3b, v92
	v_exp_f32_e32 v85, v85
	v_mul_f32_e32 v102, 0xbfb8aa3b, v93
	v_exp_f32_e32 v103, v102
	v_cmp_lt_i32_e32 vcc, v110, v148
	v_add_f32_e32 v85, 1.0, v85
	v_rcp_f32_e32 v102, v85
	v_add_f32_e32 v85, 1.0, v103
	v_rcp_f32_e32 v103, v85
	v_cndmask_b32_e32 v85, v122, v110, vcc
	v_lshlrev_b32_e32 v110, 2, v85
	v_readlane_b32 s18, v251, 3
	v_pk_mul_f32 v[92:93], v[92:93], v[102:103]
	v_lshlrev_b32_e32 v102, 16, v139
	v_and_b32_e32 v103, 0xffff0000, v139
	v_pk_fma_f32 v[90:91], v[90:91], v[102:103], 0 op_sel_hi:[1,1,0]
	v_lshlrev_b32_e32 v102, 16, v142
	v_and_b32_e32 v103, 0xffff0000, v142
	v_pk_fma_f32 v[90:91], v[100:101], v[102:103], v[90:91]
	v_lshlrev_b32_e32 v100, 16, v146
	v_and_b32_e32 v101, 0xffff0000, v146
	v_pk_fma_f32 v[90:91], v[108:109], v[100:101], v[90:91]
	v_lshlrev_b32_e32 v100, 16, v84
	v_and_b32_e32 v101, 0xffff0000, v84
	v_pk_fma_f32 v[84:85], v[134:135], v[100:101], v[90:91]
	v_lshlrev_b32_e32 v102, 16, v138
	v_mul_f32_e32 v90, 0xbfb8aa3b, v84
	v_exp_f32_e32 v100, v90
	v_mul_f32_e32 v90, 0xbfb8aa3b, v85
	v_exp_f32_e32 v101, v90
	v_and_b32_e32 v103, 0xffff0000, v138
	v_pk_fma_f32 v[88:89], v[88:89], v[102:103], 0 op_sel_hi:[1,1,0]
	v_lshlrev_b32_e32 v102, 16, v141
	v_and_b32_e32 v103, 0xffff0000, v141
	v_add_f32_e32 v100, 1.0, v100
	v_add_f32_e32 v101, 1.0, v101
	v_pk_fma_f32 v[88:89], v[96:97], v[102:103], v[88:89]
	v_lshlrev_b32_e32 v96, 16, v145
	v_and_b32_e32 v97, 0xffff0000, v145
; #define GAS __attribute__((address_space(1)))
; #define LAS __attribute__((address_space(3)))
; __device__ __forceinline__ float siluf_(float x) { return x * __builtin_amdgcn_rcpf(1.0f + __builtin_amdgcn_exp2f(-1.4426950408889634f * x)); }
; __device__ __forceinline__ unsigned gcvtpk(float lo, float hi) { gf32x2 v = {lo, hi}; gbf16x2 b = __builtin_convertvector(v, gbf16x2); return __builtin_bit_cast(unsigned, b); }
; __device__ __forceinline__ float sum16(float v) {
; #pragma unroll
;     for (int o = 1; o < 16; o <<= 1) v += __shfl_xor(v, o);
;     return v;
; }
; template <int NW>
; __device__ __forceinline__ void gp_stage0_compute(Frame& F, int cidx, const LAS float* Gs, LAS unsigned char* tiles, int w, int lane, const GpTaps<NW>& tp) {
;     ...
; #pragma unroll
;             for (int tap = 0; tap < 4; ++tap) {
;                 const v4u xv = tp.xw[it][tap];
;                 const LAS float* cw = cwl + (type * 4 + tap) * 128 + c * 8;
;                 const f32x4 c0 = *(const LAS f32x4*)cw, c1 = *(const LAS f32x4*)(cw + 4);
;                 acc[0] += bflo(xv.x) * c0.x; acc[1] += bfhi(xv.x) * c0.y; acc[2] += bflo(xv.y) * c0.z; acc[3] += bfhi(xv.y) * c0.w;
;                 acc[4] += bflo(xv.z) * c1.x; acc[5] += bfhi(xv.z) * c1.y; acc[6] += bflo(xv.w) * c1.z; acc[7] += bfhi(xv.w) * c1.w;
;             }
;             float ss = 0.f;
; #pragma unroll
;             for (int e = 0; e < 8; ++e) { acc[e] = siluf_(acc[e]); ss += acc[e] * acc[e]; }
;             ss = sum16(ss);
;             float sc = 1.0f;
;             if (type < 2) sc = __builtin_amdgcn_rsqf(ss + EPS);
;             if (type == 0) sc *= 0.08838834764831845f;
; #pragma unroll
;             for (int e = 0; e < 8; ++e) acc[e] *= sc;
;             const v4u o = {gcvtpk(acc[0], acc[1]), gcvtpk(acc[2], acc[3]), gcvtpk(acc[4], acc[5]), gcvtpk(acc[6], acc[7])};
;             *(LAS v4u*)(tiles + type * GP_TILE + i * GP_TS + c * 16) = o;
;             if (type == 0) {
;                 const float e_ = Gs[128 + i];
;                 v2u w0 = {gcvtpk(acc[0] * e_, acc[1] * e_), gcvtpk(acc[2] * e_, acc[3] * e_)}, w1 = {gcvtpk(acc[4] * e_, acc[5] * e_), gcvtpk(acc[6] * e_, acc[7] * e_)};
;                 *(GAS v2u*)(CH + CH_Q + i * RS_W + c * 16) = w0; *(GAS v2u*)(CH + CH_Q + i * RS_W + c * 16 + 8) = w1;
;             }
	v_rcp_f32_e32 v100, v100
	v_rcp_f32_e32 v101, v101
	v_pk_fma_f32 v[88:89], v[106:107], v[96:97], v[88:89]
	v_lshlrev_b32_e32 v96, 16, v83
	v_and_b32_e32 v97, 0xffff0000, v83
	v_pk_fma_f32 v[88:89], v[132:133], v[96:97], v[88:89]
	v_pk_mul_f32 v[84:85], v[84:85], v[100:101]
	v_mul_f32_e32 v83, 0xbfb8aa3b, v88
	v_exp_f32_e32 v83, v83
	v_lshlrev_b32_e32 v100, 16, v99
	v_and_b32_e32 v101, 0xffff0000, v99
	v_pk_fma_f32 v[86:87], v[86:87], v[100:101], 0 op_sel_hi:[1,1,0]
	v_lshlrev_b32_e32 v100, 16, v140
	v_and_b32_e32 v101, 0xffff0000, v140
	v_pk_fma_f32 v[86:87], v[94:95], v[100:101], v[86:87]
	v_lshlrev_b32_e32 v94, 16, v144
	v_and_b32_e32 v95, 0xffff0000, v144
	v_mul_f32_e32 v96, 0xbfb8aa3b, v89
	v_add_f32_e32 v83, 1.0, v83
	v_pk_fma_f32 v[86:87], v[104:105], v[94:95], v[86:87]
	v_lshlrev_b32_e32 v94, 16, v82
	v_and_b32_e32 v95, 0xffff0000, v82
	v_exp_f32_e32 v97, v96
	v_rcp_f32_e32 v96, v83
	v_pk_fma_f32 v[82:83], v[130:131], v[94:95], v[86:87]
	v_pk_mul_f32 v[94:95], v[84:85], v[84:85]
	v_mul_f32_e32 v86, 0xbfb8aa3b, v82
	v_mul_f32_e32 v87, 0xbfb8aa3b, v83
	v_exp_f32_e32 v86, v86
	v_exp_f32_e32 v87, v87
	v_add_f32_e32 v97, 1.0, v97
	v_rcp_f32_e32 v97, v97
	v_add_f32_e32 v86, 1.0, v86
	v_add_f32_e32 v87, 1.0, v87
	v_rcp_f32_e32 v86, v86
	v_rcp_f32_e32 v87, v87
	v_pk_mul_f32 v[96:97], v[88:89], v[96:97]
	v_pk_mul_f32 v[90:91], v[92:93], v[92:93]
	v_pk_mul_f32 v[88:89], v[96:97], v[96:97]
	v_pk_mul_f32 v[82:83], v[82:83], v[86:87]
	v_readlane_b32 s19, v251, 4
	v_pk_mul_f32 v[86:87], v[82:83], v[82:83]
	v_readlane_b32 s22, v251, 6
	v_add_f32_e32 v86, v86, v87
	v_add_f32_e32 v86, v88, v86
	v_add_f32_e32 v86, v89, v86
	v_add_f32_e32 v86, v94, v86
	v_add_f32_e32 v86, v95, v86
	v_add_f32_e32 v86, v90, v86
	v_add_f32_e32 v86, v91, v86
	s_nop 1
	v_mov_b32_dpp v87, v86 quad_perm:[1,0,3,2] row_mask:0xf bank_mask:0xf
	v_xor_b32_e32 v88, 2, v122
	v_cmp_lt_i32_e32 vcc, v88, v148
	v_readlane_b32 s23, v251, 7
	s_waitcnt lgkmcnt(0)
	v_add_f32_e32 v86, v86, v87
	v_cndmask_b32_e32 v88, v122, v88, vcc
	v_lshlrev_b32_e32 v88, 2, v88
	s_nop 1
	v_mov_b32_dpp v87, v86 quad_perm:[2,3,0,1] row_mask:0xf bank_mask:0xf
	v_xor_b32_e32 v88, 4, v122
	v_cmp_lt_i32_e32 vcc, v88, v148
	s_waitcnt lgkmcnt(0)
	v_add_f32_e32 v86, v86, v87
	v_cndmask_b32_e32 v88, v122, v88, vcc
	v_lshlrev_b32_e32 v88, 2, v88
	s_nop 1
	v_mov_b32_dpp v87, v86 row_half_mirror row_mask:0xf bank_mask:0xf
	v_xor_b32_e32 v88, 8, v122
	v_cmp_lt_i32_e32 vcc, v88, v148
	s_waitcnt lgkmcnt(0)
	v_add_f32_e32 v86, v86, v87
	v_cndmask_b32_e32 v88, v122, v88, vcc
	v_lshlrev_b32_e32 v88, 2, v88
	s_nop 1
	v_mov_b32_dpp v87, v86 row_mirror row_mask:0xf bank_mask:0xf
	s_andn2_b64 vcc, exec, s[22:23]
	s_waitcnt lgkmcnt(0)
	v_add_f32_e32 v86, v86, v87
	v_add_f32_e32 v86, 0x358637bd, v86
	v_rsq_f32_e32 v86, v86
	s_nop 0
	v_cndmask_b32_e64 v86, 1.0, v86, s[18:19]
	v_mul_f32_e32 v87, 0x3db504f3, v86
	v_cndmask_b32_e64 v90, v86, v87, s[22:23]
	v_pk_mul_f32 v[88:89], v[82:83], v[90:91] op_sel_hi:[1,0]
	v_pk_mul_f32 v[86:87], v[96:97], v[90:91] op_sel_hi:[1,0]
	v_pk_mul_f32 v[84:85], v[84:85], v[90:91] op_sel_hi:[1,0]
	v_pk_mul_f32 v[82:83], v[92:93], v[90:91] op_sel_hi:[1,0]
	v_and_b32_e32 v90, 63, v98
	v_readlane_b32 s18, v250, 7
	s_add_i32 s18, s11, s18
	v_mul_u32_u24_e32 v91, 0x110, v90
	v_cvt_pk_bf16_f32 v92, v88, v89
	v_cvt_pk_bf16_f32 v93, v86, v87
	v_cvt_pk_bf16_f32 v94, v84, v85
	v_cvt_pk_bf16_f32 v95, v82, v83
	v_add3_u32 v91, s18, v91, v114
	ds_write_b128 v91, v[92:95] offset:28672
	s_cbranch_vccnz .LBB0_1067
	v_add_u32_e32 v91, s91, v128
	v_lshl_add_u32 v91, v91, 2, s2
	ds_read_b32 v92, v91 offset:624
	s_waitcnt lgkmcnt(0)
	v_pk_mul_f32 v[86:87], v[86:87], v[92:93] op_sel_hi:[1,0]
	v_pk_mul_f32 v[82:83], v[82:83], v[92:93] op_sel_hi:[1,0]
	v_pk_mul_f32 v[88:89], v[88:89], v[92:93] op_sel_hi:[1,0]
	v_pk_mul_f32 v[94:95], v[84:85], v[92:93] op_sel_hi:[1,0]
	v_cvt_pk_bf16_f32 v85, v86, v87
	v_cvt_pk_bf16_f32 v87, v82, v83
	v_mul_u32_u24_e32 v82, 0x108, v90
	v_mov_b32_e32 v83, v115
	v_cvt_pk_bf16_f32 v84, v88, v89
	v_cvt_pk_bf16_f32 v86, v94, v95
	v_lshl_add_u64 v[82:83], v[116:117], 0, v[82:83]
	global_store_dwordx4 v[82:83], v[84:87], off
.LBB0_1067:
	s_or_b64 exec, exec, s[66:67]
	v_readlane_b32 s18, v251, 11
	s_waitcnt vmcnt(20)
	s_nop 0
	v_or_b32_e32 v82, s18, v128
	v_cmp_gt_i32_e32 vcc, s26, v82
	s_and_saveexec_b64 s[60:61], vcc
	s_cbranch_execz .LBB0_1070
; #define GAS __attribute__((address_space(1)))
; #define LAS __attribute__((address_space(3)))
; __device__ __forceinline__ float siluf_(float x) { return x * __builtin_amdgcn_rcpf(1.0f + __builtin_amdgcn_exp2f(-1.4426950408889634f * x)); }
; __device__ __forceinline__ float sum16(float v) {
; #pragma unroll
;     for (int o = 1; o < 16; o <<= 1) v += __shfl_xor(v, o);
;     return v;
; }
; template <int NW>
; __device__ __forceinline__ void gp_stage0_compute(Frame& F, int cidx, const LAS float* Gs, LAS unsigned char* tiles, int w, int lane, const GpTaps<NW>& tp) {
;     ...
;             float acc[8];
; #pragma unroll
;             for (int e = 0; e < 8; ++e) acc[e] = 0.f;
; #pragma unroll
;             for (int tap = 0; tap < 4; ++tap) {
;                 const v4u xv = tp.xw[it][tap];
;                 const LAS float* cw = cwl + (type * 4 + tap) * 128 + c * 8;
;                 const f32x4 c0 = *(const LAS f32x4*)cw, c1 = *(const LAS f32x4*)(cw + 4);
;                 acc[0] += bflo(xv.x) * c0.x; acc[1] += bfhi(xv.x) * c0.y; acc[2] += bflo(xv.y) * c0.z; acc[3] += bfhi(xv.y) * c0.w;
;                 acc[4] += bflo(xv.z) * c1.x; acc[5] += bfhi(xv.z) * c1.y; acc[6] += bflo(xv.w) * c1.z; acc[7] += bfhi(xv.w) * c1.w;
;             }
;             float ss = 0.f;
; #pragma unroll
;             for (int e = 0; e < 8; ++e) { acc[e] = siluf_(acc[e]); ss += acc[e] * acc[e]; }
;             ss = sum16(ss);
;             float sc = 1.0f;
;             if (type < 2) sc = __builtin_amdgcn_rsqf(ss + EPS);
;             if (type == 0) sc *= 0.08838834764831845f;
; #pragma unroll
;             for (int e = 0; e < 8; ++e) acc[e] *= sc;
;             const v4u o = {gcvtpk(acc[0], acc[1]), gcvtpk(acc[2], acc[3]), gcvtpk(acc[4], acc[5]), gcvtpk(acc[6], acc[7])};
;             *(LAS v4u*)(tiles + type * GP_TILE + i * GP_TS + c * 16) = o;
;             if (type == 0) {
;                 const float e_ = Gs[128 + i];
;                 v2u w0 = {gcvtpk(acc[0] * e_, acc[1] * e_), gcvtpk(acc[2] * e_, acc[3] * e_)}, w1 = {gcvtpk(acc[4] * e_, acc[5] * e_), gcvtpk(acc[6] * e_, acc[7] * e_)};
;                 *(GAS v2u*)(CH + CH_Q + i * RS_W + c * 16) = w0; *(GAS v2u*)(CH + CH_Q + i * RS_W + c * 16 + 8) = w1;
;             }
	v_readlane_b32 s18, v251, 8
	s_waitcnt vmcnt(19)
	v_cndmask_b32_e64 v83, v74, 0, s[54:55]
	v_cndmask_b32_e64 v106, v75, 0, s[54:55]
	v_add_u32_e32 v100, s18, v129
	v_cndmask_b32_e64 v107, v76, 0, s[54:55]
	v_cndmask_b32_e64 v105, v77, 0, s[54:55]
	s_waitcnt vmcnt(18)
	v_cndmask_b32_e64 v108, v70, 0, s[56:57]
	v_cndmask_b32_e64 v109, v71, 0, s[56:57]
	v_cndmask_b32_e64 v110, v72, 0, s[56:57]
	v_cndmask_b32_e64 v111, v73, 0, s[56:57]
	s_waitcnt vmcnt(17)
	v_cndmask_b32_e64 v112, v78, 0, s[58:59]
	v_cndmask_b32_e64 v113, v79, 0, s[58:59]
	v_cndmask_b32_e64 v130, v80, 0, s[58:59]
	v_cndmask_b32_e64 v131, v81, 0, s[58:59]
	ds_read_b128 v[70:73], v100
	ds_read_b128 v[74:77], v100 offset:16
	ds_read_b128 v[78:81], v100 offset:512
	ds_read_b128 v[84:87], v100 offset:528
	ds_read_b128 v[88:91], v100 offset:1024
	ds_read_b128 v[92:95], v100 offset:1040
	ds_read_b128 v[96:99], v100 offset:1536
	ds_read_b128 v[100:103], v100 offset:1552
	v_and_b32_e32 v104, 64, v122
	v_add_u32_e32 v132, 64, v104
	v_lshlrev_b32_e32 v104, 16, v105
	v_and_b32_e32 v105, 0xffff0000, v105
	s_waitcnt lgkmcnt(6)
	v_pk_fma_f32 v[76:77], v[76:77], v[104:105], 0 op_sel_hi:[1,1,0]
	v_lshlrev_b32_e32 v104, 16, v111
	v_and_b32_e32 v105, 0xffff0000, v111
	s_waitcnt lgkmcnt(4)
	v_pk_fma_f32 v[76:77], v[86:87], v[104:105], v[76:77]
	v_lshlrev_b32_e32 v86, 16, v131
	v_and_b32_e32 v87, 0xffff0000, v131
	s_waitcnt lgkmcnt(2)
	v_pk_fma_f32 v[76:77], v[94:95], v[86:87], v[76:77]
	s_waitcnt vmcnt(16)
	v_lshlrev_b32_e32 v86, 16, v69
	v_and_b32_e32 v87, 0xffff0000, v69
	s_waitcnt lgkmcnt(0)
	v_pk_fma_f32 v[76:77], v[102:103], v[86:87], v[76:77]
	v_xor_b32_e32 v94, 1, v122
	v_mul_f32_e32 v69, 0xbfb8aa3b, v76
	v_exp_f32_e32 v69, v69
	v_mul_f32_e32 v86, 0xbfb8aa3b, v77
	v_exp_f32_e32 v87, v86
	v_cmp_lt_i32_e32 vcc, v94, v132
	v_add_f32_e32 v69, 1.0, v69
	v_rcp_f32_e32 v86, v69
	v_add_f32_e32 v69, 1.0, v87
	v_rcp_f32_e32 v87, v69
	v_cndmask_b32_e32 v69, v122, v94, vcc
	v_lshlrev_b32_e32 v94, 2, v69
	v_readlane_b32 s18, v251, 9
	v_pk_mul_f32 v[76:77], v[76:77], v[86:87]
	v_lshlrev_b32_e32 v86, 16, v107
	v_and_b32_e32 v87, 0xffff0000, v107
	v_pk_fma_f32 v[74:75], v[74:75], v[86:87], 0 op_sel_hi:[1,1,0]
	v_lshlrev_b32_e32 v86, 16, v110
	v_and_b32_e32 v87, 0xffff0000, v110
	v_pk_fma_f32 v[74:75], v[84:85], v[86:87], v[74:75]
	v_lshlrev_b32_e32 v84, 16, v130
	v_and_b32_e32 v85, 0xffff0000, v130
	v_pk_fma_f32 v[74:75], v[92:93], v[84:85], v[74:75]
	v_lshlrev_b32_e32 v84, 16, v68
	v_and_b32_e32 v85, 0xffff0000, v68
	v_pk_fma_f32 v[68:69], v[100:101], v[84:85], v[74:75]
	v_lshlrev_b32_e32 v86, 16, v106
	v_mul_f32_e32 v74, 0xbfb8aa3b, v68
	v_exp_f32_e32 v84, v74
	v_mul_f32_e32 v74, 0xbfb8aa3b, v69
	v_exp_f32_e32 v85, v74
	v_and_b32_e32 v87, 0xffff0000, v106
	v_pk_fma_f32 v[72:73], v[72:73], v[86:87], 0 op_sel_hi:[1,1,0]
	v_lshlrev_b32_e32 v86, 16, v109
	v_and_b32_e32 v87, 0xffff0000, v109
	v_add_f32_e32 v84, 1.0, v84
	v_add_f32_e32 v85, 1.0, v85
	v_pk_fma_f32 v[72:73], v[80:81], v[86:87], v[72:73]
	v_lshlrev_b32_e32 v80, 16, v113
	v_and_b32_e32 v81, 0xffff0000, v113
	v_rcp_f32_e32 v84, v84
	v_rcp_f32_e32 v85, v85
	v_pk_fma_f32 v[72:73], v[90:91], v[80:81], v[72:73]
	v_lshlrev_b32_e32 v80, 16, v67
	v_and_b32_e32 v81, 0xffff0000, v67
	v_pk_fma_f32 v[72:73], v[98:99], v[80:81], v[72:73]
	v_pk_mul_f32 v[68:69], v[68:69], v[84:85]
	v_mul_f32_e32 v67, 0xbfb8aa3b, v72
	v_exp_f32_e32 v67, v67
	v_lshlrev_b32_e32 v84, 16, v83
	v_and_b32_e32 v85, 0xffff0000, v83
	v_pk_fma_f32 v[70:71], v[70:71], v[84:85], 0 op_sel_hi:[1,1,0]
	v_lshlrev_b32_e32 v84, 16, v108
	v_and_b32_e32 v85, 0xffff0000, v108
	v_pk_fma_f32 v[70:71], v[78:79], v[84:85], v[70:71]
	v_lshlrev_b32_e32 v78, 16, v112
	v_and_b32_e32 v79, 0xffff0000, v112
	v_mul_f32_e32 v80, 0xbfb8aa3b, v73
	v_add_f32_e32 v67, 1.0, v67
	v_pk_fma_f32 v[70:71], v[88:89], v[78:79], v[70:71]
	v_lshlrev_b32_e32 v78, 16, v66
	v_and_b32_e32 v79, 0xffff0000, v66
	v_exp_f32_e32 v81, v80
	v_rcp_f32_e32 v80, v67
	v_pk_fma_f32 v[66:67], v[96:97], v[78:79], v[70:71]
	v_pk_mul_f32 v[78:79], v[68:69], v[68:69]
	v_mul_f32_e32 v70, 0xbfb8aa3b, v66
	v_mul_f32_e32 v71, 0xbfb8aa3b, v67
	v_exp_f32_e32 v70, v70
	v_exp_f32_e32 v71, v71
	v_add_f32_e32 v81, 1.0, v81
	v_rcp_f32_e32 v81, v81
	v_add_f32_e32 v70, 1.0, v70
	v_add_f32_e32 v71, 1.0, v71
	v_rcp_f32_e32 v70, v70
	v_rcp_f32_e32 v71, v71
	v_pk_mul_f32 v[80:81], v[72:73], v[80:81]
	v_pk_mul_f32 v[74:75], v[76:77], v[76:77]
	v_pk_mul_f32 v[72:73], v[80:81], v[80:81]
	v_pk_mul_f32 v[66:67], v[66:67], v[70:71]
	v_readlane_b32 s19, v251, 10
	v_pk_mul_f32 v[70:71], v[66:67], v[66:67]
	v_readlane_b32 s22, v251, 12
	v_add_f32_e32 v70, v70, v71
	v_add_f32_e32 v70, v72, v70
	v_add_f32_e32 v70, v73, v70
	v_add_f32_e32 v70, v78, v70
	v_add_f32_e32 v70, v79, v70
	v_add_f32_e32 v70, v74, v70
	v_add_f32_e32 v70, v75, v70
	s_nop 1
	v_mov_b32_dpp v71, v70 quad_perm:[1,0,3,2] row_mask:0xf bank_mask:0xf
	v_xor_b32_e32 v72, 2, v122
	v_cmp_lt_i32_e32 vcc, v72, v132
	v_readlane_b32 s23, v251, 13
	s_waitcnt lgkmcnt(0)
	v_add_f32_e32 v70, v70, v71
	v_cndmask_b32_e32 v72, v122, v72, vcc
	v_lshlrev_b32_e32 v72, 2, v72
	s_nop 1
	v_mov_b32_dpp v71, v70 quad_perm:[2,3,0,1] row_mask:0xf bank_mask:0xf
	v_xor_b32_e32 v72, 4, v122
	v_cmp_lt_i32_e32 vcc, v72, v132
	s_waitcnt lgkmcnt(0)
	v_add_f32_e32 v70, v70, v71
	v_cndmask_b32_e32 v72, v122, v72, vcc
	v_lshlrev_b32_e32 v72, 2, v72
	s_nop 1
	v_mov_b32_dpp v71, v70 row_half_mirror row_mask:0xf bank_mask:0xf
	v_xor_b32_e32 v72, 8, v122
	v_cmp_lt_i32_e32 vcc, v72, v132
	s_waitcnt lgkmcnt(0)
	v_add_f32_e32 v70, v70, v71
	v_cndmask_b32_e32 v72, v122, v72, vcc
	v_lshlrev_b32_e32 v72, 2, v72
	s_nop 1
	v_mov_b32_dpp v71, v70 row_mirror row_mask:0xf bank_mask:0xf
	s_andn2_b64 vcc, exec, s[22:23]
	s_waitcnt lgkmcnt(0)
	v_add_f32_e32 v70, v70, v71
	v_add_f32_e32 v70, 0x358637bd, v70
	v_rsq_f32_e32 v70, v70
	s_nop 0
	v_cndmask_b32_e64 v70, 1.0, v70, s[18:19]
	v_mul_f32_e32 v71, 0x3db504f3, v70
	v_cndmask_b32_e64 v74, v70, v71, s[22:23]
	v_pk_mul_f32 v[72:73], v[66:67], v[74:75] op_sel_hi:[1,0]
	v_pk_mul_f32 v[70:71], v[80:81], v[74:75] op_sel_hi:[1,0]
	v_pk_mul_f32 v[68:69], v[68:69], v[74:75] op_sel_hi:[1,0]
	v_pk_mul_f32 v[66:67], v[76:77], v[74:75] op_sel_hi:[1,0]
	v_and_b32_e32 v74, 63, v82
	v_readlane_b32 s18, v250, 8
	s_add_i32 s18, s11, s18
	v_mul_u32_u24_e32 v75, 0x110, v74
	v_cvt_pk_bf16_f32 v76, v72, v73
	v_cvt_pk_bf16_f32 v77, v70, v71
	v_cvt_pk_bf16_f32 v78, v68, v69
	v_cvt_pk_bf16_f32 v79, v66, v67
	v_add3_u32 v75, s18, v75, v114
	ds_write_b128 v75, v[76:79] offset:28672
	s_cbranch_vccnz .LBB0_1070
; #define GAS __attribute__((address_space(1)))
; #define LAS __attribute__((address_space(3)))
; __device__ __forceinline__ float siluf_(float x) { return x * __builtin_amdgcn_rcpf(1.0f + __builtin_amdgcn_exp2f(-1.4426950408889634f * x)); }
; __device__ __forceinline__ float sum16(float v) {
; #pragma unroll
;     for (int o = 1; o < 16; o <<= 1) v += __shfl_xor(v, o);
;     return v;
; }
; template <int NW>
; __device__ __forceinline__ void gp_stage0_compute(Frame& F, int cidx, const LAS float* Gs, LAS unsigned char* tiles, int w, int lane, const GpTaps<NW>& tp) {
;     ...
;             float acc[8];
; #pragma unroll
;             for (int e = 0; e < 8; ++e) acc[e] = 0.f;
; #pragma unroll
;             for (int tap = 0; tap < 4; ++tap) {
;                 const v4u xv = tp.xw[it][tap];
;                 const LAS float* cw = cwl + (type * 4 + tap) * 128 + c * 8;
;                 const f32x4 c0 = *(const LAS f32x4*)cw, c1 = *(const LAS f32x4*)(cw + 4);
;                 acc[0] += bflo(xv.x) * c0.x; acc[1] += bfhi(xv.x) * c0.y; acc[2] += bflo(xv.y) * c0.z; acc[3] += bfhi(xv.y) * c0.w;
;                 acc[4] += bflo(xv.z) * c1.x; acc[5] += bfhi(xv.z) * c1.y; acc[6] += bflo(xv.w) * c1.z; acc[7] += bfhi(xv.w) * c1.w;
;             }
;             float ss = 0.f;
; #pragma unroll
;             for (int e = 0; e < 8; ++e) { acc[e] = siluf_(acc[e]); ss += acc[e] * acc[e]; }
;             ss = sum16(ss);
;             float sc = 1.0f;
;             if (type < 2) sc = __builtin_amdgcn_rsqf(ss + EPS);
;             if (type == 0) sc *= 0.08838834764831845f;
; #pragma unroll
;             for (int e = 0; e < 8; ++e) acc[e] *= sc;
;             const v4u o = {gcvtpk(acc[0], acc[1]), gcvtpk(acc[2], acc[3]), gcvtpk(acc[4], acc[5]), gcvtpk(acc[6], acc[7])};
;             *(LAS v4u*)(tiles + type * GP_TILE + i * GP_TS + c * 16) = o;
;             if (type == 0) {
;                 const float e_ = Gs[128 + i];
;                 v2u w0 = {gcvtpk(acc[0] * e_, acc[1] * e_), gcvtpk(acc[2] * e_, acc[3] * e_)}, w1 = {gcvtpk(acc[4] * e_, acc[5] * e_), gcvtpk(acc[6] * e_, acc[7] * e_)};
;                 *(GAS v2u*)(CH + CH_Q + i * RS_W + c * 16) = w0; *(GAS v2u*)(CH + CH_Q + i * RS_W + c * 16 + 8) = w1;
;             }
	v_add_u32_e32 v75, s91, v128
	v_lshl_add_u32 v75, v75, 2, s2
	ds_read_b32 v76, v75 offset:736
	s_waitcnt lgkmcnt(0)
	v_pk_mul_f32 v[70:71], v[70:71], v[76:77] op_sel_hi:[1,0]
	v_pk_mul_f32 v[66:67], v[66:67], v[76:77] op_sel_hi:[1,0]
	v_pk_mul_f32 v[72:73], v[72:73], v[76:77] op_sel_hi:[1,0]
	v_pk_mul_f32 v[78:79], v[68:69], v[76:77] op_sel_hi:[1,0]
	v_cvt_pk_bf16_f32 v69, v70, v71
	v_cvt_pk_bf16_f32 v71, v66, v67
	v_mul_u32_u24_e32 v66, 0x108, v74
	v_mov_b32_e32 v67, v115
	v_cvt_pk_bf16_f32 v68, v72, v73
	v_cvt_pk_bf16_f32 v70, v78, v79
	v_lshl_add_u64 v[66:67], v[116:117], 0, v[66:67]
	global_store_dwordx4 v[66:67], v[68:71], off
.LBB0_1070:
	s_or_b64 exec, exec, s[60:61]
	v_readlane_b32 s18, v251, 17
	s_waitcnt vmcnt(16)
	s_nop 0
	v_or_b32_e32 v66, s18, v128
	v_cmp_gt_i32_e32 vcc, s26, v66
	s_and_saveexec_b64 s[54:55], vcc
	s_cbranch_execz .LBB0_1073
	s_waitcnt vmcnt(14)
	v_cndmask_b32_e64 v92, v54, 0, s[4:5]
	v_cndmask_b32_e64 v93, v55, 0, s[4:5]
	v_cndmask_b32_e64 v94, v56, 0, s[4:5]
	v_cndmask_b32_e64 v95, v57, 0, s[4:5]
	v_readlane_b32 s4, v251, 14
	v_cndmask_b32_e64 v67, v58, 0, s[74:75]
	v_cndmask_b32_e64 v90, v59, 0, s[74:75]
	v_add_u32_e32 v84, s4, v129
	v_cndmask_b32_e64 v91, v60, 0, s[74:75]
	v_cndmask_b32_e64 v89, v61, 0, s[74:75]
	s_waitcnt vmcnt(13)
	v_cndmask_b32_e64 v96, v62, 0, s[52:53]
	v_cndmask_b32_e64 v97, v63, 0, s[52:53]
	v_cndmask_b32_e64 v98, v64, 0, s[52:53]
	v_cndmask_b32_e64 v99, v65, 0, s[52:53]
	ds_read_b128 v[54:57], v84
	ds_read_b128 v[58:61], v84 offset:16
	ds_read_b128 v[62:65], v84 offset:512
	ds_read_b128 v[68:71], v84 offset:528
	ds_read_b128 v[72:75], v84 offset:1024
	ds_read_b128 v[76:79], v84 offset:1040
	ds_read_b128 v[80:83], v84 offset:1536
	ds_read_b128 v[84:87], v84 offset:1552
	v_and_b32_e32 v88, 64, v122
	v_add_u32_e32 v100, 64, v88
	v_lshlrev_b32_e32 v88, 16, v89
	v_and_b32_e32 v89, 0xffff0000, v89
	s_waitcnt lgkmcnt(6)
	v_pk_fma_f32 v[60:61], v[60:61], v[88:89], 0 op_sel_hi:[1,1,0]
	v_lshlrev_b32_e32 v88, 16, v95
	v_and_b32_e32 v89, 0xffff0000, v95
	s_waitcnt lgkmcnt(4)
	v_pk_fma_f32 v[60:61], v[70:71], v[88:89], v[60:61]
	v_lshlrev_b32_e32 v70, 16, v99
	v_and_b32_e32 v71, 0xffff0000, v99
	s_waitcnt lgkmcnt(2)
	v_pk_fma_f32 v[60:61], v[78:79], v[70:71], v[60:61]
	s_waitcnt vmcnt(12)
	v_lshlrev_b32_e32 v70, 16, v53
	v_and_b32_e32 v71, 0xffff0000, v53
	s_waitcnt lgkmcnt(0)
	v_pk_fma_f32 v[60:61], v[86:87], v[70:71], v[60:61]
	v_xor_b32_e32 v78, 1, v122
	v_mul_f32_e32 v53, 0xbfb8aa3b, v60
	v_exp_f32_e32 v53, v53
	v_mul_f32_e32 v70, 0xbfb8aa3b, v61
	v_exp_f32_e32 v71, v70
	v_cmp_lt_i32_e32 vcc, v78, v100
	v_add_f32_e32 v53, 1.0, v53
	v_rcp_f32_e32 v70, v53
	v_add_f32_e32 v53, 1.0, v71
	v_rcp_f32_e32 v71, v53
	v_cndmask_b32_e32 v53, v122, v78, vcc
	v_lshlrev_b32_e32 v78, 2, v53
	v_readlane_b32 s4, v251, 15
	v_pk_mul_f32 v[60:61], v[60:61], v[70:71]
	v_lshlrev_b32_e32 v70, 16, v91
	v_and_b32_e32 v71, 0xffff0000, v91
	v_pk_fma_f32 v[58:59], v[58:59], v[70:71], 0 op_sel_hi:[1,1,0]
	v_lshlrev_b32_e32 v70, 16, v94
	v_and_b32_e32 v71, 0xffff0000, v94
	v_pk_fma_f32 v[58:59], v[68:69], v[70:71], v[58:59]
	v_lshlrev_b32_e32 v68, 16, v98
	v_and_b32_e32 v69, 0xffff0000, v98
	v_pk_fma_f32 v[58:59], v[76:77], v[68:69], v[58:59]
	v_lshlrev_b32_e32 v68, 16, v52
	v_and_b32_e32 v69, 0xffff0000, v52
	v_pk_fma_f32 v[52:53], v[84:85], v[68:69], v[58:59]
	v_lshlrev_b32_e32 v70, 16, v90
	v_mul_f32_e32 v58, 0xbfb8aa3b, v52
	v_exp_f32_e32 v68, v58
	v_mul_f32_e32 v58, 0xbfb8aa3b, v53
	v_exp_f32_e32 v69, v58
	v_and_b32_e32 v71, 0xffff0000, v90
	v_pk_fma_f32 v[56:57], v[56:57], v[70:71], 0 op_sel_hi:[1,1,0]
	v_lshlrev_b32_e32 v70, 16, v93
	v_and_b32_e32 v71, 0xffff0000, v93
	v_add_f32_e32 v68, 1.0, v68
	v_add_f32_e32 v69, 1.0, v69
	v_pk_fma_f32 v[56:57], v[64:65], v[70:71], v[56:57]
	v_lshlrev_b32_e32 v64, 16, v97
	v_and_b32_e32 v65, 0xffff0000, v97
	v_rcp_f32_e32 v68, v68
	v_rcp_f32_e32 v69, v69
	v_pk_fma_f32 v[56:57], v[74:75], v[64:65], v[56:57]
	v_lshlrev_b32_e32 v64, 16, v51
	v_and_b32_e32 v65, 0xffff0000, v51
	v_pk_fma_f32 v[56:57], v[82:83], v[64:65], v[56:57]
	v_pk_mul_f32 v[52:53], v[52:53], v[68:69]
	v_mul_f32_e32 v51, 0xbfb8aa3b, v56
	v_exp_f32_e32 v51, v51
	v_lshlrev_b32_e32 v68, 16, v67
	v_and_b32_e32 v69, 0xffff0000, v67
	v_pk_fma_f32 v[54:55], v[54:55], v[68:69], 0 op_sel_hi:[1,1,0]
	v_lshlrev_b32_e32 v68, 16, v92
	v_and_b32_e32 v69, 0xffff0000, v92
	v_pk_fma_f32 v[54:55], v[62:63], v[68:69], v[54:55]
	v_lshlrev_b32_e32 v62, 16, v96
	v_and_b32_e32 v63, 0xffff0000, v96
	v_mul_f32_e32 v64, 0xbfb8aa3b, v57
	v_add_f32_e32 v51, 1.0, v51
	v_pk_fma_f32 v[54:55], v[72:73], v[62:63], v[54:55]
	v_lshlrev_b32_e32 v62, 16, v50
	v_and_b32_e32 v63, 0xffff0000, v50
	v_exp_f32_e32 v65, v64
	v_rcp_f32_e32 v64, v51
	v_pk_fma_f32 v[50:51], v[80:81], v[62:63], v[54:55]
	v_pk_mul_f32 v[62:63], v[52:53], v[52:53]
	v_mul_f32_e32 v54, 0xbfb8aa3b, v50
	v_mul_f32_e32 v55, 0xbfb8aa3b, v51
	v_exp_f32_e32 v54, v54
	v_exp_f32_e32 v55, v55
	v_add_f32_e32 v65, 1.0, v65
	v_rcp_f32_e32 v65, v65
	v_add_f32_e32 v54, 1.0, v54
	v_add_f32_e32 v55, 1.0, v55
	v_rcp_f32_e32 v54, v54
	v_rcp_f32_e32 v55, v55
	v_pk_mul_f32 v[64:65], v[56:57], v[64:65]
	v_pk_mul_f32 v[58:59], v[60:61], v[60:61]
	v_pk_mul_f32 v[56:57], v[64:65], v[64:65]
	v_pk_mul_f32 v[50:51], v[50:51], v[54:55]
	v_readlane_b32 s5, v251, 16
	v_pk_mul_f32 v[54:55], v[50:51], v[50:51]
	v_readlane_b32 s18, v250, 9
	v_add_f32_e32 v54, v54, v55
	v_add_f32_e32 v54, v56, v54
	v_add_f32_e32 v54, v57, v54
	v_add_f32_e32 v54, v62, v54
	v_add_f32_e32 v54, v63, v54
	v_add_f32_e32 v54, v58, v54
	v_add_f32_e32 v54, v59, v54
	s_nop 1
	v_mov_b32_dpp v55, v54 quad_perm:[1,0,3,2] row_mask:0xf bank_mask:0xf
	v_xor_b32_e32 v56, 2, v122
	v_cmp_lt_i32_e32 vcc, v56, v100
	s_add_i32 s18, s11, s18
	s_waitcnt lgkmcnt(0)
; #define GAS __attribute__((address_space(1)))
; #define LAS __attribute__((address_space(3)))
; __device__ __forceinline__ float siluf_(float x) { return x * __builtin_amdgcn_rcpf(1.0f + __builtin_amdgcn_exp2f(-1.4426950408889634f * x)); }
; __device__ __forceinline__ float sum16(float v) {
; #pragma unroll
;     for (int o = 1; o < 16; o <<= 1) v += __shfl_xor(v, o);
;     return v;
; }
; template <int NW>
; __device__ __forceinline__ void gp_stage0_compute(Frame& F, int cidx, const LAS float* Gs, LAS unsigned char* tiles, int w, int lane, const GpTaps<NW>& tp) {
;     ...
;             float acc[8];
; #pragma unroll
;             for (int e = 0; e < 8; ++e) acc[e] = 0.f;
; #pragma unroll
;             for (int tap = 0; tap < 4; ++tap) {
;                 const v4u xv = tp.xw[it][tap];
;                 const LAS float* cw = cwl + (type * 4 + tap) * 128 + c * 8;
;                 const f32x4 c0 = *(const LAS f32x4*)cw, c1 = *(const LAS f32x4*)(cw + 4);
;                 acc[0] += bflo(xv.x) * c0.x; acc[1] += bfhi(xv.x) * c0.y; acc[2] += bflo(xv.y) * c0.z; acc[3] += bfhi(xv.y) * c0.w;
;                 acc[4] += bflo(xv.z) * c1.x; acc[5] += bfhi(xv.z) * c1.y; acc[6] += bflo(xv.w) * c1.z; acc[7] += bfhi(xv.w) * c1.w;
;             }
;             float ss = 0.f;
; #pragma unroll
;             for (int e = 0; e < 8; ++e) { acc[e] = siluf_(acc[e]); ss += acc[e] * acc[e]; }
;             ss = sum16(ss);
;             float sc = 1.0f;
;             if (type < 2) sc = __builtin_amdgcn_rsqf(ss + EPS);
;             if (type == 0) sc *= 0.08838834764831845f;
; #pragma unroll
;             for (int e = 0; e < 8; ++e) acc[e] *= sc;
;             const v4u o = {gcvtpk(acc[0], acc[1]), gcvtpk(acc[2], acc[3]), gcvtpk(acc[4], acc[5]), gcvtpk(acc[6], acc[7])};
;             *(LAS v4u*)(tiles + type * GP_TILE + i * GP_TS + c * 16) = o;
;             if (type == 0) {
;                 const float e_ = Gs[128 + i];
;                 v2u w0 = {gcvtpk(acc[0] * e_, acc[1] * e_), gcvtpk(acc[2] * e_, acc[3] * e_)}, w1 = {gcvtpk(acc[4] * e_, acc[5] * e_), gcvtpk(acc[6] * e_, acc[7] * e_)};
;                 *(GAS v2u*)(CH + CH_Q + i * RS_W + c * 16) = w0; *(GAS v2u*)(CH + CH_Q + i * RS_W + c * 16 + 8) = w1;
;             }
	v_add_f32_e32 v54, v54, v55
	v_cndmask_b32_e32 v56, v122, v56, vcc
	v_lshlrev_b32_e32 v56, 2, v56
	s_nop 1
	v_mov_b32_dpp v55, v54 quad_perm:[2,3,0,1] row_mask:0xf bank_mask:0xf
	v_xor_b32_e32 v56, 4, v122
	v_cmp_lt_i32_e32 vcc, v56, v100
	s_waitcnt lgkmcnt(0)
	v_add_f32_e32 v54, v54, v55
	v_cndmask_b32_e32 v56, v122, v56, vcc
	v_lshlrev_b32_e32 v56, 2, v56
	s_nop 1
	v_mov_b32_dpp v55, v54 row_half_mirror row_mask:0xf bank_mask:0xf
	v_xor_b32_e32 v56, 8, v122
	v_cmp_lt_i32_e32 vcc, v56, v100
	s_waitcnt lgkmcnt(0)
	v_add_f32_e32 v54, v54, v55
	v_cndmask_b32_e32 v56, v122, v56, vcc
	v_lshlrev_b32_e32 v56, 2, v56
	s_nop 1
	v_mov_b32_dpp v55, v54 row_mirror row_mask:0xf bank_mask:0xf
	s_waitcnt lgkmcnt(0)
	v_add_f32_e32 v54, v54, v55
	v_add_f32_e32 v54, 0x358637bd, v54
	v_rsq_f32_e32 v54, v54
	s_nop 0
	v_cndmask_b32_e64 v54, 1.0, v54, s[4:5]
	v_readlane_b32 s4, v251, 18
	v_mul_f32_e32 v55, 0x3db504f3, v54
	v_readlane_b32 s5, v251, 19
	s_andn2_b64 vcc, exec, s[4:5]
	s_nop 0
	v_cndmask_b32_e64 v58, v54, v55, s[4:5]
	v_pk_mul_f32 v[56:57], v[50:51], v[58:59] op_sel_hi:[1,0]
	v_pk_mul_f32 v[54:55], v[64:65], v[58:59] op_sel_hi:[1,0]
	v_pk_mul_f32 v[52:53], v[52:53], v[58:59] op_sel_hi:[1,0]
	v_pk_mul_f32 v[50:51], v[60:61], v[58:59] op_sel_hi:[1,0]
	v_and_b32_e32 v58, 63, v66
	v_mul_u32_u24_e32 v59, 0x110, v58
	v_cvt_pk_bf16_f32 v60, v56, v57
	v_cvt_pk_bf16_f32 v61, v54, v55
	v_cvt_pk_bf16_f32 v62, v52, v53
	v_cvt_pk_bf16_f32 v63, v50, v51
	v_add3_u32 v59, s18, v59, v114
	ds_write_b128 v59, v[60:63] offset:28672
	s_cbranch_vccnz .LBB0_1073
	v_add_u32_e32 v59, s91, v128
	v_lshl_add_u32 v59, v59, 2, s2
	ds_read_b32 v60, v59 offset:848
	s_waitcnt lgkmcnt(0)
	v_pk_mul_f32 v[54:55], v[54:55], v[60:61] op_sel_hi:[1,0]
	v_pk_mul_f32 v[50:51], v[50:51], v[60:61] op_sel_hi:[1,0]
	v_pk_mul_f32 v[56:57], v[56:57], v[60:61] op_sel_hi:[1,0]
	v_pk_mul_f32 v[62:63], v[52:53], v[60:61] op_sel_hi:[1,0]
	v_cvt_pk_bf16_f32 v53, v54, v55
	v_cvt_pk_bf16_f32 v55, v50, v51
	v_mul_u32_u24_e32 v50, 0x108, v58
	v_mov_b32_e32 v51, v115
	v_cvt_pk_bf16_f32 v52, v56, v57
	v_cvt_pk_bf16_f32 v54, v62, v63
	v_lshl_add_u64 v[50:51], v[116:117], 0, v[50:51]
	global_store_dwordx4 v[50:51], v[52:55], off
.LBB0_1073:
	s_or_b64 exec, exec, s[54:55]
	v_readlane_b32 s4, v251, 23
	s_waitcnt vmcnt(12)
	s_nop 0
	v_or_b32_e32 v50, s4, v128
	v_cmp_gt_i32_e32 vcc, s26, v50
	s_and_saveexec_b64 s[48:49], vcc
	s_cbranch_execz .LBB0_1076
	s_waitcnt vmcnt(9)
	v_cndmask_b32_e64 v80, v46, 0, s[0:1]
	v_cndmask_b32_e64 v81, v47, 0, s[0:1]
	v_cndmask_b32_e64 v82, v48, 0, s[0:1]
	v_cndmask_b32_e64 v83, v49, 0, s[0:1]
	v_readlane_b32 s0, v251, 20
	v_cndmask_b32_e64 v51, v42, 0, s[6:7]
	v_cndmask_b32_e64 v74, v43, 0, s[6:7]
	v_add_u32_e32 v68, s0, v129
	v_cndmask_b32_e64 v75, v44, 0, s[6:7]
	v_cndmask_b32_e64 v73, v45, 0, s[6:7]
	v_cndmask_b32_e64 v76, v38, 0, s[86:87]
	v_cndmask_b32_e64 v77, v39, 0, s[86:87]
	v_cndmask_b32_e64 v78, v40, 0, s[86:87]
	v_cndmask_b32_e64 v79, v41, 0, s[86:87]
	ds_read_b128 v[38:41], v68
	ds_read_b128 v[42:45], v68 offset:16
	ds_read_b128 v[46:49], v68 offset:512
	ds_read_b128 v[52:55], v68 offset:528
	ds_read_b128 v[56:59], v68 offset:1024
	ds_read_b128 v[60:63], v68 offset:1040
	ds_read_b128 v[64:67], v68 offset:1536
	ds_read_b128 v[68:71], v68 offset:1552
	v_and_b32_e32 v72, 64, v122
	v_add_u32_e32 v84, 64, v72
	v_lshlrev_b32_e32 v72, 16, v73
	v_and_b32_e32 v73, 0xffff0000, v73
	s_waitcnt lgkmcnt(6)
	v_pk_fma_f32 v[44:45], v[44:45], v[72:73], 0 op_sel_hi:[1,1,0]
	v_lshlrev_b32_e32 v72, 16, v79
	v_and_b32_e32 v73, 0xffff0000, v79
	s_waitcnt lgkmcnt(4)
	v_pk_fma_f32 v[44:45], v[54:55], v[72:73], v[44:45]
	v_lshlrev_b32_e32 v54, 16, v83
	v_and_b32_e32 v55, 0xffff0000, v83
	s_waitcnt lgkmcnt(2)
	v_pk_fma_f32 v[44:45], v[62:63], v[54:55], v[44:45]
	s_waitcnt vmcnt(8)
	v_lshlrev_b32_e32 v54, 16, v37
	v_and_b32_e32 v55, 0xffff0000, v37
	s_waitcnt lgkmcnt(0)
	v_pk_fma_f32 v[44:45], v[70:71], v[54:55], v[44:45]
	v_xor_b32_e32 v62, 1, v122
	v_mul_f32_e32 v37, 0xbfb8aa3b, v44
	v_exp_f32_e32 v37, v37
	v_mul_f32_e32 v54, 0xbfb8aa3b, v45
	v_exp_f32_e32 v55, v54
	v_cmp_lt_i32_e32 vcc, v62, v84
	v_add_f32_e32 v37, 1.0, v37
	v_rcp_f32_e32 v54, v37
	v_add_f32_e32 v37, 1.0, v55
	v_rcp_f32_e32 v55, v37
	v_cndmask_b32_e32 v37, v122, v62, vcc
	v_lshlrev_b32_e32 v62, 2, v37
	v_readlane_b32 s0, v251, 21
	v_pk_mul_f32 v[44:45], v[44:45], v[54:55]
	v_lshlrev_b32_e32 v54, 16, v75
	v_and_b32_e32 v55, 0xffff0000, v75
	v_pk_fma_f32 v[42:43], v[42:43], v[54:55], 0 op_sel_hi:[1,1,0]
	v_lshlrev_b32_e32 v54, 16, v78
	v_and_b32_e32 v55, 0xffff0000, v78
	v_pk_fma_f32 v[42:43], v[52:53], v[54:55], v[42:43]
	v_lshlrev_b32_e32 v52, 16, v82
	v_and_b32_e32 v53, 0xffff0000, v82
	v_pk_fma_f32 v[42:43], v[60:61], v[52:53], v[42:43]
	v_lshlrev_b32_e32 v52, 16, v36
	v_and_b32_e32 v53, 0xffff0000, v36
	v_pk_fma_f32 v[36:37], v[68:69], v[52:53], v[42:43]
	v_lshlrev_b32_e32 v54, 16, v74
	v_mul_f32_e32 v42, 0xbfb8aa3b, v36
	v_exp_f32_e32 v52, v42
	v_mul_f32_e32 v42, 0xbfb8aa3b, v37
	v_exp_f32_e32 v53, v42
	v_and_b32_e32 v55, 0xffff0000, v74
	v_pk_fma_f32 v[40:41], v[40:41], v[54:55], 0 op_sel_hi:[1,1,0]
	v_lshlrev_b32_e32 v54, 16, v77
	v_and_b32_e32 v55, 0xffff0000, v77
	v_add_f32_e32 v52, 1.0, v52
	v_add_f32_e32 v53, 1.0, v53
	v_pk_fma_f32 v[40:41], v[48:49], v[54:55], v[40:41]
	v_lshlrev_b32_e32 v48, 16, v81
	v_and_b32_e32 v49, 0xffff0000, v81
	v_rcp_f32_e32 v52, v52
	v_rcp_f32_e32 v53, v53
	v_pk_fma_f32 v[40:41], v[58:59], v[48:49], v[40:41]
	v_lshlrev_b32_e32 v48, 16, v35
	v_and_b32_e32 v49, 0xffff0000, v35
	v_pk_fma_f32 v[40:41], v[66:67], v[48:49], v[40:41]
	v_pk_mul_f32 v[36:37], v[36:37], v[52:53]
; #define GAS __attribute__((address_space(1)))
; #define LAS __attribute__((address_space(3)))
; __device__ __forceinline__ float siluf_(float x) { return x * __builtin_amdgcn_rcpf(1.0f + __builtin_amdgcn_exp2f(-1.4426950408889634f * x)); }
; __device__ __forceinline__ unsigned gcvtpk(float lo, float hi) { gf32x2 v = {lo, hi}; gbf16x2 b = __builtin_convertvector(v, gbf16x2); return __builtin_bit_cast(unsigned, b); }
; __device__ __forceinline__ float sum16(float v) {
; #pragma unroll
;     for (int o = 1; o < 16; o <<= 1) v += __shfl_xor(v, o);
;     return v;
; }
; template <int NW>
; __device__ __forceinline__ void gp_stage0_compute(Frame& F, int cidx, const LAS float* Gs, LAS unsigned char* tiles, int w, int lane, const GpTaps<NW>& tp) {
;     ...
; #pragma unroll
;             for (int tap = 0; tap < 4; ++tap) {
;                 const v4u xv = tp.xw[it][tap];
;                 const LAS float* cw = cwl + (type * 4 + tap) * 128 + c * 8;
;                 const f32x4 c0 = *(const LAS f32x4*)cw, c1 = *(const LAS f32x4*)(cw + 4);
;                 acc[0] += bflo(xv.x) * c0.x; acc[1] += bfhi(xv.x) * c0.y; acc[2] += bflo(xv.y) * c0.z; acc[3] += bfhi(xv.y) * c0.w;
;                 acc[4] += bflo(xv.z) * c1.x; acc[5] += bfhi(xv.z) * c1.y; acc[6] += bflo(xv.w) * c1.z; acc[7] += bfhi(xv.w) * c1.w;
;             }
;             float ss = 0.f;
; #pragma unroll
;             for (int e = 0; e < 8; ++e) { acc[e] = siluf_(acc[e]); ss += acc[e] * acc[e]; }
;             ss = sum16(ss);
;             float sc = 1.0f;
;             if (type < 2) sc = __builtin_amdgcn_rsqf(ss + EPS);
;             if (type == 0) sc *= 0.08838834764831845f;
; #pragma unroll
;             for (int e = 0; e < 8; ++e) acc[e] *= sc;
;             const v4u o = {gcvtpk(acc[0], acc[1]), gcvtpk(acc[2], acc[3]), gcvtpk(acc[4], acc[5]), gcvtpk(acc[6], acc[7])};
;             *(LAS v4u*)(tiles + type * GP_TILE + i * GP_TS + c * 16) = o;
;             if (type == 0) {
;                 const float e_ = Gs[128 + i];
;                 v2u w0 = {gcvtpk(acc[0] * e_, acc[1] * e_), gcvtpk(acc[2] * e_, acc[3] * e_)}, w1 = {gcvtpk(acc[4] * e_, acc[5] * e_), gcvtpk(acc[6] * e_, acc[7] * e_)};
;                 *(GAS v2u*)(CH + CH_Q + i * RS_W + c * 16) = w0; *(GAS v2u*)(CH + CH_Q + i * RS_W + c * 16 + 8) = w1;
;             }
	v_mul_f32_e32 v35, 0xbfb8aa3b, v40
	v_exp_f32_e32 v35, v35
	v_lshlrev_b32_e32 v52, 16, v51
	v_and_b32_e32 v53, 0xffff0000, v51
	v_pk_fma_f32 v[38:39], v[38:39], v[52:53], 0 op_sel_hi:[1,1,0]
	v_lshlrev_b32_e32 v52, 16, v76
	v_and_b32_e32 v53, 0xffff0000, v76
	v_pk_fma_f32 v[38:39], v[46:47], v[52:53], v[38:39]
	v_lshlrev_b32_e32 v46, 16, v80
	v_and_b32_e32 v47, 0xffff0000, v80
	v_mul_f32_e32 v48, 0xbfb8aa3b, v41
	v_add_f32_e32 v35, 1.0, v35
	v_pk_fma_f32 v[38:39], v[56:57], v[46:47], v[38:39]
	v_lshlrev_b32_e32 v46, 16, v34
	v_and_b32_e32 v47, 0xffff0000, v34
	v_exp_f32_e32 v49, v48
	v_rcp_f32_e32 v48, v35
	v_pk_fma_f32 v[34:35], v[64:65], v[46:47], v[38:39]
	v_pk_mul_f32 v[46:47], v[36:37], v[36:37]
	v_mul_f32_e32 v38, 0xbfb8aa3b, v34
	v_mul_f32_e32 v39, 0xbfb8aa3b, v35
	v_exp_f32_e32 v38, v38
	v_exp_f32_e32 v39, v39
	v_add_f32_e32 v49, 1.0, v49
	v_rcp_f32_e32 v49, v49
	v_add_f32_e32 v38, 1.0, v38
	v_add_f32_e32 v39, 1.0, v39
	v_rcp_f32_e32 v38, v38
	v_rcp_f32_e32 v39, v39
	v_pk_mul_f32 v[48:49], v[40:41], v[48:49]
	v_pk_mul_f32 v[42:43], v[44:45], v[44:45]
	v_pk_mul_f32 v[40:41], v[48:49], v[48:49]
	v_pk_mul_f32 v[34:35], v[34:35], v[38:39]
	v_readlane_b32 s1, v251, 22
	v_pk_mul_f32 v[38:39], v[34:35], v[34:35]
	v_readlane_b32 s4, v250, 10
	v_add_f32_e32 v38, v38, v39
	v_add_f32_e32 v38, v40, v38
	v_add_f32_e32 v38, v41, v38
	v_add_f32_e32 v38, v46, v38
	v_add_f32_e32 v38, v47, v38
	v_add_f32_e32 v38, v42, v38
	v_add_f32_e32 v38, v43, v38
	s_nop 1
	v_mov_b32_dpp v39, v38 quad_perm:[1,0,3,2] row_mask:0xf bank_mask:0xf
	v_xor_b32_e32 v40, 2, v122
	v_cmp_lt_i32_e32 vcc, v40, v84
	s_add_i32 s18, s11, s4
	s_waitcnt lgkmcnt(0)
	v_add_f32_e32 v38, v38, v39
	v_cndmask_b32_e32 v40, v122, v40, vcc
	v_lshlrev_b32_e32 v40, 2, v40
	s_nop 1
	v_mov_b32_dpp v39, v38 quad_perm:[2,3,0,1] row_mask:0xf bank_mask:0xf
	v_xor_b32_e32 v40, 4, v122
	v_cmp_lt_i32_e32 vcc, v40, v84
	s_waitcnt lgkmcnt(0)
	v_add_f32_e32 v38, v38, v39
	v_cndmask_b32_e32 v40, v122, v40, vcc
	v_lshlrev_b32_e32 v40, 2, v40
	s_nop 1
	v_mov_b32_dpp v39, v38 row_half_mirror row_mask:0xf bank_mask:0xf
	v_xor_b32_e32 v40, 8, v122
	v_cmp_lt_i32_e32 vcc, v40, v84
	s_waitcnt lgkmcnt(0)
	v_add_f32_e32 v38, v38, v39
	v_cndmask_b32_e32 v40, v122, v40, vcc
	v_lshlrev_b32_e32 v40, 2, v40
	s_nop 1
	v_mov_b32_dpp v39, v38 row_mirror row_mask:0xf bank_mask:0xf
	s_waitcnt lgkmcnt(0)
	v_add_f32_e32 v38, v38, v39
	v_add_f32_e32 v38, 0x358637bd, v38
	v_rsq_f32_e32 v38, v38
	s_nop 0
	v_cndmask_b32_e64 v38, 1.0, v38, s[0:1]
	v_readlane_b32 s0, v251, 24
	v_mul_f32_e32 v39, 0x3db504f3, v38
	v_readlane_b32 s1, v251, 25
	s_andn2_b64 vcc, exec, s[0:1]
	s_nop 0
	v_cndmask_b32_e64 v42, v38, v39, s[0:1]
	v_pk_mul_f32 v[40:41], v[34:35], v[42:43] op_sel_hi:[1,0]
	v_pk_mul_f32 v[38:39], v[48:49], v[42:43] op_sel_hi:[1,0]
	v_pk_mul_f32 v[36:37], v[36:37], v[42:43] op_sel_hi:[1,0]
	v_pk_mul_f32 v[34:35], v[44:45], v[42:43] op_sel_hi:[1,0]
	v_and_b32_e32 v42, 63, v50
	v_mul_u32_u24_e32 v43, 0x110, v42
	v_cvt_pk_bf16_f32 v44, v40, v41
	v_cvt_pk_bf16_f32 v45, v38, v39
	v_cvt_pk_bf16_f32 v46, v36, v37
	v_cvt_pk_bf16_f32 v47, v34, v35
	v_add3_u32 v43, s18, v43, v114
	ds_write_b128 v43, v[44:47] offset:28672
	s_cbranch_vccnz .LBB0_1076
	v_add_u32_e32 v43, s91, v128
	v_lshl_add_u32 v43, v43, 2, s2
	ds_read_b32 v44, v43 offset:960
	s_waitcnt lgkmcnt(0)
	v_pk_mul_f32 v[38:39], v[38:39], v[44:45] op_sel_hi:[1,0]
	v_pk_mul_f32 v[34:35], v[34:35], v[44:45] op_sel_hi:[1,0]
	v_pk_mul_f32 v[40:41], v[40:41], v[44:45] op_sel_hi:[1,0]
	v_pk_mul_f32 v[46:47], v[36:37], v[44:45] op_sel_hi:[1,0]
	v_cvt_pk_bf16_f32 v37, v38, v39
	v_cvt_pk_bf16_f32 v39, v34, v35
	v_mul_u32_u24_e32 v34, 0x108, v42
	v_mov_b32_e32 v35, v115
	v_cvt_pk_bf16_f32 v36, v40, v41
	v_cvt_pk_bf16_f32 v38, v46, v47
	v_lshl_add_u64 v[34:35], v[116:117], 0, v[34:35]
	global_store_dwordx4 v[34:35], v[36:39], off
.LBB0_1076:
	s_or_b64 exec, exec, s[48:49]
	v_readlane_b32 s0, v251, 29
	s_waitcnt vmcnt(8)
	s_nop 0
	v_or_b32_e32 v34, s0, v128
	v_cmp_gt_i32_e32 vcc, s26, v34
	s_and_saveexec_b64 s[42:43], vcc
	s_cbranch_execz .LBB0_1079
	v_readlane_b32 s0, v251, 26
	s_waitcnt vmcnt(7)
	v_cndmask_b32_e64 v35, v26, 0, s[14:15]
	v_cndmask_b32_e64 v58, v27, 0, s[14:15]
	v_add_u32_e32 v52, s0, v129
	v_cndmask_b32_e64 v59, v28, 0, s[14:15]
	v_cndmask_b32_e64 v57, v29, 0, s[14:15]
	s_waitcnt vmcnt(6)
	v_cndmask_b32_e64 v60, v22, 0, s[8:9]
	v_cndmask_b32_e64 v61, v23, 0, s[8:9]
	v_cndmask_b32_e64 v62, v24, 0, s[8:9]
	v_cndmask_b32_e64 v63, v25, 0, s[8:9]
	s_waitcnt vmcnt(5)
	v_cndmask_b32_e64 v64, v30, 0, s[12:13]
	v_cndmask_b32_e64 v65, v31, 0, s[12:13]
	v_cndmask_b32_e64 v66, v32, 0, s[12:13]
	v_cndmask_b32_e64 v67, v33, 0, s[12:13]
	ds_read_b128 v[22:25], v52
	ds_read_b128 v[26:29], v52 offset:16
	ds_read_b128 v[30:33], v52 offset:512
	ds_read_b128 v[36:39], v52 offset:528
	ds_read_b128 v[40:43], v52 offset:1024
	ds_read_b128 v[44:47], v52 offset:1040
	ds_read_b128 v[48:51], v52 offset:1536
	ds_read_b128 v[52:55], v52 offset:1552
	v_and_b32_e32 v56, 64, v122
	v_add_u32_e32 v68, 64, v56
	v_lshlrev_b32_e32 v56, 16, v57
	v_and_b32_e32 v57, 0xffff0000, v57
	s_waitcnt lgkmcnt(6)
	v_pk_fma_f32 v[28:29], v[28:29], v[56:57], 0 op_sel_hi:[1,1,0]
	v_lshlrev_b32_e32 v56, 16, v63
	v_and_b32_e32 v57, 0xffff0000, v63
	s_waitcnt lgkmcnt(4)
	v_pk_fma_f32 v[28:29], v[38:39], v[56:57], v[28:29]
	v_lshlrev_b32_e32 v38, 16, v67
	v_and_b32_e32 v39, 0xffff0000, v67
	s_waitcnt lgkmcnt(2)
	v_pk_fma_f32 v[28:29], v[46:47], v[38:39], v[28:29]
	s_waitcnt vmcnt(4)
	v_lshlrev_b32_e32 v38, 16, v21
	v_and_b32_e32 v39, 0xffff0000, v21
	s_waitcnt lgkmcnt(0)
; #define GAS __attribute__((address_space(1)))
; #define LAS __attribute__((address_space(3)))
; __device__ __forceinline__ float siluf_(float x) { return x * __builtin_amdgcn_rcpf(1.0f + __builtin_amdgcn_exp2f(-1.4426950408889634f * x)); }
; __device__ __forceinline__ unsigned gcvtpk(float lo, float hi) { gf32x2 v = {lo, hi}; gbf16x2 b = __builtin_convertvector(v, gbf16x2); return __builtin_bit_cast(unsigned, b); }
; __device__ __forceinline__ float sum16(float v) {
; #pragma unroll
;     for (int o = 1; o < 16; o <<= 1) v += __shfl_xor(v, o);
;     return v;
; }
; template <int NW>
; __device__ __forceinline__ void gp_stage0_compute(Frame& F, int cidx, const LAS float* Gs, LAS unsigned char* tiles, int w, int lane, const GpTaps<NW>& tp) {
;     ...
; #pragma unroll
;             for (int tap = 0; tap < 4; ++tap) {
;                 const v4u xv = tp.xw[it][tap];
;                 const LAS float* cw = cwl + (type * 4 + tap) * 128 + c * 8;
;                 const f32x4 c0 = *(const LAS f32x4*)cw, c1 = *(const LAS f32x4*)(cw + 4);
;                 acc[0] += bflo(xv.x) * c0.x; acc[1] += bfhi(xv.x) * c0.y; acc[2] += bflo(xv.y) * c0.z; acc[3] += bfhi(xv.y) * c0.w;
;                 acc[4] += bflo(xv.z) * c1.x; acc[5] += bfhi(xv.z) * c1.y; acc[6] += bflo(xv.w) * c1.z; acc[7] += bfhi(xv.w) * c1.w;
;             }
;             float ss = 0.f;
; #pragma unroll
;             for (int e = 0; e < 8; ++e) { acc[e] = siluf_(acc[e]); ss += acc[e] * acc[e]; }
;             ss = sum16(ss);
;             float sc = 1.0f;
;             if (type < 2) sc = __builtin_amdgcn_rsqf(ss + EPS);
;             if (type == 0) sc *= 0.08838834764831845f;
; #pragma unroll
;             for (int e = 0; e < 8; ++e) acc[e] *= sc;
;             const v4u o = {gcvtpk(acc[0], acc[1]), gcvtpk(acc[2], acc[3]), gcvtpk(acc[4], acc[5]), gcvtpk(acc[6], acc[7])};
;             *(LAS v4u*)(tiles + type * GP_TILE + i * GP_TS + c * 16) = o;
;             if (type == 0) {
;                 const float e_ = Gs[128 + i];
;                 v2u w0 = {gcvtpk(acc[0] * e_, acc[1] * e_), gcvtpk(acc[2] * e_, acc[3] * e_)}, w1 = {gcvtpk(acc[4] * e_, acc[5] * e_), gcvtpk(acc[6] * e_, acc[7] * e_)};
;                 *(GAS v2u*)(CH + CH_Q + i * RS_W + c * 16) = w0; *(GAS v2u*)(CH + CH_Q + i * RS_W + c * 16 + 8) = w1;
;             }
	v_pk_fma_f32 v[28:29], v[54:55], v[38:39], v[28:29]
	v_xor_b32_e32 v46, 1, v122
	v_mul_f32_e32 v21, 0xbfb8aa3b, v28
	v_exp_f32_e32 v21, v21
	v_mul_f32_e32 v38, 0xbfb8aa3b, v29
	v_exp_f32_e32 v39, v38
	v_cmp_lt_i32_e32 vcc, v46, v68
	v_add_f32_e32 v21, 1.0, v21
	v_rcp_f32_e32 v38, v21
	v_add_f32_e32 v21, 1.0, v39
	v_rcp_f32_e32 v39, v21
	v_cndmask_b32_e32 v21, v122, v46, vcc
	v_lshlrev_b32_e32 v46, 2, v21
	v_readlane_b32 s0, v251, 27
	v_pk_mul_f32 v[28:29], v[28:29], v[38:39]
	v_lshlrev_b32_e32 v38, 16, v59
	v_and_b32_e32 v39, 0xffff0000, v59
	v_pk_fma_f32 v[26:27], v[26:27], v[38:39], 0 op_sel_hi:[1,1,0]
	v_lshlrev_b32_e32 v38, 16, v62
	v_and_b32_e32 v39, 0xffff0000, v62
	v_pk_fma_f32 v[26:27], v[36:37], v[38:39], v[26:27]
	v_lshlrev_b32_e32 v36, 16, v66
	v_and_b32_e32 v37, 0xffff0000, v66
	v_pk_fma_f32 v[26:27], v[44:45], v[36:37], v[26:27]
	v_lshlrev_b32_e32 v36, 16, v20
	v_and_b32_e32 v37, 0xffff0000, v20
	v_pk_fma_f32 v[20:21], v[52:53], v[36:37], v[26:27]
	v_lshlrev_b32_e32 v38, 16, v58
	v_mul_f32_e32 v26, 0xbfb8aa3b, v20
	v_exp_f32_e32 v36, v26
	v_mul_f32_e32 v26, 0xbfb8aa3b, v21
	v_exp_f32_e32 v37, v26
	v_and_b32_e32 v39, 0xffff0000, v58
	v_pk_fma_f32 v[24:25], v[24:25], v[38:39], 0 op_sel_hi:[1,1,0]
	v_lshlrev_b32_e32 v38, 16, v61
	v_and_b32_e32 v39, 0xffff0000, v61
	v_add_f32_e32 v36, 1.0, v36
	v_add_f32_e32 v37, 1.0, v37
	v_pk_fma_f32 v[24:25], v[32:33], v[38:39], v[24:25]
	v_lshlrev_b32_e32 v32, 16, v65
	v_and_b32_e32 v33, 0xffff0000, v65
	v_rcp_f32_e32 v36, v36
	v_rcp_f32_e32 v37, v37
	v_pk_fma_f32 v[24:25], v[42:43], v[32:33], v[24:25]
	v_lshlrev_b32_e32 v32, 16, v19
	v_and_b32_e32 v33, 0xffff0000, v19
	v_pk_fma_f32 v[24:25], v[50:51], v[32:33], v[24:25]
	v_pk_mul_f32 v[20:21], v[20:21], v[36:37]
	v_mul_f32_e32 v19, 0xbfb8aa3b, v24
	v_exp_f32_e32 v19, v19
	v_lshlrev_b32_e32 v36, 16, v35
	v_and_b32_e32 v37, 0xffff0000, v35
	v_pk_fma_f32 v[22:23], v[22:23], v[36:37], 0 op_sel_hi:[1,1,0]
	v_lshlrev_b32_e32 v36, 16, v60
	v_and_b32_e32 v37, 0xffff0000, v60
	v_pk_fma_f32 v[22:23], v[30:31], v[36:37], v[22:23]
	v_lshlrev_b32_e32 v30, 16, v64
	v_and_b32_e32 v31, 0xffff0000, v64
	v_mul_f32_e32 v32, 0xbfb8aa3b, v25
	v_add_f32_e32 v19, 1.0, v19
	v_pk_fma_f32 v[22:23], v[40:41], v[30:31], v[22:23]
	v_lshlrev_b32_e32 v30, 16, v18
	v_and_b32_e32 v31, 0xffff0000, v18
	v_exp_f32_e32 v33, v32
	v_rcp_f32_e32 v32, v19
	v_pk_fma_f32 v[18:19], v[48:49], v[30:31], v[22:23]
	v_pk_mul_f32 v[30:31], v[20:21], v[20:21]
	v_mul_f32_e32 v22, 0xbfb8aa3b, v18
	v_mul_f32_e32 v23, 0xbfb8aa3b, v19
	v_exp_f32_e32 v22, v22
	v_exp_f32_e32 v23, v23
	v_add_f32_e32 v33, 1.0, v33
	v_rcp_f32_e32 v33, v33
	v_add_f32_e32 v22, 1.0, v22
	v_add_f32_e32 v23, 1.0, v23
	v_rcp_f32_e32 v22, v22
	v_rcp_f32_e32 v23, v23
	v_pk_mul_f32 v[32:33], v[24:25], v[32:33]
	v_pk_mul_f32 v[26:27], v[28:29], v[28:29]
	v_pk_mul_f32 v[24:25], v[32:33], v[32:33]
	v_pk_mul_f32 v[18:19], v[18:19], v[22:23]
	v_readlane_b32 s1, v251, 28
	v_pk_mul_f32 v[22:23], v[18:19], v[18:19]
	v_readlane_b32 s4, v250, 11
	v_add_f32_e32 v22, v22, v23
	v_add_f32_e32 v22, v24, v22
	v_add_f32_e32 v22, v25, v22
	v_add_f32_e32 v22, v30, v22
	v_add_f32_e32 v22, v31, v22
	v_add_f32_e32 v22, v26, v22
	v_add_f32_e32 v22, v27, v22
	s_nop 1
	v_mov_b32_dpp v23, v22 quad_perm:[1,0,3,2] row_mask:0xf bank_mask:0xf
	v_xor_b32_e32 v24, 2, v122
	v_cmp_lt_i32_e32 vcc, v24, v68
	s_add_i32 s18, s11, s4
	s_waitcnt lgkmcnt(0)
	v_add_f32_e32 v22, v22, v23
	v_cndmask_b32_e32 v24, v122, v24, vcc
	v_lshlrev_b32_e32 v24, 2, v24
	s_nop 1
	v_mov_b32_dpp v23, v22 quad_perm:[2,3,0,1] row_mask:0xf bank_mask:0xf
	v_xor_b32_e32 v24, 4, v122
	v_cmp_lt_i32_e32 vcc, v24, v68
	s_waitcnt lgkmcnt(0)
	v_add_f32_e32 v22, v22, v23
	v_cndmask_b32_e32 v24, v122, v24, vcc
	v_lshlrev_b32_e32 v24, 2, v24
	s_nop 1
	v_mov_b32_dpp v23, v22 row_half_mirror row_mask:0xf bank_mask:0xf
	v_xor_b32_e32 v24, 8, v122
	v_cmp_lt_i32_e32 vcc, v24, v68
	s_waitcnt lgkmcnt(0)
	v_add_f32_e32 v22, v22, v23
	v_cndmask_b32_e32 v24, v122, v24, vcc
	v_lshlrev_b32_e32 v24, 2, v24
	s_nop 1
	v_mov_b32_dpp v23, v22 row_mirror row_mask:0xf bank_mask:0xf
	s_waitcnt lgkmcnt(0)
	v_add_f32_e32 v22, v22, v23
	v_add_f32_e32 v22, 0x358637bd, v22
	v_rsq_f32_e32 v22, v22
	s_nop 0
	v_cndmask_b32_e64 v22, 1.0, v22, s[0:1]
	v_readlane_b32 s0, v251, 30
	v_mul_f32_e32 v23, 0x3db504f3, v22
	v_readlane_b32 s1, v251, 31
	s_andn2_b64 vcc, exec, s[0:1]
	s_nop 0
	v_cndmask_b32_e64 v26, v22, v23, s[0:1]
	v_pk_mul_f32 v[24:25], v[18:19], v[26:27] op_sel_hi:[1,0]
	v_pk_mul_f32 v[22:23], v[32:33], v[26:27] op_sel_hi:[1,0]
	v_pk_mul_f32 v[20:21], v[20:21], v[26:27] op_sel_hi:[1,0]
	v_pk_mul_f32 v[18:19], v[28:29], v[26:27] op_sel_hi:[1,0]
	v_and_b32_e32 v26, 63, v34
	v_mul_u32_u24_e32 v27, 0x110, v26
	v_cvt_pk_bf16_f32 v28, v24, v25
	v_cvt_pk_bf16_f32 v29, v22, v23
	v_cvt_pk_bf16_f32 v30, v20, v21
	v_cvt_pk_bf16_f32 v31, v18, v19
	v_add3_u32 v27, s18, v27, v114
	ds_write_b128 v27, v[28:31] offset:28672
	s_cbranch_vccnz .LBB0_1079
	v_add_u32_e32 v27, s91, v128
	v_lshl_add_u32 v27, v27, 2, s2
	ds_read_b32 v28, v27 offset:1072
	s_waitcnt lgkmcnt(0)
	v_pk_mul_f32 v[22:23], v[22:23], v[28:29] op_sel_hi:[1,0]
	v_pk_mul_f32 v[18:19], v[18:19], v[28:29] op_sel_hi:[1,0]
	v_pk_mul_f32 v[24:25], v[24:25], v[28:29] op_sel_hi:[1,0]
	v_pk_mul_f32 v[30:31], v[20:21], v[28:29] op_sel_hi:[1,0]
	v_cvt_pk_bf16_f32 v21, v22, v23
	v_cvt_pk_bf16_f32 v23, v18, v19
	v_mul_u32_u24_e32 v18, 0x108, v26
	v_mov_b32_e32 v19, v115
	v_cvt_pk_bf16_f32 v20, v24, v25
	v_cvt_pk_bf16_f32 v22, v30, v31
	v_lshl_add_u64 v[18:19], v[116:117], 0, v[18:19]
	global_store_dwordx4 v[18:19], v[20:23], off
; #define GAS __attribute__((address_space(1)))
; #define LAS __attribute__((address_space(3)))
; __device__ __forceinline__ float siluf_(float x) { return x * __builtin_amdgcn_rcpf(1.0f + __builtin_amdgcn_exp2f(-1.4426950408889634f * x)); }
; __device__ __forceinline__ float sum16(float v) {
; #pragma unroll
;     for (int o = 1; o < 16; o <<= 1) v += __shfl_xor(v, o);
;     return v;
; }
; template <int NW>
; __device__ __forceinline__ void gp_stage0_compute(Frame& F, int cidx, const LAS float* Gs, LAS unsigned char* tiles, int w, int lane, const GpTaps<NW>& tp) {
;     ...
;             float acc[8];
; #pragma unroll
;             for (int e = 0; e < 8; ++e) acc[e] = 0.f;
; #pragma unroll
;             for (int tap = 0; tap < 4; ++tap) {
;                 const v4u xv = tp.xw[it][tap];
;                 const LAS float* cw = cwl + (type * 4 + tap) * 128 + c * 8;
;                 const f32x4 c0 = *(const LAS f32x4*)cw, c1 = *(const LAS f32x4*)(cw + 4);
;                 acc[0] += bflo(xv.x) * c0.x; acc[1] += bfhi(xv.x) * c0.y; acc[2] += bflo(xv.y) * c0.z; acc[3] += bfhi(xv.y) * c0.w;
;                 acc[4] += bflo(xv.z) * c1.x; acc[5] += bfhi(xv.z) * c1.y; acc[6] += bflo(xv.w) * c1.z; acc[7] += bfhi(xv.w) * c1.w;
;             }
;             float ss = 0.f;
; #pragma unroll
;             for (int e = 0; e < 8; ++e) { acc[e] = siluf_(acc[e]); ss += acc[e] * acc[e]; }
;             ss = sum16(ss);
;             float sc = 1.0f;
;             if (type < 2) sc = __builtin_amdgcn_rsqf(ss + EPS);
;             if (type == 0) sc *= 0.08838834764831845f;
; #pragma unroll
;             for (int e = 0; e < 8; ++e) acc[e] *= sc;
;             const v4u o = {gcvtpk(acc[0], acc[1]), gcvtpk(acc[2], acc[3]), gcvtpk(acc[4], acc[5]), gcvtpk(acc[6], acc[7])};
;             *(LAS v4u*)(tiles + type * GP_TILE + i * GP_TS + c * 16) = o;
;             if (type == 0) {
;                 const float e_ = Gs[128 + i];
;                 v2u w0 = {gcvtpk(acc[0] * e_, acc[1] * e_), gcvtpk(acc[2] * e_, acc[3] * e_)}, w1 = {gcvtpk(acc[4] * e_, acc[5] * e_), gcvtpk(acc[6] * e_, acc[7] * e_)};
;                 *(GAS v2u*)(CH + CH_Q + i * RS_W + c * 16) = w0; *(GAS v2u*)(CH + CH_Q + i * RS_W + c * 16 + 8) = w1;
;             }
.LBB0_1079:
	s_or_b64 exec, exec, s[42:43]
	v_readlane_b32 s0, v251, 35
	s_waitcnt vmcnt(4)
	s_nop 0
	v_or_b32_e32 v18, s0, v128
	v_cmp_gt_i32_e32 vcc, s26, v18
	s_and_saveexec_b64 s[36:37], vcc
	s_cbranch_execz .LBB0_1082
	v_readlane_b32 s0, v251, 32
	s_waitcnt vmcnt(3)
	v_cndmask_b32_e64 v19, v10, 0, s[28:29]
	v_cndmask_b32_e64 v42, v11, 0, s[28:29]
	v_add_u32_e32 v36, s0, v129
	v_cndmask_b32_e64 v43, v12, 0, s[28:29]
	v_cndmask_b32_e64 v41, v13, 0, s[28:29]
	s_waitcnt vmcnt(2)
	v_cndmask_b32_e64 v44, v6, 0, s[30:31]
	v_cndmask_b32_e64 v45, v7, 0, s[30:31]
	v_cndmask_b32_e64 v46, v8, 0, s[30:31]
	v_cndmask_b32_e64 v47, v9, 0, s[30:31]
	s_waitcnt vmcnt(1)
	v_cndmask_b32_e64 v48, v14, 0, s[34:35]
	v_cndmask_b32_e64 v49, v15, 0, s[34:35]
	v_cndmask_b32_e64 v50, v16, 0, s[34:35]
	v_cndmask_b32_e64 v51, v17, 0, s[34:35]
	ds_read_b128 v[6:9], v36
	ds_read_b128 v[10:13], v36 offset:16
	ds_read_b128 v[14:17], v36 offset:512
	ds_read_b128 v[20:23], v36 offset:528
	ds_read_b128 v[24:27], v36 offset:1024
	ds_read_b128 v[28:31], v36 offset:1040
	ds_read_b128 v[32:35], v36 offset:1536
	ds_read_b128 v[36:39], v36 offset:1552
	v_and_b32_e32 v40, 64, v122
	v_add_u32_e32 v52, 64, v40
	v_lshlrev_b32_e32 v40, 16, v41
	v_and_b32_e32 v41, 0xffff0000, v41
	s_waitcnt lgkmcnt(6)
	v_pk_fma_f32 v[12:13], v[12:13], v[40:41], 0 op_sel_hi:[1,1,0]
	v_lshlrev_b32_e32 v40, 16, v47
	v_and_b32_e32 v41, 0xffff0000, v47
	s_waitcnt lgkmcnt(4)
	v_pk_fma_f32 v[12:13], v[22:23], v[40:41], v[12:13]
	v_lshlrev_b32_e32 v22, 16, v51
	v_and_b32_e32 v23, 0xffff0000, v51
	s_waitcnt lgkmcnt(2)
	v_pk_fma_f32 v[12:13], v[30:31], v[22:23], v[12:13]
	s_waitcnt vmcnt(0)
	v_lshlrev_b32_e32 v22, 16, v5
	v_and_b32_e32 v23, 0xffff0000, v5
	s_waitcnt lgkmcnt(0)
	v_pk_fma_f32 v[12:13], v[38:39], v[22:23], v[12:13]
	v_xor_b32_e32 v30, 1, v122
	v_mul_f32_e32 v5, 0xbfb8aa3b, v12
	v_exp_f32_e32 v5, v5
	v_mul_f32_e32 v22, 0xbfb8aa3b, v13
	v_exp_f32_e32 v23, v22
	v_cmp_lt_i32_e32 vcc, v30, v52
	v_add_f32_e32 v5, 1.0, v5
	v_rcp_f32_e32 v22, v5
	v_add_f32_e32 v5, 1.0, v23
	v_rcp_f32_e32 v23, v5
	v_cndmask_b32_e32 v5, v122, v30, vcc
	v_lshlrev_b32_e32 v30, 2, v5
	v_readlane_b32 s0, v251, 33
	v_pk_mul_f32 v[12:13], v[12:13], v[22:23]
	v_lshlrev_b32_e32 v22, 16, v43
	v_and_b32_e32 v23, 0xffff0000, v43
	v_pk_fma_f32 v[10:11], v[10:11], v[22:23], 0 op_sel_hi:[1,1,0]
	v_lshlrev_b32_e32 v22, 16, v46
	v_and_b32_e32 v23, 0xffff0000, v46
	v_pk_fma_f32 v[10:11], v[20:21], v[22:23], v[10:11]
	v_lshlrev_b32_e32 v20, 16, v50
	v_and_b32_e32 v21, 0xffff0000, v50
	v_pk_fma_f32 v[10:11], v[28:29], v[20:21], v[10:11]
	v_lshlrev_b32_e32 v20, 16, v4
	v_and_b32_e32 v21, 0xffff0000, v4
	v_pk_fma_f32 v[4:5], v[36:37], v[20:21], v[10:11]
	v_lshlrev_b32_e32 v22, 16, v42
	v_mul_f32_e32 v10, 0xbfb8aa3b, v4
	v_exp_f32_e32 v20, v10
	v_mul_f32_e32 v10, 0xbfb8aa3b, v5
	v_exp_f32_e32 v21, v10
	v_and_b32_e32 v23, 0xffff0000, v42
	v_pk_fma_f32 v[8:9], v[8:9], v[22:23], 0 op_sel_hi:[1,1,0]
	v_lshlrev_b32_e32 v22, 16, v45
	v_and_b32_e32 v23, 0xffff0000, v45
	v_add_f32_e32 v20, 1.0, v20
	v_add_f32_e32 v21, 1.0, v21
	v_pk_fma_f32 v[8:9], v[16:17], v[22:23], v[8:9]
	v_lshlrev_b32_e32 v16, 16, v49
	v_and_b32_e32 v17, 0xffff0000, v49
	v_rcp_f32_e32 v20, v20
	v_rcp_f32_e32 v21, v21
	v_pk_fma_f32 v[8:9], v[26:27], v[16:17], v[8:9]
	v_lshlrev_b32_e32 v16, 16, v3
	v_and_b32_e32 v17, 0xffff0000, v3
	v_pk_fma_f32 v[8:9], v[34:35], v[16:17], v[8:9]
	v_pk_mul_f32 v[4:5], v[4:5], v[20:21]
	v_mul_f32_e32 v3, 0xbfb8aa3b, v8
	v_exp_f32_e32 v3, v3
	v_lshlrev_b32_e32 v20, 16, v19
	v_and_b32_e32 v21, 0xffff0000, v19
	v_pk_fma_f32 v[6:7], v[6:7], v[20:21], 0 op_sel_hi:[1,1,0]
	v_lshlrev_b32_e32 v20, 16, v44
	v_and_b32_e32 v21, 0xffff0000, v44
	v_pk_fma_f32 v[6:7], v[14:15], v[20:21], v[6:7]
	v_lshlrev_b32_e32 v14, 16, v48
	v_and_b32_e32 v15, 0xffff0000, v48
	v_mul_f32_e32 v16, 0xbfb8aa3b, v9
	v_add_f32_e32 v3, 1.0, v3
	v_pk_fma_f32 v[6:7], v[24:25], v[14:15], v[6:7]
	v_lshlrev_b32_e32 v14, 16, v2
	v_and_b32_e32 v15, 0xffff0000, v2
	v_exp_f32_e32 v17, v16
	v_rcp_f32_e32 v16, v3
	v_pk_fma_f32 v[2:3], v[32:33], v[14:15], v[6:7]
	v_pk_mul_f32 v[14:15], v[4:5], v[4:5]
	v_mul_f32_e32 v6, 0xbfb8aa3b, v2
	v_mul_f32_e32 v7, 0xbfb8aa3b, v3
	v_exp_f32_e32 v6, v6
	v_exp_f32_e32 v7, v7
	v_add_f32_e32 v17, 1.0, v17
	v_rcp_f32_e32 v17, v17
	v_add_f32_e32 v6, 1.0, v6
	v_add_f32_e32 v7, 1.0, v7
	v_rcp_f32_e32 v6, v6
	v_rcp_f32_e32 v7, v7
	v_pk_mul_f32 v[16:17], v[8:9], v[16:17]
	v_pk_mul_f32 v[10:11], v[12:13], v[12:13]
	v_pk_mul_f32 v[8:9], v[16:17], v[16:17]
	v_pk_mul_f32 v[2:3], v[2:3], v[6:7]
	v_readlane_b32 s1, v251, 34
	v_pk_mul_f32 v[6:7], v[2:3], v[2:3]
	v_readlane_b32 s4, v250, 12
	v_add_f32_e32 v6, v6, v7
	v_add_f32_e32 v6, v8, v6
	v_add_f32_e32 v6, v9, v6
	v_add_f32_e32 v6, v14, v6
	v_add_f32_e32 v6, v15, v6
	v_add_f32_e32 v6, v10, v6
	v_add_f32_e32 v6, v11, v6
	s_nop 1
	v_mov_b32_dpp v7, v6 quad_perm:[1,0,3,2] row_mask:0xf bank_mask:0xf
	v_xor_b32_e32 v8, 2, v122
	v_cmp_lt_i32_e32 vcc, v8, v52
	s_add_i32 s11, s11, s4
	s_waitcnt lgkmcnt(0)
	v_add_f32_e32 v6, v6, v7
	v_cndmask_b32_e32 v8, v122, v8, vcc
	v_lshlrev_b32_e32 v8, 2, v8
	s_nop 1
	v_mov_b32_dpp v7, v6 quad_perm:[2,3,0,1] row_mask:0xf bank_mask:0xf
	v_xor_b32_e32 v8, 4, v122
	v_cmp_lt_i32_e32 vcc, v8, v52
	s_waitcnt lgkmcnt(0)
	v_add_f32_e32 v6, v6, v7
	v_cndmask_b32_e32 v8, v122, v8, vcc
	v_lshlrev_b32_e32 v8, 2, v8
	s_nop 1
	v_mov_b32_dpp v7, v6 row_half_mirror row_mask:0xf bank_mask:0xf
	v_xor_b32_e32 v8, 8, v122
	v_cmp_lt_i32_e32 vcc, v8, v52
	s_waitcnt lgkmcnt(0)
	v_add_f32_e32 v6, v6, v7
	v_cndmask_b32_e32 v8, v122, v8, vcc
	v_lshlrev_b32_e32 v8, 2, v8
	s_nop 1
	v_mov_b32_dpp v7, v6 row_mirror row_mask:0xf bank_mask:0xf
	s_waitcnt lgkmcnt(0)
	v_add_f32_e32 v6, v6, v7
	v_add_f32_e32 v6, 0x358637bd, v6
	v_rsq_f32_e32 v6, v6
	s_nop 0
	v_cndmask_b32_e64 v6, 1.0, v6, s[0:1]
	v_readlane_b32 s0, v251, 36
	v_mul_f32_e32 v7, 0x3db504f3, v6
	v_readlane_b32 s1, v251, 37
	s_andn2_b64 vcc, exec, s[0:1]
	s_nop 0
	v_cndmask_b32_e64 v10, v6, v7, s[0:1]
	v_pk_mul_f32 v[8:9], v[2:3], v[10:11] op_sel_hi:[1,0]
	v_pk_mul_f32 v[6:7], v[16:17], v[10:11] op_sel_hi:[1,0]
	v_pk_mul_f32 v[4:5], v[4:5], v[10:11] op_sel_hi:[1,0]
	v_pk_mul_f32 v[2:3], v[12:13], v[10:11] op_sel_hi:[1,0]
	v_and_b32_e32 v10, 63, v18
	v_mul_u32_u24_e32 v11, 0x110, v10
	v_cvt_pk_bf16_f32 v12, v8, v9
	v_cvt_pk_bf16_f32 v13, v6, v7
	v_cvt_pk_bf16_f32 v14, v4, v5
	v_cvt_pk_bf16_f32 v15, v2, v3
	v_add3_u32 v11, s11, v11, v114
	ds_write_b128 v11, v[12:15] offset:28672
	s_cbranch_vccnz .LBB0_1082
; #define GAS __attribute__((address_space(1)))
; __device__ __forceinline__ unsigned gcvtpk(float lo, float hi) { gf32x2 v = {lo, hi}; gbf16x2 b = __builtin_convertvector(v, gbf16x2); return __builtin_bit_cast(unsigned, b); }
; template <int NW>
; __device__ __forceinline__ void gp_stage0_compute(Frame& F, int cidx, const LAS float* Gs, LAS unsigned char* tiles, int w, int lane, const GpTaps<NW>& tp) {
;     ...
;             if (type == 0) {
;                 const float e_ = Gs[128 + i];
;                 v2u w0 = {gcvtpk(acc[0] * e_, acc[1] * e_), gcvtpk(acc[2] * e_, acc[3] * e_)}, w1 = {gcvtpk(acc[4] * e_, acc[5] * e_), gcvtpk(acc[6] * e_, acc[7] * e_)};
;                 *(GAS v2u*)(CH + CH_Q + i * RS_W + c * 16) = w0; *(GAS v2u*)(CH + CH_Q + i * RS_W + c * 16 + 8) = w1;
	v_add_u32_e32 v11, s91, v128
	v_lshl_add_u32 v11, v11, 2, s2
	ds_read_b32 v12, v11 offset:1184
	v_mul_u32_u24_e32 v114, 0x108, v10
	s_waitcnt lgkmcnt(0)
	v_pk_mul_f32 v[8:9], v[8:9], v[12:13] op_sel_hi:[1,0]
	v_pk_mul_f32 v[6:7], v[6:7], v[12:13] op_sel_hi:[1,0]
	v_pk_mul_f32 v[14:15], v[4:5], v[12:13] op_sel_hi:[1,0]
	v_pk_mul_f32 v[2:3], v[2:3], v[12:13] op_sel_hi:[1,0]
	v_cvt_pk_bf16_f32 v4, v8, v9
	v_cvt_pk_bf16_f32 v5, v6, v7
	v_cvt_pk_bf16_f32 v6, v14, v15
	v_cvt_pk_bf16_f32 v7, v2, v3
	v_lshl_add_u64 v[2:3], v[116:117], 0, v[114:115]
	global_store_dwordx4 v[2:3], v[4:7], off

; #define SBAR() __builtin_amdgcn_sched_barrier(0)
; __device__ __forceinline__ int crow(int r, int hi) { return (r & 3) + 8 * (r >> 2) + 4 * hi; }
; __device__ __forceinline__ unsigned cvtpk(float lo, float hi) { unsigned r; asm volatile("v_cvt_pk_bf16_f32 %0, %1, %2" : "=v"(r) : "v"(lo), "v"(hi)); return r; }
; #define SEAM_K0() do { VMWN(NQL); SWRITE_HK(0); SBAR(); } while (0)
; template <int PQ, int PO>
; __device__ __forceinline__ void fox_block(const Bases& Bs, const BlockRef& cur, const BlockRef& nxt, char* lds, Seam& S) {
;     ...
;     SBAR(); SEAM_K0();
;     if (hi == 0) li_l[r32] = l_reg; asm volatile("s_waitcnt lgkmcnt(0)" ::: "memory");
;     float rli[16];
; #pragma unroll
;     for (int r = 0; r < 16; ++r) rli[r] = __builtin_amdgcn_rcpf(li_l[crow(r, hi)]);
;     bf16* Ow = Bs.O + cur.o + (size_t)(wid * QBLK) * PO;
; #pragma unroll
;     for (int r = 0; r < 16; ++r) { const int orow = crow(r, hi);
; #pragma unroll
;         for (int d0 = 0; d0 < 4; ++d0) { const float v = o[d0][r] * rli[r];
;             const float vn = __shfl_xor(v, 1);
;             if ((r32 & 1) == 0) *(unsigned*)(Ow + (unsigned)(orow * PO + d0 * 32 + r32)) = cvtpk(v, vn); } }
.LBB0_1496:
	s_mov_b32 s97, s75
	s_waitcnt vmcnt(8)
	s_waitcnt vmcnt(0)
	ds_write_b128 v214, v[122:125] offset:32768
	ds_write_b128 v214, v[126:129] offset:40960
	s_and_saveexec_b64 s[6:7], s[38:39]
	ds_write_b32 v217, v4
	s_or_b64 exec, exec, s[6:7]
	s_waitcnt lgkmcnt(0)
	ds_read_b128 v[82:85], v216
	ds_read_b128 v[12:15], v216 offset:32
	v_and_b32_e32 v16, 64, v210
	v_xor_b32_e32 v3, 1, v210
	v_add_u32_e32 v16, 64, v16
	s_waitcnt lgkmcnt(0)
	v_rcp_f32_e32 v17, v82
	s_add_i32 s0, s0, s1
	v_cmp_lt_i32_e32 vcc, v3, v16
	s_lshl_b32 s0, s0, 12
	s_or_b32 s74, s0, s87
	v_cndmask_b32_e32 v3, v210, v3, vcc
	v_lshlrev_b32_e32 v3, 2, v3
	v_mul_f32_e32 v66, v66, v17
	ds_read_b128 v[8:11], v216 offset:64
	ds_read_b128 v[4:7], v216 offset:96
	s_lshl_b64 s[0:1], s[74:75], 1
	s_nop 1
	v_mov_b32_dpp v82, v66 quad_perm:[1,0,3,2] row_mask:0xf bank_mask:0xf
	s_add_u32 s2, s90, s0
	s_addc_u32 s7, s91, s1
	s_lshl_b64 s[0:1], s[96:97], 13
	s_add_u32 s6, s2, s0
	s_addc_u32 s7, s7, s1
	v_lshlrev_b32_e32 v16, 1, v182
	s_and_saveexec_b64 s[8:9], s[4:5]
	s_cbranch_execz .LBB0_1500
	s_waitcnt lgkmcnt(0)
	v_cvt_pk_bf16_f32 v66, v66, v82
	global_store_dword v16, v66, s[6:7]
.LBB0_1500:
	s_or_b64 exec, exec, s[8:9]
	v_mul_f32_e32 v50, v50, v17
	s_nop 1
	v_mov_b32_dpp v66, v50 quad_perm:[1,0,3,2] row_mask:0xf bank_mask:0xf
	s_and_saveexec_b64 s[8:9], s[4:5]
	s_cbranch_execz .LBB0_1502
	s_waitcnt lgkmcnt(0)
	v_cvt_pk_bf16_f32 v50, v50, v66
	global_store_dword v16, v50, s[6:7] offset:64
.LBB0_1502:
	s_or_b64 exec, exec, s[8:9]
	v_mul_f32_e32 v34, v34, v17
	s_nop 1
	v_mov_b32_dpp v50, v34 quad_perm:[1,0,3,2] row_mask:0xf bank_mask:0xf
	s_and_saveexec_b64 s[8:9], s[4:5]
	s_cbranch_execz .LBB0_1504
	s_waitcnt lgkmcnt(0)
	v_cvt_pk_bf16_f32 v34, v34, v50
	global_store_dword v16, v34, s[6:7] offset:128
.LBB0_1504:
	s_or_b64 exec, exec, s[8:9]
	v_mul_f32_e32 v17, v18, v17
	s_nop 1
	v_mov_b32_dpp v18, v17 quad_perm:[1,0,3,2] row_mask:0xf bank_mask:0xf
	s_and_saveexec_b64 s[8:9], s[4:5]
	s_cbranch_execz .LBB0_1506
	s_waitcnt lgkmcnt(0)
	v_cvt_pk_bf16_f32 v17, v17, v18
	global_store_dword v16, v17, s[6:7] offset:192
.LBB0_1506:
	s_or_b64 exec, exec, s[8:9]
	s_waitcnt lgkmcnt(0)
	v_rcp_f32_e32 v18, v83
	s_nop 0
	v_mul_f32_e32 v34, v67, v18
	s_nop 1
	v_mov_b32_dpp v50, v34 quad_perm:[1,0,3,2] row_mask:0xf bank_mask:0xf
	s_and_saveexec_b64 s[8:9], s[4:5]
	s_cbranch_execz .LBB0_1508
	v_mov_b32_e32 v17, v2
	v_lshl_add_u64 v[66:67], s[6:7], 0, v[16:17]
	v_add_co_u32_e32 v66, vcc, 0x2000, v66
	s_waitcnt lgkmcnt(0)
	v_cvt_pk_bf16_f32 v17, v34, v50
	s_nop 0
	v_addc_co_u32_e32 v67, vcc, 0, v67, vcc
	global_store_dword v[66:67], v17, off
.LBB0_1508:
	s_or_b64 exec, exec, s[8:9]
	v_mul_f32_e32 v34, v51, v18
	s_waitcnt lgkmcnt(0)
	s_nop 1
	v_mov_b32_dpp v50, v34 quad_perm:[1,0,3,2] row_mask:0xf bank_mask:0xf
	s_and_saveexec_b64 s[8:9], s[4:5]
	s_cbranch_execz .LBB0_1510
	v_mov_b32_e32 v17, v2
	v_lshl_add_u64 v[66:67], s[6:7], 0, v[16:17]
	s_waitcnt lgkmcnt(0)
	v_cvt_pk_bf16_f32 v17, v34, v50
	v_add_co_u32_e32 v50, vcc, 0x2000, v66
	s_nop 1
	v_addc_co_u32_e32 v51, vcc, 0, v67, vcc
	global_store_dword v[50:51], v17, off offset:64
.LBB0_1510:
	s_or_b64 exec, exec, s[8:9]
	v_mul_f32_e32 v34, v35, v18
	s_nop 1
	v_mov_b32_dpp v35, v34 quad_perm:[1,0,3,2] row_mask:0xf bank_mask:0xf
	s_and_saveexec_b64 s[8:9], s[4:5]
	s_cbranch_execz .LBB0_1512
	v_mov_b32_e32 v17, v2
	s_waitcnt lgkmcnt(1)
	v_lshl_add_u64 v[50:51], s[6:7], 0, v[16:17]
	s_waitcnt lgkmcnt(0)
	v_cvt_pk_bf16_f32 v17, v34, v35
	v_add_co_u32_e32 v34, vcc, 0x2000, v50
	s_nop 1
	v_addc_co_u32_e32 v35, vcc, 0, v51, vcc
	global_store_dword v[34:35], v17, off offset:128
.LBB0_1512:
	s_or_b64 exec, exec, s[8:9]
	v_mul_f32_e32 v18, v19, v18
	s_nop 1
	v_mov_b32_dpp v19, v18 quad_perm:[1,0,3,2] row_mask:0xf bank_mask:0xf
	s_and_saveexec_b64 s[8:9], s[4:5]
	s_cbranch_execz .LBB0_1514
	v_mov_b32_e32 v17, v2
	s_waitcnt lgkmcnt(1)
	v_lshl_add_u64 v[34:35], s[6:7], 0, v[16:17]
	s_waitcnt lgkmcnt(0)
	v_cvt_pk_bf16_f32 v17, v18, v19
	v_add_co_u32_e32 v18, vcc, 0x2000, v34
	s_nop 1
	v_addc_co_u32_e32 v19, vcc, 0, v35, vcc
	global_store_dword v[18:19], v17, off offset:192
.LBB0_1514:
	s_or_b64 exec, exec, s[8:9]
	v_rcp_f32_e32 v18, v84
	s_waitcnt lgkmcnt(0)
	v_mul_f32_e32 v19, v68, v18
	s_nop 1
	v_mov_b32_dpp v34, v19 quad_perm:[1,0,3,2] row_mask:0xf bank_mask:0xf
	s_and_saveexec_b64 s[8:9], s[4:5]
	s_cbranch_execz .LBB0_1516
	v_mov_b32_e32 v17, v2
	v_lshl_add_u64 v[50:51], s[6:7], 0, v[16:17]
	s_waitcnt lgkmcnt(0)
	v_cvt_pk_bf16_f32 v17, v19, v34
	v_add_co_u32_e32 v34, vcc, 0x4000, v50
	s_nop 1
	v_addc_co_u32_e32 v35, vcc, 0, v51, vcc
	global_store_dword v[34:35], v17, off
.LBB0_1516:
	s_or_b64 exec, exec, s[8:9]
	v_mul_f32_e32 v19, v52, v18
	s_waitcnt lgkmcnt(0)
	s_nop 1
	v_mov_b32_dpp v34, v19 quad_perm:[1,0,3,2] row_mask:0xf bank_mask:0xf
	s_and_saveexec_b64 s[8:9], s[4:5]
	s_cbranch_execz .LBB0_1518
	v_mov_b32_e32 v17, v2
	v_lshl_add_u64 v[50:51], s[6:7], 0, v[16:17]
	s_waitcnt lgkmcnt(0)
	v_cvt_pk_bf16_f32 v17, v19, v34
	v_add_co_u32_e32 v34, vcc, 0x4000, v50
	s_nop 1
	v_addc_co_u32_e32 v35, vcc, 0, v51, vcc
	global_store_dword v[34:35], v17, off offset:64
.LBB0_1518:
	s_or_b64 exec, exec, s[8:9]
	v_mul_f32_e32 v19, v36, v18
	s_waitcnt lgkmcnt(0)
	s_nop 1
	v_mov_b32_dpp v34, v19 quad_perm:[1,0,3,2] row_mask:0xf bank_mask:0xf
	s_and_saveexec_b64 s[8:9], s[4:5]
	s_cbranch_execz .LBB0_1520
	v_mov_b32_e32 v17, v2
	v_lshl_add_u64 v[50:51], s[6:7], 0, v[16:17]
	s_waitcnt lgkmcnt(0)
	v_cvt_pk_bf16_f32 v17, v19, v34
	v_add_co_u32_e32 v34, vcc, 0x4000, v50
	s_nop 1
	v_addc_co_u32_e32 v35, vcc, 0, v51, vcc
	global_store_dword v[34:35], v17, off offset:128
; __device__ __forceinline__ int crow(int r, int hi) { return (r & 3) + 8 * (r >> 2) + 4 * hi; }
; __device__ __forceinline__ unsigned cvtpk(float lo, float hi) { unsigned r; asm volatile("v_cvt_pk_bf16_f32 %0, %1, %2" : "=v"(r) : "v"(lo), "v"(hi)); return r; }
; template <int PQ, int PO>
; __device__ __forceinline__ void fox_block(const Bases& Bs, const BlockRef& cur, const BlockRef& nxt, char* lds, Seam& S) {
;     ...
;     float rli[16];
; #pragma unroll
;     for (int r = 0; r < 16; ++r) rli[r] = __builtin_amdgcn_rcpf(li_l[crow(r, hi)]);
;     bf16* Ow = Bs.O + cur.o + (size_t)(wid * QBLK) * PO;
; #pragma unroll
;     for (int r = 0; r < 16; ++r) { const int orow = crow(r, hi);
; #pragma unroll
;         for (int d0 = 0; d0 < 4; ++d0) { const float v = o[d0][r] * rli[r];
;             const float vn = __shfl_xor(v, 1);
;             if ((r32 & 1) == 0) *(unsigned*)(Ow + (unsigned)(orow * PO + d0 * 32 + r32)) = cvtpk(v, vn); } }
.LBB0_1520:
	s_or_b64 exec, exec, s[8:9]
	v_mul_f32_e32 v18, v20, v18
	s_nop 1
	v_mov_b32_dpp v19, v18 quad_perm:[1,0,3,2] row_mask:0xf bank_mask:0xf
	s_and_saveexec_b64 s[8:9], s[4:5]
	s_cbranch_execz .LBB0_1522
	v_mov_b32_e32 v17, v2
	s_waitcnt lgkmcnt(1)
	v_lshl_add_u64 v[34:35], s[6:7], 0, v[16:17]
	s_waitcnt lgkmcnt(0)
	v_cvt_pk_bf16_f32 v17, v18, v19
	v_add_co_u32_e32 v18, vcc, 0x4000, v34
	s_nop 1
	v_addc_co_u32_e32 v19, vcc, 0, v35, vcc
	global_store_dword v[18:19], v17, off offset:192
.LBB0_1522:
	s_or_b64 exec, exec, s[8:9]
	v_rcp_f32_e32 v18, v85
	s_waitcnt lgkmcnt(0)
	v_mul_f32_e32 v19, v69, v18
	s_nop 1
	v_mov_b32_dpp v20, v19 quad_perm:[1,0,3,2] row_mask:0xf bank_mask:0xf
	s_and_saveexec_b64 s[8:9], s[4:5]
	s_cbranch_execz .LBB0_1524
	v_mov_b32_e32 v17, v2
	v_lshl_add_u64 v[34:35], s[6:7], 0, v[16:17]
	v_add_co_u32_e32 v34, vcc, 0x6000, v34
	s_waitcnt lgkmcnt(0)
	v_cvt_pk_bf16_f32 v17, v19, v20
	s_nop 0
	v_addc_co_u32_e32 v35, vcc, 0, v35, vcc
	global_store_dword v[34:35], v17, off
.LBB0_1524:
	s_or_b64 exec, exec, s[8:9]
	v_mul_f32_e32 v19, v53, v18
	s_waitcnt lgkmcnt(0)
	s_nop 1
	v_mov_b32_dpp v20, v19 quad_perm:[1,0,3,2] row_mask:0xf bank_mask:0xf
	s_and_saveexec_b64 s[8:9], s[4:5]
	s_cbranch_execz .LBB0_1526
	v_mov_b32_e32 v17, v2
	v_lshl_add_u64 v[34:35], s[6:7], 0, v[16:17]
	v_add_co_u32_e32 v34, vcc, 0x6000, v34
	s_waitcnt lgkmcnt(0)
	v_cvt_pk_bf16_f32 v17, v19, v20
	s_nop 0
	v_addc_co_u32_e32 v35, vcc, 0, v35, vcc
	global_store_dword v[34:35], v17, off offset:64
.LBB0_1526:
	s_or_b64 exec, exec, s[8:9]
	v_mul_f32_e32 v19, v37, v18
	s_waitcnt lgkmcnt(0)
	s_nop 1
	v_mov_b32_dpp v20, v19 quad_perm:[1,0,3,2] row_mask:0xf bank_mask:0xf
	s_and_saveexec_b64 s[8:9], s[4:5]
	s_cbranch_execz .LBB0_1528
	v_mov_b32_e32 v17, v2
	v_lshl_add_u64 v[34:35], s[6:7], 0, v[16:17]
	v_add_co_u32_e32 v34, vcc, 0x6000, v34
	s_waitcnt lgkmcnt(0)
	v_cvt_pk_bf16_f32 v17, v19, v20
	s_nop 0
	v_addc_co_u32_e32 v35, vcc, 0, v35, vcc
	global_store_dword v[34:35], v17, off offset:128
.LBB0_1528:
	s_or_b64 exec, exec, s[8:9]
	v_mul_f32_e32 v18, v21, v18
	s_nop 1
	v_mov_b32_dpp v19, v18 quad_perm:[1,0,3,2] row_mask:0xf bank_mask:0xf
	s_and_saveexec_b64 s[8:9], s[4:5]
	s_cbranch_execz .LBB0_1530
	v_mov_b32_e32 v17, v2
	s_waitcnt lgkmcnt(1)
	v_lshl_add_u64 v[20:21], s[6:7], 0, v[16:17]
	s_waitcnt lgkmcnt(0)
	v_cvt_pk_bf16_f32 v17, v18, v19
	v_add_co_u32_e32 v18, vcc, 0x6000, v20
	s_nop 1
	v_addc_co_u32_e32 v19, vcc, 0, v21, vcc
	global_store_dword v[18:19], v17, off offset:192
.LBB0_1530:
	s_or_b64 exec, exec, s[8:9]
	v_rcp_f32_e32 v12, v12
	s_nop 0
	v_mul_f32_e32 v18, v70, v12
	s_waitcnt lgkmcnt(0)
	s_nop 1
	v_mov_b32_dpp v19, v18 quad_perm:[1,0,3,2] row_mask:0xf bank_mask:0xf
	s_and_saveexec_b64 s[8:9], s[4:5]
	s_cbranch_execz .LBB0_1532
	v_mov_b32_e32 v17, v2
	v_lshl_add_u64 v[20:21], s[6:7], 0, v[16:17]
	s_waitcnt lgkmcnt(0)
	v_cvt_pk_bf16_f32 v17, v18, v19
	v_add_co_u32_e32 v18, vcc, 0x10000, v20
	s_nop 1
	v_addc_co_u32_e32 v19, vcc, 0, v21, vcc
	global_store_dword v[18:19], v17, off
.LBB0_1532:
	s_or_b64 exec, exec, s[8:9]
	v_mul_f32_e32 v18, v54, v12
	s_waitcnt lgkmcnt(0)
	s_nop 1
	v_mov_b32_dpp v19, v18 quad_perm:[1,0,3,2] row_mask:0xf bank_mask:0xf
	s_and_saveexec_b64 s[8:9], s[4:5]
	s_cbranch_execz .LBB0_1534
	v_mov_b32_e32 v17, v2
	v_lshl_add_u64 v[20:21], s[6:7], 0, v[16:17]
	s_waitcnt lgkmcnt(0)
	v_cvt_pk_bf16_f32 v17, v18, v19
	v_add_co_u32_e32 v18, vcc, 0x10000, v20
	s_nop 1
	v_addc_co_u32_e32 v19, vcc, 0, v21, vcc
	global_store_dword v[18:19], v17, off offset:64
.LBB0_1534:
	s_or_b64 exec, exec, s[8:9]
	v_mul_f32_e32 v18, v38, v12
	s_waitcnt lgkmcnt(0)
	s_nop 1
	v_mov_b32_dpp v19, v18 quad_perm:[1,0,3,2] row_mask:0xf bank_mask:0xf
	s_and_saveexec_b64 s[8:9], s[4:5]
	s_cbranch_execz .LBB0_1536
	v_mov_b32_e32 v17, v2
	v_lshl_add_u64 v[20:21], s[6:7], 0, v[16:17]
	s_waitcnt lgkmcnt(0)
	v_cvt_pk_bf16_f32 v17, v18, v19
	v_add_co_u32_e32 v18, vcc, 0x10000, v20
	s_nop 1
	v_addc_co_u32_e32 v19, vcc, 0, v21, vcc
	global_store_dword v[18:19], v17, off offset:128
.LBB0_1536:
	s_or_b64 exec, exec, s[8:9]
	v_mul_f32_e32 v12, v22, v12
	s_nop 1
	v_mov_b32_dpp v18, v12 quad_perm:[1,0,3,2] row_mask:0xf bank_mask:0xf
	s_and_saveexec_b64 s[8:9], s[4:5]
	s_cbranch_execz .LBB0_1538
	v_mov_b32_e32 v17, v2
	v_lshl_add_u64 v[20:21], s[6:7], 0, v[16:17]
	s_waitcnt lgkmcnt(0)
	v_cvt_pk_bf16_f32 v12, v12, v18
	v_add_co_u32_e32 v18, vcc, 0x10000, v20
	s_nop 1
	v_addc_co_u32_e32 v19, vcc, 0, v21, vcc
	global_store_dword v[18:19], v12, off offset:192
.LBB0_1538:
	s_or_b64 exec, exec, s[8:9]
	v_rcp_f32_e32 v12, v13
	s_nop 0
	v_mul_f32_e32 v13, v71, v12
	s_waitcnt lgkmcnt(0)
	s_nop 1
	v_mov_b32_dpp v18, v13 quad_perm:[1,0,3,2] row_mask:0xf bank_mask:0xf
	s_and_saveexec_b64 s[8:9], s[4:5]
	s_cbranch_execz .LBB0_1540
	v_mov_b32_e32 v17, v2
	v_lshl_add_u64 v[20:21], s[6:7], 0, v[16:17]
	s_waitcnt lgkmcnt(0)
	v_cvt_pk_bf16_f32 v13, v13, v18
	v_add_co_u32_e32 v18, vcc, 0x12000, v20
	s_nop 1
	v_addc_co_u32_e32 v19, vcc, 0, v21, vcc
	global_store_dword v[18:19], v13, off
.LBB0_1540:
	s_or_b64 exec, exec, s[8:9]
	v_mul_f32_e32 v13, v55, v12
	s_waitcnt lgkmcnt(0)
	s_nop 1
	v_mov_b32_dpp v18, v13 quad_perm:[1,0,3,2] row_mask:0xf bank_mask:0xf
	s_and_saveexec_b64 s[8:9], s[4:5]
	s_cbranch_execz .LBB0_1542
	v_mov_b32_e32 v17, v2
	v_lshl_add_u64 v[20:21], s[6:7], 0, v[16:17]
	s_waitcnt lgkmcnt(0)
	v_cvt_pk_bf16_f32 v13, v13, v18
	v_add_co_u32_e32 v18, vcc, 0x12000, v20
	s_nop 1
	v_addc_co_u32_e32 v19, vcc, 0, v21, vcc
	global_store_dword v[18:19], v13, off offset:64
; __device__ __forceinline__ int crow(int r, int hi) { return (r & 3) + 8 * (r >> 2) + 4 * hi; }
; __device__ __forceinline__ unsigned cvtpk(float lo, float hi) { unsigned r; asm volatile("v_cvt_pk_bf16_f32 %0, %1, %2" : "=v"(r) : "v"(lo), "v"(hi)); return r; }
; template <int PQ, int PO>
; __device__ __forceinline__ void fox_block(const Bases& Bs, const BlockRef& cur, const BlockRef& nxt, char* lds, Seam& S) {
;     ...
;     float rli[16];
; #pragma unroll
;     for (int r = 0; r < 16; ++r) rli[r] = __builtin_amdgcn_rcpf(li_l[crow(r, hi)]);
;     bf16* Ow = Bs.O + cur.o + (size_t)(wid * QBLK) * PO;
; #pragma unroll
;     for (int r = 0; r < 16; ++r) { const int orow = crow(r, hi);
; #pragma unroll
;         for (int d0 = 0; d0 < 4; ++d0) { const float v = o[d0][r] * rli[r];
;             const float vn = __shfl_xor(v, 1);
;             if ((r32 & 1) == 0) *(unsigned*)(Ow + (unsigned)(orow * PO + d0 * 32 + r32)) = cvtpk(v, vn); } }
.LBB0_1542:
	s_or_b64 exec, exec, s[8:9]
	v_mul_f32_e32 v13, v39, v12
	s_waitcnt lgkmcnt(0)
	s_nop 1
	v_mov_b32_dpp v18, v13 quad_perm:[1,0,3,2] row_mask:0xf bank_mask:0xf
	s_and_saveexec_b64 s[8:9], s[4:5]
	s_cbranch_execz .LBB0_1544
	v_mov_b32_e32 v17, v2
	v_lshl_add_u64 v[20:21], s[6:7], 0, v[16:17]
	s_waitcnt lgkmcnt(0)
	v_cvt_pk_bf16_f32 v13, v13, v18
	v_add_co_u32_e32 v18, vcc, 0x12000, v20
	s_nop 1
	v_addc_co_u32_e32 v19, vcc, 0, v21, vcc
	global_store_dword v[18:19], v13, off offset:128
.LBB0_1544:
	s_or_b64 exec, exec, s[8:9]
	v_mul_f32_e32 v12, v23, v12
	s_nop 1
	v_mov_b32_dpp v13, v12 quad_perm:[1,0,3,2] row_mask:0xf bank_mask:0xf
	s_and_saveexec_b64 s[8:9], s[4:5]
	s_cbranch_execz .LBB0_1546
	v_mov_b32_e32 v17, v2
	s_waitcnt lgkmcnt(1)
	v_lshl_add_u64 v[18:19], s[6:7], 0, v[16:17]
	s_waitcnt lgkmcnt(0)
	v_cvt_pk_bf16_f32 v17, v12, v13
	v_add_co_u32_e32 v12, vcc, 0x12000, v18
	s_nop 1
	v_addc_co_u32_e32 v13, vcc, 0, v19, vcc
	global_store_dword v[12:13], v17, off offset:192
.LBB0_1546:
	s_or_b64 exec, exec, s[8:9]
	v_rcp_f32_e32 v12, v14
	s_waitcnt lgkmcnt(0)
	v_mul_f32_e32 v13, v72, v12
	s_nop 1
	v_mov_b32_dpp v14, v13 quad_perm:[1,0,3,2] row_mask:0xf bank_mask:0xf
	s_and_saveexec_b64 s[8:9], s[4:5]
	s_cbranch_execz .LBB0_1548
	v_mov_b32_e32 v17, v2
	v_lshl_add_u64 v[18:19], s[6:7], 0, v[16:17]
	v_add_co_u32_e32 v18, vcc, 0x14000, v18
	s_waitcnt lgkmcnt(0)
	v_cvt_pk_bf16_f32 v13, v13, v14
	s_nop 0
	v_addc_co_u32_e32 v19, vcc, 0, v19, vcc
	global_store_dword v[18:19], v13, off
.LBB0_1548:
	s_or_b64 exec, exec, s[8:9]
	v_mul_f32_e32 v13, v56, v12
	s_waitcnt lgkmcnt(0)
	s_nop 1
	v_mov_b32_dpp v14, v13 quad_perm:[1,0,3,2] row_mask:0xf bank_mask:0xf
	s_and_saveexec_b64 s[8:9], s[4:5]
	s_cbranch_execz .LBB0_1550
	v_mov_b32_e32 v17, v2
	v_lshl_add_u64 v[18:19], s[6:7], 0, v[16:17]
	v_add_co_u32_e32 v18, vcc, 0x14000, v18
	s_waitcnt lgkmcnt(0)
	v_cvt_pk_bf16_f32 v13, v13, v14
	s_nop 0
	v_addc_co_u32_e32 v19, vcc, 0, v19, vcc
	global_store_dword v[18:19], v13, off offset:64
.LBB0_1550:
	s_or_b64 exec, exec, s[8:9]
	v_mul_f32_e32 v13, v40, v12
	s_waitcnt lgkmcnt(0)
	s_nop 1
	v_mov_b32_dpp v14, v13 quad_perm:[1,0,3,2] row_mask:0xf bank_mask:0xf
	s_and_saveexec_b64 s[8:9], s[4:5]
	s_cbranch_execz .LBB0_1552
	v_mov_b32_e32 v17, v2
	v_lshl_add_u64 v[18:19], s[6:7], 0, v[16:17]
	v_add_co_u32_e32 v18, vcc, 0x14000, v18
	s_waitcnt lgkmcnt(0)
	v_cvt_pk_bf16_f32 v13, v13, v14
	s_nop 0
	v_addc_co_u32_e32 v19, vcc, 0, v19, vcc
	global_store_dword v[18:19], v13, off offset:128
.LBB0_1552:
	s_or_b64 exec, exec, s[8:9]
	v_mul_f32_e32 v12, v24, v12
	s_nop 1
	v_mov_b32_dpp v13, v12 quad_perm:[1,0,3,2] row_mask:0xf bank_mask:0xf
	s_and_saveexec_b64 s[8:9], s[4:5]
	s_cbranch_execz .LBB0_1554
	v_mov_b32_e32 v17, v2
	v_lshl_add_u64 v[18:19], s[6:7], 0, v[16:17]
	s_waitcnt lgkmcnt(0)
	v_cvt_pk_bf16_f32 v14, v12, v13
	v_add_co_u32_e32 v12, vcc, 0x14000, v18
	s_nop 1
	v_addc_co_u32_e32 v13, vcc, 0, v19, vcc
	global_store_dword v[12:13], v14, off offset:192
.LBB0_1554:
	s_or_b64 exec, exec, s[8:9]
	v_rcp_f32_e32 v12, v15
	s_waitcnt lgkmcnt(0)
	v_mul_f32_e32 v13, v73, v12
	s_nop 1
	v_mov_b32_dpp v14, v13 quad_perm:[1,0,3,2] row_mask:0xf bank_mask:0xf
	s_and_saveexec_b64 s[8:9], s[4:5]
	s_cbranch_execz .LBB0_1556
	v_mov_b32_e32 v17, v2
	v_lshl_add_u64 v[18:19], s[6:7], 0, v[16:17]
	s_waitcnt lgkmcnt(0)
	v_cvt_pk_bf16_f32 v13, v13, v14
	v_add_co_u32_e32 v14, vcc, 0x16000, v18
	s_nop 1
	v_addc_co_u32_e32 v15, vcc, 0, v19, vcc
	global_store_dword v[14:15], v13, off
.LBB0_1556:
	s_or_b64 exec, exec, s[8:9]
	v_mul_f32_e32 v13, v57, v12
	s_waitcnt lgkmcnt(0)
	s_nop 1
	v_mov_b32_dpp v14, v13 quad_perm:[1,0,3,2] row_mask:0xf bank_mask:0xf
	s_and_saveexec_b64 s[8:9], s[4:5]
	s_cbranch_execz .LBB0_1558
	v_mov_b32_e32 v17, v2
	v_lshl_add_u64 v[18:19], s[6:7], 0, v[16:17]
	s_waitcnt lgkmcnt(0)
	v_cvt_pk_bf16_f32 v13, v13, v14
	v_add_co_u32_e32 v14, vcc, 0x16000, v18
	s_nop 1
	v_addc_co_u32_e32 v15, vcc, 0, v19, vcc
	global_store_dword v[14:15], v13, off offset:64
.LBB0_1558:
	s_or_b64 exec, exec, s[8:9]
	v_mul_f32_e32 v13, v41, v12
	s_waitcnt lgkmcnt(0)
	s_nop 1
	v_mov_b32_dpp v14, v13 quad_perm:[1,0,3,2] row_mask:0xf bank_mask:0xf
	s_and_saveexec_b64 s[8:9], s[4:5]
	s_cbranch_execz .LBB0_1560
	v_mov_b32_e32 v17, v2
	v_lshl_add_u64 v[18:19], s[6:7], 0, v[16:17]
	s_waitcnt lgkmcnt(0)
	v_cvt_pk_bf16_f32 v13, v13, v14
	v_add_co_u32_e32 v14, vcc, 0x16000, v18
	s_nop 1
	v_addc_co_u32_e32 v15, vcc, 0, v19, vcc
	global_store_dword v[14:15], v13, off offset:128
.LBB0_1560:
	s_or_b64 exec, exec, s[8:9]
	v_mul_f32_e32 v12, v25, v12
	s_nop 1
	v_mov_b32_dpp v13, v12 quad_perm:[1,0,3,2] row_mask:0xf bank_mask:0xf
	s_and_saveexec_b64 s[8:9], s[4:5]
	s_cbranch_execz .LBB0_1562
	v_mov_b32_e32 v17, v2
	s_waitcnt lgkmcnt(1)
	v_lshl_add_u64 v[14:15], s[6:7], 0, v[16:17]
	s_waitcnt lgkmcnt(0)
	v_cvt_pk_bf16_f32 v17, v12, v13
	v_add_co_u32_e32 v12, vcc, 0x16000, v14
	s_nop 1
	v_addc_co_u32_e32 v13, vcc, 0, v15, vcc
	global_store_dword v[12:13], v17, off offset:192
.LBB0_1562:
	s_or_b64 exec, exec, s[8:9]
	v_rcp_f32_e32 v8, v8
	s_nop 0
	v_mul_f32_e32 v12, v74, v8
	s_waitcnt lgkmcnt(0)
	s_nop 1
	v_mov_b32_dpp v13, v12 quad_perm:[1,0,3,2] row_mask:0xf bank_mask:0xf
	s_and_saveexec_b64 s[8:9], s[4:5]
	s_cbranch_execz .LBB0_1564
	v_mov_b32_e32 v17, v2
	v_lshl_add_u64 v[14:15], s[6:7], 0, v[16:17]
	s_waitcnt lgkmcnt(0)
	v_cvt_pk_bf16_f32 v17, v12, v13
	v_add_co_u32_e32 v12, vcc, 0x20000, v14
	s_nop 1
	v_addc_co_u32_e32 v13, vcc, 0, v15, vcc
	global_store_dword v[12:13], v17, off
; __device__ __forceinline__ int crow(int r, int hi) { return (r & 3) + 8 * (r >> 2) + 4 * hi; }
; __device__ __forceinline__ unsigned cvtpk(float lo, float hi) { unsigned r; asm volatile("v_cvt_pk_bf16_f32 %0, %1, %2" : "=v"(r) : "v"(lo), "v"(hi)); return r; }
; template <int PQ, int PO>
; __device__ __forceinline__ void fox_block(const Bases& Bs, const BlockRef& cur, const BlockRef& nxt, char* lds, Seam& S) {
;     ...
;     float rli[16];
; #pragma unroll
;     for (int r = 0; r < 16; ++r) rli[r] = __builtin_amdgcn_rcpf(li_l[crow(r, hi)]);
;     bf16* Ow = Bs.O + cur.o + (size_t)(wid * QBLK) * PO;
; #pragma unroll
;     for (int r = 0; r < 16; ++r) { const int orow = crow(r, hi);
; #pragma unroll
;         for (int d0 = 0; d0 < 4; ++d0) { const float v = o[d0][r] * rli[r];
;             const float vn = __shfl_xor(v, 1);
;             if ((r32 & 1) == 0) *(unsigned*)(Ow + (unsigned)(orow * PO + d0 * 32 + r32)) = cvtpk(v, vn); } }
.LBB0_1564:
	s_or_b64 exec, exec, s[8:9]
	v_mul_f32_e32 v12, v58, v8
	s_waitcnt lgkmcnt(0)
	s_nop 1
	v_mov_b32_dpp v13, v12 quad_perm:[1,0,3,2] row_mask:0xf bank_mask:0xf
	s_and_saveexec_b64 s[8:9], s[4:5]
	s_cbranch_execz .LBB0_1566
	v_mov_b32_e32 v17, v2
	v_lshl_add_u64 v[14:15], s[6:7], 0, v[16:17]
	s_waitcnt lgkmcnt(0)
	v_cvt_pk_bf16_f32 v17, v12, v13
	v_add_co_u32_e32 v12, vcc, 0x20000, v14
	s_nop 1
	v_addc_co_u32_e32 v13, vcc, 0, v15, vcc
	global_store_dword v[12:13], v17, off offset:64
.LBB0_1566:
	s_or_b64 exec, exec, s[8:9]
	v_mul_f32_e32 v12, v42, v8
	s_waitcnt lgkmcnt(0)
	s_nop 1
	v_mov_b32_dpp v13, v12 quad_perm:[1,0,3,2] row_mask:0xf bank_mask:0xf
	s_and_saveexec_b64 s[8:9], s[4:5]
	s_cbranch_execz .LBB0_1568
	v_mov_b32_e32 v17, v2
	v_lshl_add_u64 v[14:15], s[6:7], 0, v[16:17]
	s_waitcnt lgkmcnt(0)
	v_cvt_pk_bf16_f32 v17, v12, v13
	v_add_co_u32_e32 v12, vcc, 0x20000, v14
	s_nop 1
	v_addc_co_u32_e32 v13, vcc, 0, v15, vcc
	global_store_dword v[12:13], v17, off offset:128
.LBB0_1568:
	s_or_b64 exec, exec, s[8:9]
	v_mul_f32_e32 v8, v26, v8
	s_nop 1
	v_mov_b32_dpp v12, v8 quad_perm:[1,0,3,2] row_mask:0xf bank_mask:0xf
	s_and_saveexec_b64 s[8:9], s[4:5]
	s_cbranch_execz .LBB0_1570
	v_mov_b32_e32 v17, v2
	v_lshl_add_u64 v[14:15], s[6:7], 0, v[16:17]
	s_waitcnt lgkmcnt(0)
	v_cvt_pk_bf16_f32 v8, v8, v12
	v_add_co_u32_e32 v12, vcc, 0x20000, v14
	s_nop 1
	v_addc_co_u32_e32 v13, vcc, 0, v15, vcc
	global_store_dword v[12:13], v8, off offset:192
.LBB0_1570:
	s_or_b64 exec, exec, s[8:9]
	v_rcp_f32_e32 v8, v9
	s_nop 0
	v_mul_f32_e32 v9, v75, v8
	s_waitcnt lgkmcnt(0)
	s_nop 1
	v_mov_b32_dpp v12, v9 quad_perm:[1,0,3,2] row_mask:0xf bank_mask:0xf
	s_and_saveexec_b64 s[8:9], s[4:5]
	s_cbranch_execz .LBB0_1572
	v_mov_b32_e32 v17, v2
	v_lshl_add_u64 v[14:15], s[6:7], 0, v[16:17]
	s_waitcnt lgkmcnt(0)
	v_cvt_pk_bf16_f32 v9, v9, v12
	v_add_co_u32_e32 v12, vcc, 0x22000, v14
	s_nop 1
	v_addc_co_u32_e32 v13, vcc, 0, v15, vcc
	global_store_dword v[12:13], v9, off
.LBB0_1572:
	s_or_b64 exec, exec, s[8:9]
	v_mul_f32_e32 v9, v59, v8
	s_waitcnt lgkmcnt(0)
	s_nop 1
	v_mov_b32_dpp v12, v9 quad_perm:[1,0,3,2] row_mask:0xf bank_mask:0xf
	s_and_saveexec_b64 s[8:9], s[4:5]
	s_cbranch_execz .LBB0_1574
	v_mov_b32_e32 v17, v2
	v_lshl_add_u64 v[14:15], s[6:7], 0, v[16:17]
	s_waitcnt lgkmcnt(0)
	v_cvt_pk_bf16_f32 v9, v9, v12
	v_add_co_u32_e32 v12, vcc, 0x22000, v14
	s_nop 1
	v_addc_co_u32_e32 v13, vcc, 0, v15, vcc
	global_store_dword v[12:13], v9, off offset:64
.LBB0_1574:
	s_or_b64 exec, exec, s[8:9]
	v_mul_f32_e32 v9, v43, v8
	s_waitcnt lgkmcnt(0)
	s_nop 1
	v_mov_b32_dpp v12, v9 quad_perm:[1,0,3,2] row_mask:0xf bank_mask:0xf
	s_and_saveexec_b64 s[8:9], s[4:5]
	s_cbranch_execz .LBB0_1576
	v_mov_b32_e32 v17, v2
	v_lshl_add_u64 v[14:15], s[6:7], 0, v[16:17]
	s_waitcnt lgkmcnt(0)
	v_cvt_pk_bf16_f32 v9, v9, v12
	v_add_co_u32_e32 v12, vcc, 0x22000, v14
	s_nop 1
	v_addc_co_u32_e32 v13, vcc, 0, v15, vcc
	global_store_dword v[12:13], v9, off offset:128
.LBB0_1576:
	s_or_b64 exec, exec, s[8:9]
	v_mul_f32_e32 v8, v27, v8
	s_nop 1
	v_mov_b32_dpp v9, v8 quad_perm:[1,0,3,2] row_mask:0xf bank_mask:0xf
	s_and_saveexec_b64 s[8:9], s[4:5]
	s_cbranch_execz .LBB0_1578
	v_mov_b32_e32 v17, v2
	s_waitcnt lgkmcnt(1)
	v_lshl_add_u64 v[12:13], s[6:7], 0, v[16:17]
	s_waitcnt lgkmcnt(0)
	v_cvt_pk_bf16_f32 v14, v8, v9
	v_add_co_u32_e32 v8, vcc, 0x22000, v12
	s_nop 1
	v_addc_co_u32_e32 v9, vcc, 0, v13, vcc
	global_store_dword v[8:9], v14, off offset:192
.LBB0_1578:
	s_or_b64 exec, exec, s[8:9]
	v_rcp_f32_e32 v8, v10
	s_waitcnt lgkmcnt(0)
	v_mul_f32_e32 v9, v76, v8
	s_nop 1
	v_mov_b32_dpp v10, v9 quad_perm:[1,0,3,2] row_mask:0xf bank_mask:0xf
	s_and_saveexec_b64 s[8:9], s[4:5]
	s_cbranch_execz .LBB0_1580
	v_mov_b32_e32 v17, v2
	v_lshl_add_u64 v[12:13], s[6:7], 0, v[16:17]
	v_add_co_u32_e32 v12, vcc, 0x24000, v12
	s_waitcnt lgkmcnt(0)
	v_cvt_pk_bf16_f32 v9, v9, v10
	s_nop 0
	v_addc_co_u32_e32 v13, vcc, 0, v13, vcc
	global_store_dword v[12:13], v9, off
.LBB0_1580:
	s_or_b64 exec, exec, s[8:9]
	v_mul_f32_e32 v9, v60, v8
	s_waitcnt lgkmcnt(0)
	s_nop 1
	v_mov_b32_dpp v10, v9 quad_perm:[1,0,3,2] row_mask:0xf bank_mask:0xf
	s_and_saveexec_b64 s[8:9], s[4:5]
	s_cbranch_execz .LBB0_1582
	v_mov_b32_e32 v17, v2
	v_lshl_add_u64 v[12:13], s[6:7], 0, v[16:17]
	v_add_co_u32_e32 v12, vcc, 0x24000, v12
	s_waitcnt lgkmcnt(0)
	v_cvt_pk_bf16_f32 v9, v9, v10
	s_nop 0
	v_addc_co_u32_e32 v13, vcc, 0, v13, vcc
	global_store_dword v[12:13], v9, off offset:64
.LBB0_1582:
	s_or_b64 exec, exec, s[8:9]
	v_mul_f32_e32 v9, v44, v8
	s_waitcnt lgkmcnt(0)
	s_nop 1
	v_mov_b32_dpp v10, v9 quad_perm:[1,0,3,2] row_mask:0xf bank_mask:0xf
	s_and_saveexec_b64 s[8:9], s[4:5]
	s_cbranch_execz .LBB0_1584
	v_mov_b32_e32 v17, v2
	v_lshl_add_u64 v[12:13], s[6:7], 0, v[16:17]
	v_add_co_u32_e32 v12, vcc, 0x24000, v12
	s_waitcnt lgkmcnt(0)
	v_cvt_pk_bf16_f32 v9, v9, v10
	s_nop 0
	v_addc_co_u32_e32 v13, vcc, 0, v13, vcc
	global_store_dword v[12:13], v9, off offset:128
.LBB0_1584:
	s_or_b64 exec, exec, s[8:9]
	v_mul_f32_e32 v8, v28, v8
	s_nop 1
	v_mov_b32_dpp v9, v8 quad_perm:[1,0,3,2] row_mask:0xf bank_mask:0xf
	s_and_saveexec_b64 s[8:9], s[4:5]
	s_cbranch_execz .LBB0_1586
	v_mov_b32_e32 v17, v2
	v_lshl_add_u64 v[12:13], s[6:7], 0, v[16:17]
	s_waitcnt lgkmcnt(0)
	v_cvt_pk_bf16_f32 v10, v8, v9
	v_add_co_u32_e32 v8, vcc, 0x24000, v12
	s_nop 1
	v_addc_co_u32_e32 v9, vcc, 0, v13, vcc
	global_store_dword v[8:9], v10, off offset:192
; __device__ __forceinline__ int crow(int r, int hi) { return (r & 3) + 8 * (r >> 2) + 4 * hi; }
; __device__ __forceinline__ unsigned cvtpk(float lo, float hi) { unsigned r; asm volatile("v_cvt_pk_bf16_f32 %0, %1, %2" : "=v"(r) : "v"(lo), "v"(hi)); return r; }
; template <int PQ, int PO>
; __device__ __forceinline__ void fox_block(const Bases& Bs, const BlockRef& cur, const BlockRef& nxt, char* lds, Seam& S) {
;     ...
;     float rli[16];
; #pragma unroll
;     for (int r = 0; r < 16; ++r) rli[r] = __builtin_amdgcn_rcpf(li_l[crow(r, hi)]);
;     bf16* Ow = Bs.O + cur.o + (size_t)(wid * QBLK) * PO;
; #pragma unroll
;     for (int r = 0; r < 16; ++r) { const int orow = crow(r, hi);
; #pragma unroll
;         for (int d0 = 0; d0 < 4; ++d0) { const float v = o[d0][r] * rli[r];
;             const float vn = __shfl_xor(v, 1);
;             if ((r32 & 1) == 0) *(unsigned*)(Ow + (unsigned)(orow * PO + d0 * 32 + r32)) = cvtpk(v, vn); } }
.LBB0_1586:
	s_or_b64 exec, exec, s[8:9]
	v_rcp_f32_e32 v8, v11
	s_waitcnt lgkmcnt(0)
	v_mul_f32_e32 v9, v77, v8
	s_nop 1
	v_mov_b32_dpp v10, v9 quad_perm:[1,0,3,2] row_mask:0xf bank_mask:0xf
	s_and_saveexec_b64 s[8:9], s[4:5]
	s_cbranch_execz .LBB0_1588
	v_mov_b32_e32 v17, v2
	v_lshl_add_u64 v[12:13], s[6:7], 0, v[16:17]
	s_waitcnt lgkmcnt(0)
	v_cvt_pk_bf16_f32 v9, v9, v10
	v_add_co_u32_e32 v10, vcc, 0x26000, v12
	s_nop 1
	v_addc_co_u32_e32 v11, vcc, 0, v13, vcc
	global_store_dword v[10:11], v9, off
.LBB0_1588:
	s_or_b64 exec, exec, s[8:9]
	v_mul_f32_e32 v9, v61, v8
	s_waitcnt lgkmcnt(0)
	s_nop 1
	v_mov_b32_dpp v10, v9 quad_perm:[1,0,3,2] row_mask:0xf bank_mask:0xf
	s_and_saveexec_b64 s[8:9], s[4:5]
	s_cbranch_execz .LBB0_1590
	v_mov_b32_e32 v17, v2
	v_lshl_add_u64 v[12:13], s[6:7], 0, v[16:17]
	s_waitcnt lgkmcnt(0)
	v_cvt_pk_bf16_f32 v9, v9, v10
	v_add_co_u32_e32 v10, vcc, 0x26000, v12
	s_nop 1
	v_addc_co_u32_e32 v11, vcc, 0, v13, vcc
	global_store_dword v[10:11], v9, off offset:64
.LBB0_1590:
	s_or_b64 exec, exec, s[8:9]
	v_mul_f32_e32 v9, v45, v8
	s_waitcnt lgkmcnt(0)
	s_nop 1
	v_mov_b32_dpp v10, v9 quad_perm:[1,0,3,2] row_mask:0xf bank_mask:0xf
	s_and_saveexec_b64 s[8:9], s[4:5]
	s_cbranch_execz .LBB0_1592
	v_mov_b32_e32 v17, v2
	v_lshl_add_u64 v[12:13], s[6:7], 0, v[16:17]
	s_waitcnt lgkmcnt(0)
	v_cvt_pk_bf16_f32 v9, v9, v10
	v_add_co_u32_e32 v10, vcc, 0x26000, v12
	s_nop 1
	v_addc_co_u32_e32 v11, vcc, 0, v13, vcc
	global_store_dword v[10:11], v9, off offset:128
.LBB0_1592:
	s_or_b64 exec, exec, s[8:9]
	v_mul_f32_e32 v8, v29, v8
	s_nop 1
	v_mov_b32_dpp v9, v8 quad_perm:[1,0,3,2] row_mask:0xf bank_mask:0xf
	s_and_saveexec_b64 s[8:9], s[4:5]
	s_cbranch_execz .LBB0_1594
	v_mov_b32_e32 v17, v2
	s_waitcnt lgkmcnt(1)
	v_lshl_add_u64 v[10:11], s[6:7], 0, v[16:17]
	s_waitcnt lgkmcnt(0)
	v_cvt_pk_bf16_f32 v12, v8, v9
	v_add_co_u32_e32 v8, vcc, 0x26000, v10
	s_nop 1
	v_addc_co_u32_e32 v9, vcc, 0, v11, vcc
	global_store_dword v[8:9], v12, off offset:192
.LBB0_1594:
	s_or_b64 exec, exec, s[8:9]
	v_rcp_f32_e32 v4, v4
	s_nop 0
	v_mul_f32_e32 v8, v78, v4
	s_waitcnt lgkmcnt(0)
	s_nop 1
	v_mov_b32_dpp v9, v8 quad_perm:[1,0,3,2] row_mask:0xf bank_mask:0xf
	s_and_saveexec_b64 s[8:9], s[4:5]
	s_cbranch_execz .LBB0_1596
	v_mov_b32_e32 v17, v2
	v_lshl_add_u64 v[10:11], s[6:7], 0, v[16:17]
	s_waitcnt lgkmcnt(0)
	v_cvt_pk_bf16_f32 v12, v8, v9
	v_add_co_u32_e32 v8, vcc, 0x30000, v10
	s_nop 1
	v_addc_co_u32_e32 v9, vcc, 0, v11, vcc
	global_store_dword v[8:9], v12, off
.LBB0_1596:
	s_or_b64 exec, exec, s[8:9]
	v_mul_f32_e32 v8, v62, v4
	s_waitcnt lgkmcnt(0)
	s_nop 1
	v_mov_b32_dpp v9, v8 quad_perm:[1,0,3,2] row_mask:0xf bank_mask:0xf
	s_and_saveexec_b64 s[8:9], s[4:5]
	s_cbranch_execz .LBB0_1598
	v_mov_b32_e32 v17, v2
	v_lshl_add_u64 v[10:11], s[6:7], 0, v[16:17]
	s_waitcnt lgkmcnt(0)
	v_cvt_pk_bf16_f32 v12, v8, v9
	v_add_co_u32_e32 v8, vcc, 0x30000, v10
	s_nop 1
	v_addc_co_u32_e32 v9, vcc, 0, v11, vcc
	global_store_dword v[8:9], v12, off offset:64
.LBB0_1598:
	s_or_b64 exec, exec, s[8:9]
	v_mul_f32_e32 v8, v46, v4
	s_waitcnt lgkmcnt(0)
	s_nop 1
	v_mov_b32_dpp v9, v8 quad_perm:[1,0,3,2] row_mask:0xf bank_mask:0xf
	s_and_saveexec_b64 s[8:9], s[4:5]
	s_cbranch_execz .LBB0_1600
	v_mov_b32_e32 v17, v2
	v_lshl_add_u64 v[10:11], s[6:7], 0, v[16:17]
	s_waitcnt lgkmcnt(0)
	v_cvt_pk_bf16_f32 v12, v8, v9
	v_add_co_u32_e32 v8, vcc, 0x30000, v10
	s_nop 1
	v_addc_co_u32_e32 v9, vcc, 0, v11, vcc
	global_store_dword v[8:9], v12, off offset:128
.LBB0_1600:
	s_or_b64 exec, exec, s[8:9]
	v_mul_f32_e32 v4, v30, v4
	s_nop 1
	v_mov_b32_dpp v8, v4 quad_perm:[1,0,3,2] row_mask:0xf bank_mask:0xf
	s_and_saveexec_b64 s[8:9], s[4:5]
	s_cbranch_execz .LBB0_1602
	v_mov_b32_e32 v17, v2
	v_lshl_add_u64 v[10:11], s[6:7], 0, v[16:17]
	s_waitcnt lgkmcnt(0)
	v_cvt_pk_bf16_f32 v4, v4, v8
	v_add_co_u32_e32 v8, vcc, 0x30000, v10
	s_nop 1
	v_addc_co_u32_e32 v9, vcc, 0, v11, vcc
	global_store_dword v[8:9], v4, off offset:192
.LBB0_1602:
	s_or_b64 exec, exec, s[8:9]
	v_rcp_f32_e32 v4, v5
	s_nop 0
	v_mul_f32_e32 v5, v79, v4
	s_waitcnt lgkmcnt(0)
	s_nop 1
	v_mov_b32_dpp v8, v5 quad_perm:[1,0,3,2] row_mask:0xf bank_mask:0xf
	s_and_saveexec_b64 s[8:9], s[4:5]
	s_cbranch_execz .LBB0_1604
	v_mov_b32_e32 v17, v2
	v_lshl_add_u64 v[10:11], s[6:7], 0, v[16:17]
	s_waitcnt lgkmcnt(0)
	v_cvt_pk_bf16_f32 v5, v5, v8
	v_add_co_u32_e32 v8, vcc, 0x32000, v10
	s_nop 1
	v_addc_co_u32_e32 v9, vcc, 0, v11, vcc
	global_store_dword v[8:9], v5, off
.LBB0_1604:
	s_or_b64 exec, exec, s[8:9]
	v_mul_f32_e32 v5, v63, v4
	s_waitcnt lgkmcnt(0)
	s_nop 1
	v_mov_b32_dpp v8, v5 quad_perm:[1,0,3,2] row_mask:0xf bank_mask:0xf
	s_and_saveexec_b64 s[8:9], s[4:5]
	s_cbranch_execz .LBB0_1606
	v_mov_b32_e32 v17, v2
	v_lshl_add_u64 v[10:11], s[6:7], 0, v[16:17]
	s_waitcnt lgkmcnt(0)
	v_cvt_pk_bf16_f32 v5, v5, v8
	v_add_co_u32_e32 v8, vcc, 0x32000, v10
	s_nop 1
	v_addc_co_u32_e32 v9, vcc, 0, v11, vcc
	global_store_dword v[8:9], v5, off offset:64
; __device__ __forceinline__ int crow(int r, int hi) { return (r & 3) + 8 * (r >> 2) + 4 * hi; }
; __device__ __forceinline__ unsigned cvtpk(float lo, float hi) { unsigned r; asm volatile("v_cvt_pk_bf16_f32 %0, %1, %2" : "=v"(r) : "v"(lo), "v"(hi)); return r; }
; template <int PQ, int PO>
; __device__ __forceinline__ void fox_block(const Bases& Bs, const BlockRef& cur, const BlockRef& nxt, char* lds, Seam& S) {
;     ...
;     float rli[16];
; #pragma unroll
;     for (int r = 0; r < 16; ++r) rli[r] = __builtin_amdgcn_rcpf(li_l[crow(r, hi)]);
;     bf16* Ow = Bs.O + cur.o + (size_t)(wid * QBLK) * PO;
; #pragma unroll
;     for (int r = 0; r < 16; ++r) { const int orow = crow(r, hi);
; #pragma unroll
;         for (int d0 = 0; d0 < 4; ++d0) { const float v = o[d0][r] * rli[r];
;             const float vn = __shfl_xor(v, 1);
;             if ((r32 & 1) == 0) *(unsigned*)(Ow + (unsigned)(orow * PO + d0 * 32 + r32)) = cvtpk(v, vn); } }
.LBB0_1606:
	s_or_b64 exec, exec, s[8:9]
	v_mul_f32_e32 v5, v47, v4
	s_waitcnt lgkmcnt(0)
	s_nop 1
	v_mov_b32_dpp v8, v5 quad_perm:[1,0,3,2] row_mask:0xf bank_mask:0xf
	s_and_saveexec_b64 s[8:9], s[4:5]
	s_cbranch_execz .LBB0_1608
	v_mov_b32_e32 v17, v2
	v_lshl_add_u64 v[10:11], s[6:7], 0, v[16:17]
	s_waitcnt lgkmcnt(0)
	v_cvt_pk_bf16_f32 v5, v5, v8
	v_add_co_u32_e32 v8, vcc, 0x32000, v10
	s_nop 1
	v_addc_co_u32_e32 v9, vcc, 0, v11, vcc
	global_store_dword v[8:9], v5, off offset:128
.LBB0_1608:
	s_or_b64 exec, exec, s[8:9]
	v_mul_f32_e32 v4, v31, v4
	s_nop 1
	v_mov_b32_dpp v5, v4 quad_perm:[1,0,3,2] row_mask:0xf bank_mask:0xf
	s_and_saveexec_b64 s[8:9], s[4:5]
	s_cbranch_execz .LBB0_1610
	v_mov_b32_e32 v17, v2
	s_waitcnt lgkmcnt(1)
	v_lshl_add_u64 v[8:9], s[6:7], 0, v[16:17]
	s_waitcnt lgkmcnt(0)
	v_cvt_pk_bf16_f32 v10, v4, v5
	v_add_co_u32_e32 v4, vcc, 0x32000, v8
	s_nop 1
	v_addc_co_u32_e32 v5, vcc, 0, v9, vcc
	global_store_dword v[4:5], v10, off offset:192
.LBB0_1610:
	s_or_b64 exec, exec, s[8:9]
	v_rcp_f32_e32 v4, v6
	s_waitcnt lgkmcnt(0)
	v_mul_f32_e32 v5, v80, v4
	s_nop 1
	v_mov_b32_dpp v6, v5 quad_perm:[1,0,3,2] row_mask:0xf bank_mask:0xf
	s_and_saveexec_b64 s[8:9], s[4:5]
	s_cbranch_execz .LBB0_1612
	v_mov_b32_e32 v17, v2
	v_lshl_add_u64 v[8:9], s[6:7], 0, v[16:17]
	v_add_co_u32_e32 v8, vcc, 0x34000, v8
	s_waitcnt lgkmcnt(0)
	v_cvt_pk_bf16_f32 v5, v5, v6
	s_nop 0
	v_addc_co_u32_e32 v9, vcc, 0, v9, vcc
	global_store_dword v[8:9], v5, off
.LBB0_1612:
	s_or_b64 exec, exec, s[8:9]
	v_mul_f32_e32 v5, v64, v4
	s_waitcnt lgkmcnt(0)
	s_nop 1
	v_mov_b32_dpp v6, v5 quad_perm:[1,0,3,2] row_mask:0xf bank_mask:0xf
	s_and_saveexec_b64 s[8:9], s[4:5]
	s_cbranch_execz .LBB0_1614
	v_mov_b32_e32 v17, v2
	v_lshl_add_u64 v[8:9], s[6:7], 0, v[16:17]
	v_add_co_u32_e32 v8, vcc, 0x34000, v8
	s_waitcnt lgkmcnt(0)
	v_cvt_pk_bf16_f32 v5, v5, v6
	s_nop 0
	v_addc_co_u32_e32 v9, vcc, 0, v9, vcc
	global_store_dword v[8:9], v5, off offset:64
.LBB0_1614:
	s_or_b64 exec, exec, s[8:9]
	v_mul_f32_e32 v5, v48, v4
	s_waitcnt lgkmcnt(0)
	s_nop 1
	v_mov_b32_dpp v6, v5 quad_perm:[1,0,3,2] row_mask:0xf bank_mask:0xf
	s_and_saveexec_b64 s[8:9], s[4:5]
	s_cbranch_execz .LBB0_1616
	v_mov_b32_e32 v17, v2
	v_lshl_add_u64 v[8:9], s[6:7], 0, v[16:17]
	v_add_co_u32_e32 v8, vcc, 0x34000, v8
	s_waitcnt lgkmcnt(0)
	v_cvt_pk_bf16_f32 v5, v5, v6
	s_nop 0
	v_addc_co_u32_e32 v9, vcc, 0, v9, vcc
	global_store_dword v[8:9], v5, off offset:128
.LBB0_1616:
	s_or_b64 exec, exec, s[8:9]
	v_mul_f32_e32 v4, v32, v4
	s_nop 1
	v_mov_b32_dpp v5, v4 quad_perm:[1,0,3,2] row_mask:0xf bank_mask:0xf
	s_and_saveexec_b64 s[8:9], s[4:5]
	s_cbranch_execz .LBB0_1618
	v_mov_b32_e32 v17, v2
	v_lshl_add_u64 v[8:9], s[6:7], 0, v[16:17]
	s_waitcnt lgkmcnt(0)
	v_cvt_pk_bf16_f32 v6, v4, v5
	v_add_co_u32_e32 v4, vcc, 0x34000, v8
	s_nop 1
	v_addc_co_u32_e32 v5, vcc, 0, v9, vcc
	global_store_dword v[4:5], v6, off offset:192
.LBB0_1618:
	s_or_b64 exec, exec, s[8:9]
	v_rcp_f32_e32 v4, v7
	s_waitcnt lgkmcnt(0)
	v_mul_f32_e32 v5, v81, v4
	s_nop 1
	v_mov_b32_dpp v6, v5 quad_perm:[1,0,3,2] row_mask:0xf bank_mask:0xf
	s_and_saveexec_b64 s[8:9], s[4:5]
	s_cbranch_execz .LBB0_1620
	v_mov_b32_e32 v17, v2
	v_lshl_add_u64 v[8:9], s[6:7], 0, v[16:17]
	s_waitcnt lgkmcnt(0)
	v_cvt_pk_bf16_f32 v5, v5, v6
	v_add_co_u32_e32 v6, vcc, 0x36000, v8
	s_nop 1
	v_addc_co_u32_e32 v7, vcc, 0, v9, vcc
	global_store_dword v[6:7], v5, off
.LBB0_1620:
	s_or_b64 exec, exec, s[8:9]
	v_mul_f32_e32 v5, v65, v4
	s_waitcnt lgkmcnt(0)
	s_nop 1
	v_mov_b32_dpp v6, v5 quad_perm:[1,0,3,2] row_mask:0xf bank_mask:0xf
	s_and_saveexec_b64 s[8:9], s[4:5]
	s_cbranch_execz .LBB0_1622
	v_mov_b32_e32 v17, v2
	v_lshl_add_u64 v[8:9], s[6:7], 0, v[16:17]
	s_waitcnt lgkmcnt(0)
	v_cvt_pk_bf16_f32 v5, v5, v6
	v_add_co_u32_e32 v6, vcc, 0x36000, v8
	s_nop 1
	v_addc_co_u32_e32 v7, vcc, 0, v9, vcc
	global_store_dword v[6:7], v5, off offset:64
.LBB0_1622:
	s_or_b64 exec, exec, s[8:9]
	v_mul_f32_e32 v5, v49, v4
	s_waitcnt lgkmcnt(0)
	s_nop 1
	v_mov_b32_dpp v6, v5 quad_perm:[1,0,3,2] row_mask:0xf bank_mask:0xf
	s_and_saveexec_b64 s[8:9], s[4:5]
	s_cbranch_execz .LBB0_1624
	v_mov_b32_e32 v17, v2
	v_lshl_add_u64 v[8:9], s[6:7], 0, v[16:17]
	s_waitcnt lgkmcnt(0)
	v_cvt_pk_bf16_f32 v5, v5, v6
	v_add_co_u32_e32 v6, vcc, 0x36000, v8
	s_nop 1
	v_addc_co_u32_e32 v7, vcc, 0, v9, vcc
	global_store_dword v[6:7], v5, off offset:128
.LBB0_1624:
	s_or_b64 exec, exec, s[8:9]
	v_mul_f32_e32 v4, v33, v4
	s_nop 1
	v_mov_b32_dpp v3, v4 quad_perm:[1,0,3,2] row_mask:0xf bank_mask:0xf
	s_and_saveexec_b64 s[8:9], s[4:5]
	s_cbranch_execz .LBB0_1626
	v_mov_b32_e32 v17, v2
	s_waitcnt lgkmcnt(1)
	v_lshl_add_u64 v[6:7], s[6:7], 0, v[16:17]
	s_waitcnt lgkmcnt(0)
	v_cvt_pk_bf16_f32 v3, v4, v3
	v_add_co_u32_e32 v4, vcc, 0x36000, v6
	s_nop 1
	v_addc_co_u32_e32 v5, vcc, 0, v7, vcc
	global_store_dword v[4:5], v3, off offset:192

; #define GAS __attribute__((address_space(1)))
; __device__ __forceinline__ unsigned pk2(float lo, float hi) { pkf32x2 v = {lo, hi}; pkbf16x2 b = __builtin_convertvector(v, pkbf16x2); return __builtin_bit_cast(unsigned, b); }
; __device__ __forceinline__ float siluf_(float x) { return x * __builtin_amdgcn_rcpf(1.0f + __builtin_amdgcn_exp2f(-1.4426950408889634f * x)); }
; __device__ __forceinline__ void p6_gdn_out(Frame& F) {
;     ...
;     for (int row = gw; row < M; row += NGW) {
;         const int b = row / SEQ, t = row % SEQ;
; #pragma unroll
;         for (int it = 0; it < 4; ++it) {
;             const int h = it * 4 + sub;
;             const v4u ow = *(const GAS v4u*)(GO + ((size_t)(b * NH + h) * SEQ + t) * HD + l16 * 8);
;             const f32x4 o0 = {bflo(ow.x), bfhi(ow.x), bflo(ow.y), bfhi(ow.y)}, o1 = {bflo(ow.z), bfhi(ow.z), bflo(ow.w), bfhi(ow.w)};
;             const v4u zw = *(const GAS v4u*)(P + (size_t)row * NPP + PC_Z + h * HD + l16 * 8);
;             float ss = (o0.x * o0.x + o0.y * o0.y) + (o0.z * o0.z + o0.w * o0.w) + (o1.x * o1.x + o1.y * o1.y) + (o1.z * o1.z + o1.w * o1.w);
;             const float rstd = 1.0f / sqrtf(sum16(ss) * (1.0f / HD) + EPS);
;             const float* gn = F.gdn_norm_w + l16 * 8; const f32x4 g0 = *(const f32x4*)gn, g1 = *(const f32x4*)(gn + 4);
;             v4u w;
;             w.x = pk2(o0.x * rstd * g0.x * siluf_(bflo(zw.x)), o0.y * rstd * g0.y * siluf_(bfhi(zw.x)));
;             w.y = pk2(o0.z * rstd * g0.z * siluf_(bflo(zw.y)), o0.w * rstd * g0.w * siluf_(bfhi(zw.y)));
;             w.z = pk2(o1.x * rstd * g1.x * siluf_(bflo(zw.z)), o1.y * rstd * g1.y * siluf_(bfhi(zw.z)));
;             w.w = pk2(o1.z * rstd * g1.z * siluf_(bflo(zw.w)), o1.w * rstd * g1.w * siluf_(bfhi(zw.w)));
;             *(GAS v4u*)(MIX + (size_t)row * LDMIX + FOXW + h * HD + l16 * 8) = w;
;         }
.LBB0_1690:
	s_ashr_i32 s0, s2, 31
	s_lshr_b32 s0, s0, 20
	s_add_i32 s0, s2, s0
	s_ashr_i32 s1, s0, 12
	s_and_b32 s0, s0, 0xfffff000
	s_sub_i32 s0, s2, s0
	s_lshl_b32 s14, s1, 4
	s_ashr_i32 s1, s0, 31
	v_or_b32_e32 v24, s14, v1
	s_lshl_b64 s[0:1], s[0:1], 8
	v_ashrrev_i32_e32 v25, 31, v24
	s_mul_i32 s13, s2, 0x7080
	v_or_b32_e32 v26, s14, v42
	v_lshl_add_u64 v[32:33], v[12:13], 0, s[0:1]
	v_lshlrev_b64 v[24:25], 20, v[24:25]
	s_mul_hi_i32 s11, s2, 0x7080
	v_ashrrev_i32_e32 v27, 31, v26
	s_add_u32 s0, s82, s13
	v_lshl_add_u64 v[36:37], v[32:33], 0, v[24:25]
	global_load_dwordx4 v[2:5], v[14:15], off offset:16
	global_load_dwordx4 v[6:9], v[14:15], off
	v_lshlrev_b64 v[26:27], 20, v[26:27]
	s_addc_u32 s1, s83, s11
	global_load_dwordx4 v[48:51], v[36:37], off
	v_lshl_add_u64 v[34:35], v[32:33], 0, v[26:27]
	v_lshl_add_u64 v[26:27], s[0:1], 0, v[10:11]
	v_lshl_add_u64 v[26:27], v[26:27], 0, s[4:5]
	v_lshl_add_u64 v[52:53], v[26:27], 0, v[16:17]
	global_load_dwordx4 v[52:55], v[52:53], off
	s_mul_i32 s12, s2, 0xffffaf80
	v_or_b32_e32 v28, s14, v43
	v_or_b32_e32 v30, s14, v44
	s_mul_hi_i32 s10, s2, 0xffffaf80
	v_ashrrev_i32_e32 v29, 31, v28
	v_ashrrev_i32_e32 v31, 31, v30
	s_add_u32 s0, s0, s12
	v_lshlrev_b64 v[28:29], 20, v[28:29]
	v_lshlrev_b64 v[30:31], 20, v[30:31]
	s_addc_u32 s1, s1, s10
	v_lshl_add_u64 v[28:29], v[32:33], 0, v[28:29]
	v_lshl_add_u64 v[24:25], v[32:33], 0, v[30:31]
	v_lshl_add_u64 v[32:33], s[0:1], 0, v[10:11]
	v_lshl_add_u64 v[56:57], v[26:27], 0, v[18:19]
	v_lshl_add_u64 v[36:37], v[26:27], 0, v[20:21]
	v_lshl_add_u64 v[30:31], v[26:27], 0, v[22:23]
	v_lshl_add_u64 v[26:27], v[32:33], 0, s[6:7]
	v_lshl_add_u64 v[58:59], v[26:27], 0, v[16:17]
	v_lshl_add_u64 v[60:61], v[26:27], 0, v[18:19]
	v_lshl_add_u64 v[32:33], v[26:27], 0, v[20:21]
	s_add_i32 s2, s2, s8
	s_cmpk_lt_i32 s2, 0x2000
	v_lshl_add_u64 v[26:27], v[26:27], 0, v[22:23]
	s_waitcnt vmcnt(1)
	v_lshlrev_b32_e32 v62, 16, v51
	v_and_b32_e32 v63, 0xffff0000, v51
	v_and_b32_e32 v51, 0xffff0000, v49
	v_and_b32_e32 v67, 0xffff0000, v48
	v_lshlrev_b32_e32 v64, 16, v50
	v_and_b32_e32 v65, 0xffff0000, v50
	v_lshlrev_b32_e32 v50, 16, v49
	v_lshlrev_b32_e32 v66, 16, v48
	v_mov_b32_e32 v72, v67
	v_mov_b32_e32 v73, v51
	v_mov_b32_e32 v68, v63
	v_mov_b32_e32 v69, v65
	v_mov_b32_e32 v70, v66
	v_mov_b32_e32 v71, v50
	v_pk_mul_f32 v[72:73], v[72:73], v[72:73]
	v_mov_b32_e32 v48, v62
	v_mov_b32_e32 v49, v64
	v_pk_mul_f32 v[68:69], v[68:69], v[68:69]
	v_pk_fma_f32 v[70:71], v[70:71], v[70:71], v[72:73]
	v_pk_fma_f32 v[48:49], v[48:49], v[48:49], v[68:69]
	s_waitcnt vmcnt(0)
	v_lshlrev_b32_e32 v74, 16, v53
	v_and_b32_e32 v75, 0xffff0000, v53
	v_lshlrev_b32_e32 v72, 16, v52
	v_and_b32_e32 v73, 0xffff0000, v52
	v_lshlrev_b32_e32 v52, 16, v55
	v_and_b32_e32 v53, 0xffff0000, v55
	v_add_f32_e32 v70, v70, v71
	v_lshlrev_b32_e32 v68, 16, v54
	v_mul_f32_e32 v71, 0xbfb8aa3b, v52
	v_mul_f32_e32 v79, 0xbfb8aa3b, v53
	v_add_f32_e32 v49, v49, v70
	v_and_b32_e32 v69, 0xffff0000, v54
	v_mul_f32_e32 v47, 0xbfb8aa3b, v68
	v_exp_f32_e32 v70, v71
	v_exp_f32_e32 v71, v79
	v_add_f32_e32 v79, v48, v49
	v_mul_f32_e32 v54, 0xbfb8aa3b, v69
	v_mul_f32_e32 v55, 0xbfb8aa3b, v74
	v_mul_f32_e32 v76, 0xbfb8aa3b, v75
	v_mul_f32_e32 v77, 0xbfb8aa3b, v72
	v_mul_f32_e32 v78, 0xbfb8aa3b, v73
	v_exp_f32_e32 v47, v47
	s_nop 1
	v_mov_b32_dpp v80, v79 quad_perm:[1,0,3,2] row_mask:0xf bank_mask:0xf
	v_exp_f32_e32 v54, v54
	v_exp_f32_e32 v55, v55
	v_exp_f32_e32 v76, v76
	v_exp_f32_e32 v77, v77
	v_exp_f32_e32 v78, v78
	v_add_f32_e32 v47, 1.0, v47
	v_add_f32_e32 v49, 1.0, v54
	v_add_f32_e32 v54, 1.0, v55
	v_add_f32_e32 v55, 1.0, v76
	v_add_f32_e32 v76, 1.0, v77
	v_add_f32_e32 v77, 1.0, v78
	v_add_f32_e32 v78, 1.0, v70
	v_rcp_f32_e32 v48, v47
	s_waitcnt lgkmcnt(0)
	v_add_f32_e32 v47, v79, v80
	v_rcp_f32_e32 v70, v76
	v_rcp_f32_e32 v76, v78
	s_nop 1
	v_mov_b32_dpp v78, v47 quad_perm:[2,3,0,1] row_mask:0xf bank_mask:0xf
	v_add_f32_e32 v81, 1.0, v71
	v_rcp_f32_e32 v49, v49
	v_rcp_f32_e32 v71, v77
	v_rcp_f32_e32 v54, v54
	s_waitcnt lgkmcnt(0)
	v_add_f32_e32 v47, v47, v78
	v_pk_mul_f32 v[48:49], v[48:49], v[68:69]
	v_pk_mul_f32 v[68:69], v[70:71], v[72:73]
	s_nop 1
	v_mov_b32_dpp v70, v47 row_half_mirror row_mask:0xf bank_mask:0xf
	v_rcp_f32_e32 v55, v55
	v_rcp_f32_e32 v77, v81
	s_waitcnt lgkmcnt(0)
	v_add_f32_e32 v47, v47, v70
	s_nop 1
	v_mov_b32_dpp v70, v47 row_mirror row_mask:0xf bank_mask:0xf
	v_pk_mul_f32 v[54:55], v[54:55], v[74:75]
	v_pk_mul_f32 v[52:53], v[76:77], v[52:53]
	s_waitcnt lgkmcnt(0)
	v_add_f32_e32 v47, v47, v70
	v_fmamk_f32 v47, v47, 0x3c000000, v45
	v_mul_f32_e32 v70, 0x4f800000, v47
	v_cmp_gt_f32_e32 vcc, s9, v47
	s_nop 1
	v_cndmask_b32_e32 v47, v47, v70, vcc
	v_sqrt_f32_e32 v70, v47
	s_nop 0
	v_add_u32_e32 v71, -1, v70
	v_add_u32_e32 v72, 1, v70
	v_fma_f32 v73, -v71, v70, v47
	v_fma_f32 v74, -v72, v70, v47
	v_cmp_ge_f32_e64 s[0:1], 0, v73
	s_nop 1
	v_cndmask_b32_e64 v70, v70, v71, s[0:1]
	v_cmp_lt_f32_e64 s[0:1], 0, v74
	s_nop 1
	v_cndmask_b32_e64 v70, v70, v72, s[0:1]
	v_mul_f32_e32 v71, 0x37800000, v70
	v_cndmask_b32_e32 v70, v70, v71, vcc
	v_cmp_class_f32_e32 vcc, v47, v46
	s_nop 1
	v_cndmask_b32_e32 v47, v70, v47, vcc
	v_div_scale_f32 v70, s[0:1], v47, v47, 1.0
	v_rcp_f32_e32 v72, v70
	v_div_scale_f32 v71, vcc, 1.0, v47, 1.0
	v_fma_f32 v73, -v70, v72, 1.0
	v_fmac_f32_e32 v72, v73, v72
	v_mul_f32_e32 v73, v71, v72
	v_fma_f32 v74, -v70, v73, v71
	v_fmac_f32_e32 v73, v74, v72
	v_fma_f32 v70, -v70, v73, v71
	v_div_fmas_f32 v70, v70, v72, v73
	v_div_fixup_f32 v70, v70, v47, 1.0
	v_pk_mul_f32 v[66:67], v[70:71], v[66:67] op_sel_hi:[0,1]
	v_pk_mul_f32 v[50:51], v[70:71], v[50:51] op_sel_hi:[0,1]
	v_pk_mul_f32 v[64:65], v[70:71], v[64:65] op_sel_hi:[0,1]
	v_pk_mul_f32 v[62:63], v[70:71], v[62:63] op_sel_hi:[0,1]
	v_pk_mul_f32 v[6:7], v[6:7], v[66:67]
	v_pk_mul_f32 v[8:9], v[8:9], v[50:51]
	v_pk_mul_f32 v[2:3], v[2:3], v[64:65]
	v_pk_mul_f32 v[4:5], v[4:5], v[62:63]
	v_pk_mul_f32 v[6:7], v[68:69], v[6:7]
	v_pk_mul_f32 v[8:9], v[54:55], v[8:9]
	v_pk_mul_f32 v[48:49], v[48:49], v[2:3]
	v_pk_mul_f32 v[50:51], v[52:53], v[4:5]
	v_cvt_pk_bf16_f32 v2, v6, v7
	v_cvt_pk_bf16_f32 v3, v8, v9
	v_cvt_pk_bf16_f32 v4, v48, v49
	v_cvt_pk_bf16_f32 v5, v50, v51
	global_store_dwordx4 v[58:59], v[2:5], off
	global_load_dwordx4 v[2:5], v[34:35], off
	s_nop 0
	global_load_dwordx4 v[6:9], v[56:57], off
	global_load_dwordx4 v[48:51], v[14:15], off offset:16
	global_load_dwordx4 v[52:55], v[14:15], off
	s_waitcnt vmcnt(3)
; #define GAS __attribute__((address_space(1)))
; __device__ __forceinline__ unsigned pk2(float lo, float hi) { pkf32x2 v = {lo, hi}; pkbf16x2 b = __builtin_convertvector(v, pkbf16x2); return __builtin_bit_cast(unsigned, b); }
; __device__ __forceinline__ float siluf_(float x) { return x * __builtin_amdgcn_rcpf(1.0f + __builtin_amdgcn_exp2f(-1.4426950408889634f * x)); }
; __device__ __forceinline__ void p6_gdn_out(Frame& F) {
;     ...
; #pragma unroll
;         for (int it = 0; it < 4; ++it) {
;             const int h = it * 4 + sub;
;             const v4u ow = *(const GAS v4u*)(GO + ((size_t)(b * NH + h) * SEQ + t) * HD + l16 * 8);
;             const f32x4 o0 = {bflo(ow.x), bfhi(ow.x), bflo(ow.y), bfhi(ow.y)}, o1 = {bflo(ow.z), bfhi(ow.z), bflo(ow.w), bfhi(ow.w)};
;             const v4u zw = *(const GAS v4u*)(P + (size_t)row * NPP + PC_Z + h * HD + l16 * 8);
;             float ss = (o0.x * o0.x + o0.y * o0.y) + (o0.z * o0.z + o0.w * o0.w) + (o1.x * o1.x + o1.y * o1.y) + (o1.z * o1.z + o1.w * o1.w);
;             const float rstd = 1.0f / sqrtf(sum16(ss) * (1.0f / HD) + EPS);
;             const float* gn = F.gdn_norm_w + l16 * 8; const f32x4 g0 = *(const f32x4*)gn, g1 = *(const f32x4*)(gn + 4);
;             v4u w;
;             w.x = pk2(o0.x * rstd * g0.x * siluf_(bflo(zw.x)), o0.y * rstd * g0.y * siluf_(bfhi(zw.x)));
;             w.y = pk2(o0.z * rstd * g0.z * siluf_(bflo(zw.y)), o0.w * rstd * g0.w * siluf_(bfhi(zw.y)));
;             w.z = pk2(o1.x * rstd * g1.x * siluf_(bflo(zw.z)), o1.y * rstd * g1.y * siluf_(bfhi(zw.z)));
;             w.w = pk2(o1.z * rstd * g1.z * siluf_(bflo(zw.w)), o1.w * rstd * g1.w * siluf_(bfhi(zw.w)));
;             *(GAS v4u*)(MIX + (size_t)row * LDMIX + FOXW + h * HD + l16 * 8) = w;
	v_lshlrev_b32_e32 v34, 16, v5
	v_and_b32_e32 v35, 0xffff0000, v5
	v_lshlrev_b32_e32 v56, 16, v4
	v_and_b32_e32 v57, 0xffff0000, v4
	s_waitcnt vmcnt(2)
	v_lshlrev_b32_e32 v4, 16, v8
	v_and_b32_e32 v5, 0xffff0000, v8
	v_and_b32_e32 v59, 0xffff0000, v3
	v_and_b32_e32 v65, 0xffff0000, v2
	v_lshlrev_b32_e32 v58, 16, v3
	v_lshlrev_b32_e32 v64, 16, v2
	v_mov_b32_e32 v66, v35
	v_mov_b32_e32 v67, v57
	v_mul_f32_e32 v47, 0xbfb8aa3b, v4
	v_mul_f32_e32 v72, 0xbfb8aa3b, v5
	v_mov_b32_e32 v70, v65
	v_mov_b32_e32 v71, v59
	v_lshlrev_b32_e32 v62, 16, v7
	v_and_b32_e32 v63, 0xffff0000, v7
	v_lshlrev_b32_e32 v2, 16, v6
	v_and_b32_e32 v3, 0xffff0000, v6
	v_lshlrev_b32_e32 v6, 16, v9
	v_and_b32_e32 v7, 0xffff0000, v9
	v_mov_b32_e32 v8, v34
	v_mov_b32_e32 v9, v56
	v_mov_b32_e32 v68, v64
	v_mov_b32_e32 v69, v58
	v_pk_mul_f32 v[66:67], v[66:67], v[66:67]
	v_exp_f32_e32 v47, v47
	v_exp_f32_e32 v72, v72
	v_pk_mul_f32 v[70:71], v[70:71], v[70:71]
	v_mul_f32_e32 v73, 0xbfb8aa3b, v62
	v_mul_f32_e32 v74, 0xbfb8aa3b, v63
	v_pk_fma_f32 v[8:9], v[8:9], v[8:9], v[66:67]
	v_pk_fma_f32 v[66:67], v[68:69], v[68:69], v[70:71]
	v_exp_f32_e32 v73, v73
	v_exp_f32_e32 v74, v74
	v_add_f32_e32 v66, v66, v67
	v_add_f32_e32 v9, v9, v66
	v_add_f32_e32 v47, 1.0, v47
	v_add_f32_e32 v66, 1.0, v72
	v_add_f32_e32 v72, v8, v9
	v_rcp_f32_e32 v8, v47
	s_nop 1
	v_mov_b32_dpp v47, v72 quad_perm:[1,0,3,2] row_mask:0xf bank_mask:0xf
	v_add_f32_e32 v67, 1.0, v73
	v_add_f32_e32 v68, 1.0, v74
	v_rcp_f32_e32 v9, v66
	v_rcp_f32_e32 v66, v67
	v_rcp_f32_e32 v67, v68
	s_waitcnt lgkmcnt(0)
	v_add_f32_e32 v47, v72, v47
	v_pk_mul_f32 v[4:5], v[8:9], v[4:5]
	v_mul_f32_e32 v75, 0xbfb8aa3b, v2
	v_pk_mul_f32 v[8:9], v[66:67], v[62:63]
	s_nop 1
	v_mov_b32_dpp v62, v47 quad_perm:[2,3,0,1] row_mask:0xf bank_mask:0xf
	v_mul_f32_e32 v76, 0xbfb8aa3b, v3
	v_exp_f32_e32 v75, v75
	v_exp_f32_e32 v76, v76
	v_mul_f32_e32 v77, 0xbfb8aa3b, v6
	s_waitcnt lgkmcnt(0)
	v_add_f32_e32 v47, v47, v62
	s_nop 1
	v_mov_b32_dpp v62, v47 row_half_mirror row_mask:0xf bank_mask:0xf
	v_add_f32_e32 v69, 1.0, v75
	v_add_f32_e32 v70, 1.0, v76
	v_rcp_f32_e32 v68, v69
	v_rcp_f32_e32 v69, v70
	s_waitcnt lgkmcnt(0)
	v_add_f32_e32 v47, v47, v62
	s_nop 1
	v_mov_b32_dpp v62, v47 row_mirror row_mask:0xf bank_mask:0xf
	v_mul_f32_e32 v78, 0xbfb8aa3b, v7
	v_pk_mul_f32 v[2:3], v[68:69], v[2:3]
	v_exp_f32_e32 v77, v77
	v_exp_f32_e32 v78, v78
	s_waitcnt lgkmcnt(0)
	v_add_f32_e32 v47, v47, v62
	v_fmamk_f32 v47, v47, 0x3c000000, v45
	v_mul_f32_e32 v62, 0x4f800000, v47
	v_cmp_gt_f32_e32 vcc, s9, v47
	v_add_f32_e32 v71, 1.0, v77
	v_add_f32_e32 v73, 1.0, v78
	v_cndmask_b32_e32 v47, v47, v62, vcc
	v_sqrt_f32_e32 v62, v47
	v_rcp_f32_e32 v70, v71
	v_rcp_f32_e32 v71, v73
	v_add_u32_e32 v63, -1, v62
	v_add_u32_e32 v66, 1, v62
	v_fma_f32 v67, -v63, v62, v47
	v_fma_f32 v68, -v66, v62, v47
	v_cmp_ge_f32_e64 s[0:1], 0, v67
	v_pk_mul_f32 v[6:7], v[70:71], v[6:7]
	s_nop 0
	v_cndmask_b32_e64 v62, v62, v63, s[0:1]
	v_cmp_lt_f32_e64 s[0:1], 0, v68
	s_nop 1
	v_cndmask_b32_e64 v62, v62, v66, s[0:1]
	v_mul_f32_e32 v63, 0x37800000, v62
	v_cndmask_b32_e32 v62, v62, v63, vcc
	v_cmp_class_f32_e32 vcc, v47, v46
	s_nop 1
	v_cndmask_b32_e32 v47, v62, v47, vcc
	v_div_scale_f32 v62, s[0:1], v47, v47, 1.0
	v_rcp_f32_e32 v66, v62
	v_div_scale_f32 v63, vcc, 1.0, v47, 1.0
	v_fma_f32 v67, -v62, v66, 1.0
	v_fmac_f32_e32 v66, v67, v66
	v_mul_f32_e32 v67, v63, v66
	v_fma_f32 v68, -v62, v67, v63
	v_fmac_f32_e32 v67, v68, v66
	v_fma_f32 v62, -v62, v67, v63
	v_div_fmas_f32 v62, v62, v66, v67
	v_div_fixup_f32 v62, v62, v47, 1.0
	v_pk_mul_f32 v[64:65], v[62:63], v[64:65] op_sel_hi:[0,1]
	v_pk_mul_f32 v[58:59], v[62:63], v[58:59] op_sel_hi:[0,1]
	v_pk_mul_f32 v[56:57], v[62:63], v[56:57] op_sel_hi:[0,1]
	v_pk_mul_f32 v[34:35], v[62:63], v[34:35] op_sel_hi:[0,1]
	s_waitcnt vmcnt(0)
	v_pk_mul_f32 v[52:53], v[52:53], v[64:65]
	v_pk_mul_f32 v[54:55], v[54:55], v[58:59]
	v_pk_mul_f32 v[48:49], v[48:49], v[56:57]
	v_pk_mul_f32 v[34:35], v[50:51], v[34:35]
	v_pk_mul_f32 v[2:3], v[2:3], v[52:53]
	v_pk_mul_f32 v[8:9], v[8:9], v[54:55]
	v_pk_mul_f32 v[4:5], v[4:5], v[48:49]
	v_pk_mul_f32 v[6:7], v[6:7], v[34:35]
	v_cvt_pk_bf16_f32 v2, v2, v3
	v_cvt_pk_bf16_f32 v3, v8, v9
	v_cvt_pk_bf16_f32 v4, v4, v5
	v_cvt_pk_bf16_f32 v5, v6, v7
	global_store_dwordx4 v[60:61], v[2:5], off
	global_load_dwordx4 v[2:5], v[28:29], off
	s_nop 0
	global_load_dwordx4 v[6:9], v[36:37], off
	global_load_dwordx4 v[48:51], v[14:15], off offset:16
	global_load_dwordx4 v[52:55], v[14:15], off
	s_waitcnt vmcnt(3)
	v_lshlrev_b32_e32 v28, 16, v5
	v_and_b32_e32 v29, 0xffff0000, v5
	v_lshlrev_b32_e32 v34, 16, v4
	v_and_b32_e32 v35, 0xffff0000, v4
	s_waitcnt vmcnt(2)
	v_lshlrev_b32_e32 v4, 16, v8
	v_and_b32_e32 v5, 0xffff0000, v8
	v_and_b32_e32 v37, 0xffff0000, v3
	v_and_b32_e32 v59, 0xffff0000, v2
	v_lshlrev_b32_e32 v36, 16, v3
	v_lshlrev_b32_e32 v58, 16, v2
	v_mov_b32_e32 v60, v29
	v_mov_b32_e32 v61, v35
	v_mul_f32_e32 v47, 0xbfb8aa3b, v4
	v_mul_f32_e32 v66, 0xbfb8aa3b, v5
	v_mov_b32_e32 v64, v59
	v_mov_b32_e32 v65, v37
	v_lshlrev_b32_e32 v56, 16, v7
	v_and_b32_e32 v57, 0xffff0000, v7
	v_lshlrev_b32_e32 v2, 16, v6
	v_and_b32_e32 v3, 0xffff0000, v6
	v_lshlrev_b32_e32 v6, 16, v9
	v_and_b32_e32 v7, 0xffff0000, v9
	v_mov_b32_e32 v8, v28
	v_mov_b32_e32 v9, v34
	v_mov_b32_e32 v62, v58
	v_mov_b32_e32 v63, v36
	v_pk_mul_f32 v[60:61], v[60:61], v[60:61]
	v_exp_f32_e32 v47, v47
	v_exp_f32_e32 v66, v66
	v_pk_mul_f32 v[64:65], v[64:65], v[64:65]
	v_mul_f32_e32 v67, 0xbfb8aa3b, v56
	v_mul_f32_e32 v68, 0xbfb8aa3b, v57
	v_pk_fma_f32 v[8:9], v[8:9], v[8:9], v[60:61]
	v_pk_fma_f32 v[60:61], v[62:63], v[62:63], v[64:65]
	v_exp_f32_e32 v67, v67
	v_exp_f32_e32 v68, v68
	v_add_f32_e32 v60, v60, v61
	v_add_f32_e32 v9, v9, v60
	v_add_f32_e32 v47, 1.0, v47
	v_add_f32_e32 v60, 1.0, v66
	v_add_f32_e32 v66, v8, v9
	v_rcp_f32_e32 v8, v47
	s_nop 1
	v_mov_b32_dpp v47, v66 quad_perm:[1,0,3,2] row_mask:0xf bank_mask:0xf
	v_add_f32_e32 v61, 1.0, v67
	v_add_f32_e32 v62, 1.0, v68
	v_rcp_f32_e32 v9, v60
	v_rcp_f32_e32 v60, v61
	v_rcp_f32_e32 v61, v62
	s_waitcnt lgkmcnt(0)
; #define GAS __attribute__((address_space(1)))
; __device__ __forceinline__ unsigned pk2(float lo, float hi) { pkf32x2 v = {lo, hi}; pkbf16x2 b = __builtin_convertvector(v, pkbf16x2); return __builtin_bit_cast(unsigned, b); }
; __device__ __forceinline__ float siluf_(float x) { return x * __builtin_amdgcn_rcpf(1.0f + __builtin_amdgcn_exp2f(-1.4426950408889634f * x)); }
; __device__ __forceinline__ void p6_gdn_out(Frame& F) {
;     ...
;             float ss = (o0.x * o0.x + o0.y * o0.y) + (o0.z * o0.z + o0.w * o0.w) + (o1.x * o1.x + o1.y * o1.y) + (o1.z * o1.z + o1.w * o1.w);
;             const float rstd = 1.0f / sqrtf(sum16(ss) * (1.0f / HD) + EPS);
;             const float* gn = F.gdn_norm_w + l16 * 8; const f32x4 g0 = *(const f32x4*)gn, g1 = *(const f32x4*)(gn + 4);
;             v4u w;
;             w.x = pk2(o0.x * rstd * g0.x * siluf_(bflo(zw.x)), o0.y * rstd * g0.y * siluf_(bfhi(zw.x)));
;             w.y = pk2(o0.z * rstd * g0.z * siluf_(bflo(zw.y)), o0.w * rstd * g0.w * siluf_(bfhi(zw.y)));
;             w.z = pk2(o1.x * rstd * g1.x * siluf_(bflo(zw.z)), o1.y * rstd * g1.y * siluf_(bfhi(zw.z)));
;             w.w = pk2(o1.z * rstd * g1.z * siluf_(bflo(zw.w)), o1.w * rstd * g1.w * siluf_(bfhi(zw.w)));
;             *(GAS v4u*)(MIX + (size_t)row * LDMIX + FOXW + h * HD + l16 * 8) = w;
	v_add_f32_e32 v47, v66, v47
	v_pk_mul_f32 v[4:5], v[8:9], v[4:5]
	v_mul_f32_e32 v69, 0xbfb8aa3b, v2
	v_pk_mul_f32 v[8:9], v[60:61], v[56:57]
	s_nop 1
	v_mov_b32_dpp v56, v47 quad_perm:[2,3,0,1] row_mask:0xf bank_mask:0xf
	v_mul_f32_e32 v70, 0xbfb8aa3b, v3
	v_exp_f32_e32 v69, v69
	v_exp_f32_e32 v70, v70
	v_mul_f32_e32 v71, 0xbfb8aa3b, v6
	s_waitcnt lgkmcnt(0)
	v_add_f32_e32 v47, v47, v56
	s_nop 1
	v_mov_b32_dpp v56, v47 row_half_mirror row_mask:0xf bank_mask:0xf
	v_add_f32_e32 v63, 1.0, v69
	v_add_f32_e32 v64, 1.0, v70
	v_rcp_f32_e32 v62, v63
	v_rcp_f32_e32 v63, v64
	s_waitcnt lgkmcnt(0)
	v_add_f32_e32 v47, v47, v56
	s_nop 1
	v_mov_b32_dpp v56, v47 row_mirror row_mask:0xf bank_mask:0xf
	v_mul_f32_e32 v72, 0xbfb8aa3b, v7
	v_pk_mul_f32 v[2:3], v[62:63], v[2:3]
	v_exp_f32_e32 v71, v71
	v_exp_f32_e32 v72, v72
	s_waitcnt lgkmcnt(0)
	v_add_f32_e32 v47, v47, v56
	v_fmamk_f32 v47, v47, 0x3c000000, v45
	v_mul_f32_e32 v56, 0x4f800000, v47
	v_cmp_gt_f32_e32 vcc, s9, v47
	v_add_f32_e32 v65, 1.0, v71
	v_add_f32_e32 v67, 1.0, v72
	v_cndmask_b32_e32 v47, v47, v56, vcc
	v_sqrt_f32_e32 v56, v47
	v_rcp_f32_e32 v64, v65
	v_rcp_f32_e32 v65, v67
	v_add_u32_e32 v57, -1, v56
	v_add_u32_e32 v60, 1, v56
	v_fma_f32 v61, -v57, v56, v47
	v_fma_f32 v62, -v60, v56, v47
	v_cmp_ge_f32_e64 s[0:1], 0, v61
	v_pk_mul_f32 v[6:7], v[64:65], v[6:7]
	s_nop 0
	v_cndmask_b32_e64 v56, v56, v57, s[0:1]
	v_cmp_lt_f32_e64 s[0:1], 0, v62
	s_nop 1
	v_cndmask_b32_e64 v56, v56, v60, s[0:1]
	v_mul_f32_e32 v57, 0x37800000, v56
	v_cndmask_b32_e32 v56, v56, v57, vcc
	v_cmp_class_f32_e32 vcc, v47, v46
	s_nop 1
	v_cndmask_b32_e32 v47, v56, v47, vcc
	v_div_scale_f32 v56, s[0:1], v47, v47, 1.0
	v_rcp_f32_e32 v60, v56
	v_div_scale_f32 v57, vcc, 1.0, v47, 1.0
	v_fma_f32 v61, -v56, v60, 1.0
	v_fmac_f32_e32 v60, v61, v60
	v_mul_f32_e32 v61, v57, v60
	v_fma_f32 v62, -v56, v61, v57
	v_fmac_f32_e32 v61, v62, v60
	v_fma_f32 v56, -v56, v61, v57
	v_div_fmas_f32 v56, v56, v60, v61
	v_div_fixup_f32 v56, v56, v47, 1.0
	v_pk_mul_f32 v[58:59], v[56:57], v[58:59] op_sel_hi:[0,1]
	v_pk_mul_f32 v[36:37], v[56:57], v[36:37] op_sel_hi:[0,1]
	v_pk_mul_f32 v[34:35], v[56:57], v[34:35] op_sel_hi:[0,1]
	v_pk_mul_f32 v[28:29], v[56:57], v[28:29] op_sel_hi:[0,1]
	s_waitcnt vmcnt(0)
	v_pk_mul_f32 v[52:53], v[52:53], v[58:59]
	v_pk_mul_f32 v[36:37], v[54:55], v[36:37]
	v_pk_mul_f32 v[34:35], v[48:49], v[34:35]
	v_pk_mul_f32 v[28:29], v[50:51], v[28:29]
	v_pk_mul_f32 v[2:3], v[2:3], v[52:53]
	v_pk_mul_f32 v[8:9], v[8:9], v[36:37]
	v_pk_mul_f32 v[4:5], v[4:5], v[34:35]
	v_pk_mul_f32 v[6:7], v[6:7], v[28:29]
	v_cvt_pk_bf16_f32 v2, v2, v3
	v_cvt_pk_bf16_f32 v3, v8, v9
	v_cvt_pk_bf16_f32 v4, v4, v5
	v_cvt_pk_bf16_f32 v5, v6, v7
	global_store_dwordx4 v[32:33], v[2:5], off
	global_load_dwordx4 v[2:5], v[24:25], off
	s_nop 0
	global_load_dwordx4 v[6:9], v[30:31], off
	global_load_dwordx4 v[32:35], v[14:15], off offset:16
	global_load_dwordx4 v[48:51], v[14:15], off
	s_waitcnt vmcnt(3)
	v_lshlrev_b32_e32 v24, 16, v5
	v_and_b32_e32 v25, 0xffff0000, v5
	v_lshlrev_b32_e32 v28, 16, v4
	v_and_b32_e32 v29, 0xffff0000, v4
	s_waitcnt vmcnt(2)
; #define GAS __attribute__((address_space(1)))
; __device__ __forceinline__ unsigned pk2(float lo, float hi) { pkf32x2 v = {lo, hi}; pkbf16x2 b = __builtin_convertvector(v, pkbf16x2); return __builtin_bit_cast(unsigned, b); }
; __device__ __forceinline__ float siluf_(float x) { return x * __builtin_amdgcn_rcpf(1.0f + __builtin_amdgcn_exp2f(-1.4426950408889634f * x)); }
; __device__ __forceinline__ void p6_gdn_out(Frame& F) {
;     ...
;             const int h = it * 4 + sub;
;             const v4u ow = *(const GAS v4u*)(GO + ((size_t)(b * NH + h) * SEQ + t) * HD + l16 * 8);
;             const f32x4 o0 = {bflo(ow.x), bfhi(ow.x), bflo(ow.y), bfhi(ow.y)}, o1 = {bflo(ow.z), bfhi(ow.z), bflo(ow.w), bfhi(ow.w)};
;             const v4u zw = *(const GAS v4u*)(P + (size_t)row * NPP + PC_Z + h * HD + l16 * 8);
;             float ss = (o0.x * o0.x + o0.y * o0.y) + (o0.z * o0.z + o0.w * o0.w) + (o1.x * o1.x + o1.y * o1.y) + (o1.z * o1.z + o1.w * o1.w);
;             const float rstd = 1.0f / sqrtf(sum16(ss) * (1.0f / HD) + EPS);
;             const float* gn = F.gdn_norm_w + l16 * 8; const f32x4 g0 = *(const f32x4*)gn, g1 = *(const f32x4*)(gn + 4);
;             v4u w;
;             w.x = pk2(o0.x * rstd * g0.x * siluf_(bflo(zw.x)), o0.y * rstd * g0.y * siluf_(bfhi(zw.x)));
;             w.y = pk2(o0.z * rstd * g0.z * siluf_(bflo(zw.y)), o0.w * rstd * g0.w * siluf_(bfhi(zw.y)));
;             w.z = pk2(o1.x * rstd * g1.x * siluf_(bflo(zw.z)), o1.y * rstd * g1.y * siluf_(bfhi(zw.z)));
;             w.w = pk2(o1.z * rstd * g1.z * siluf_(bflo(zw.w)), o1.w * rstd * g1.w * siluf_(bfhi(zw.w)));
;             *(GAS v4u*)(MIX + (size_t)row * LDMIX + FOXW + h * HD + l16 * 8) = w;
;         }
;     }
	v_lshlrev_b32_e32 v4, 16, v8
	v_and_b32_e32 v5, 0xffff0000, v8
	v_and_b32_e32 v31, 0xffff0000, v3
	v_and_b32_e32 v53, 0xffff0000, v2
	v_lshlrev_b32_e32 v30, 16, v3
	v_lshlrev_b32_e32 v36, 16, v7
	v_and_b32_e32 v37, 0xffff0000, v7
	v_lshlrev_b32_e32 v52, 16, v2
	v_mov_b32_e32 v54, v25
	v_mov_b32_e32 v55, v29
	v_mul_f32_e32 v47, 0xbfb8aa3b, v4
	v_mul_f32_e32 v60, 0xbfb8aa3b, v5
	v_mov_b32_e32 v58, v53
	v_mov_b32_e32 v59, v31
	v_lshlrev_b32_e32 v2, 16, v6
	v_and_b32_e32 v3, 0xffff0000, v6
	v_lshlrev_b32_e32 v6, 16, v9
	v_and_b32_e32 v7, 0xffff0000, v9
	v_mov_b32_e32 v8, v24
	v_mov_b32_e32 v9, v28
	v_mul_f32_e32 v61, 0xbfb8aa3b, v36
	v_mul_f32_e32 v62, 0xbfb8aa3b, v37
	v_mov_b32_e32 v56, v52
	v_mov_b32_e32 v57, v30
	v_pk_mul_f32 v[54:55], v[54:55], v[54:55]
	v_exp_f32_e32 v47, v47
	v_exp_f32_e32 v60, v60
	v_pk_mul_f32 v[58:59], v[58:59], v[58:59]
	v_exp_f32_e32 v61, v61
	v_exp_f32_e32 v62, v62
	v_pk_fma_f32 v[8:9], v[8:9], v[8:9], v[54:55]
	v_pk_fma_f32 v[54:55], v[56:57], v[56:57], v[58:59]
	v_add_f32_e32 v47, 1.0, v47
	v_add_f32_e32 v54, v54, v55
	v_add_f32_e32 v9, v9, v54
	v_add_f32_e32 v54, 1.0, v60
	v_add_f32_e32 v60, v8, v9
	v_add_f32_e32 v55, 1.0, v61
	v_add_f32_e32 v56, 1.0, v62
	v_rcp_f32_e32 v8, v47
	s_nop 1
	v_mov_b32_dpp v47, v60 quad_perm:[1,0,3,2] row_mask:0xf bank_mask:0xf
	v_rcp_f32_e32 v9, v54
	v_rcp_f32_e32 v54, v55
	v_rcp_f32_e32 v55, v56
	v_mul_f32_e32 v63, 0xbfb8aa3b, v2
	v_pk_mul_f32 v[4:5], v[8:9], v[4:5]
	v_mul_f32_e32 v64, 0xbfb8aa3b, v3
	v_pk_mul_f32 v[8:9], v[54:55], v[36:37]
	s_waitcnt lgkmcnt(0)
	v_add_f32_e32 v36, v60, v47
	s_nop 1
	v_mov_b32_dpp v37, v36 quad_perm:[2,3,0,1] row_mask:0xf bank_mask:0xf
	v_exp_f32_e32 v63, v63
	v_exp_f32_e32 v64, v64
	v_mul_f32_e32 v65, 0xbfb8aa3b, v6
	v_mul_f32_e32 v66, 0xbfb8aa3b, v7
	s_waitcnt lgkmcnt(0)
	v_add_f32_e32 v36, v36, v37
	s_nop 1
	v_mov_b32_dpp v37, v36 row_half_mirror row_mask:0xf bank_mask:0xf
	v_add_f32_e32 v57, 1.0, v63
	v_add_f32_e32 v58, 1.0, v64
	v_rcp_f32_e32 v56, v57
	v_rcp_f32_e32 v57, v58
	s_waitcnt lgkmcnt(0)
	v_add_f32_e32 v36, v36, v37
	s_nop 1
	v_mov_b32_dpp v37, v36 row_mirror row_mask:0xf bank_mask:0xf
	v_exp_f32_e32 v65, v65
	v_pk_mul_f32 v[2:3], v[56:57], v[2:3]
	v_exp_f32_e32 v66, v66
	s_waitcnt lgkmcnt(0)
	v_add_f32_e32 v36, v36, v37
	v_fmamk_f32 v36, v36, 0x3c000000, v45
	v_mul_f32_e32 v37, 0x4f800000, v36
	v_cmp_gt_f32_e32 vcc, s9, v36
	v_add_f32_e32 v59, 1.0, v65
	v_add_f32_e32 v61, 1.0, v66
	v_cndmask_b32_e32 v36, v36, v37, vcc
	v_sqrt_f32_e32 v37, v36
	v_rcp_f32_e32 v58, v59
	v_rcp_f32_e32 v59, v61
	v_add_u32_e32 v47, -1, v37
	v_add_u32_e32 v54, 1, v37
	v_fma_f32 v55, -v47, v37, v36
	v_fma_f32 v56, -v54, v37, v36
	v_cmp_ge_f32_e64 s[0:1], 0, v55
	v_pk_mul_f32 v[6:7], v[58:59], v[6:7]
	s_nop 0
	v_cndmask_b32_e64 v37, v37, v47, s[0:1]
	v_cmp_lt_f32_e64 s[0:1], 0, v56
	s_nop 1
	v_cndmask_b32_e64 v37, v37, v54, s[0:1]
	v_mul_f32_e32 v47, 0x37800000, v37
	v_cndmask_b32_e32 v37, v37, v47, vcc
	v_cmp_class_f32_e32 vcc, v36, v46
	s_nop 1
	v_cndmask_b32_e32 v36, v37, v36, vcc
	v_div_scale_f32 v37, s[0:1], v36, v36, 1.0
	v_rcp_f32_e32 v54, v37
	v_div_scale_f32 v47, vcc, 1.0, v36, 1.0
	v_fma_f32 v55, -v37, v54, 1.0
	v_fmac_f32_e32 v54, v55, v54
	v_mul_f32_e32 v55, v47, v54
	v_fma_f32 v56, -v37, v55, v47
	v_fmac_f32_e32 v55, v56, v54
	v_fma_f32 v37, -v37, v55, v47
	v_div_fmas_f32 v37, v37, v54, v55
	v_div_fixup_f32 v36, v37, v36, 1.0
	v_pk_mul_f32 v[52:53], v[36:37], v[52:53] op_sel_hi:[0,1]
	v_pk_mul_f32 v[30:31], v[36:37], v[30:31] op_sel_hi:[0,1]
	v_pk_mul_f32 v[28:29], v[36:37], v[28:29] op_sel_hi:[0,1]
	v_pk_mul_f32 v[24:25], v[36:37], v[24:25] op_sel_hi:[0,1]
	s_waitcnt vmcnt(0)
	v_pk_mul_f32 v[36:37], v[48:49], v[52:53]
	v_pk_mul_f32 v[30:31], v[50:51], v[30:31]
	v_pk_mul_f32 v[28:29], v[32:33], v[28:29]
	v_pk_mul_f32 v[24:25], v[34:35], v[24:25]
	v_pk_mul_f32 v[2:3], v[2:3], v[36:37]
	v_pk_mul_f32 v[8:9], v[8:9], v[30:31]
	v_pk_mul_f32 v[4:5], v[4:5], v[28:29]
	v_pk_mul_f32 v[6:7], v[6:7], v[24:25]
	v_cvt_pk_bf16_f32 v2, v2, v3
	v_cvt_pk_bf16_f32 v3, v8, v9
	v_cvt_pk_bf16_f32 v4, v4, v5
	v_cvt_pk_bf16_f32 v5, v6, v7
	global_store_dwordx4 v[26:27], v[2:5], off
	s_cbranch_scc1 .LBB0_1690
